# K-loop: MMA wave drops priority right after its last MFMA, before the closing barrier (32 sites)
# speedup vs baseline: 1.0107x; 1.0056x over previous
; #define PG8_STAGE(bufoff, gbase, voff) do { _Pragma("unroll") for (int _i = 0; _i < 2; ++_i) \
;         __builtin_amdgcn_global_load_lds((const unsigned*)((const char*)(gbase) + (voff)[_i]), (PG8_LAS unsigned*)(lds + (bufoff) + ldsw + _i * 8192), 16, 0, 0); } while (0)
; #define PG8_LDA(dst, b, h) do { _Pragma("unroll") for (int m = 0; m < 4; ++m) _Pragma("unroll") for (int k = 0; k < 2; ++k) dst[m][k] = *(const PG8_LAS bf16x8*)(lds + PG8_SA(b, h) + aoff + m * 2048 + k * 1024); } while (0)
; #define PG8_LDB(dst, b, h) do { _Pragma("unroll") for (int n = 0; n < 2; ++n) _Pragma("unroll") for (int k = 0; k < 2; ++k) dst[n][k] = *(const PG8_LAS bf16x8*)(lds + PG8_SB(b, h) + boff + n * 2048 + k * 1024); } while (0)
; #define PG8_WAIT_V(n) asm volatile("s_waitcnt vmcnt(" #n ")" ::: "memory")
; #define PG8_WAIT_L(n) asm volatile("s_waitcnt lgkmcnt(" #n ")" ::: "memory")
; #define PG8_BAR __builtin_amdgcn_s_barrier()
; #define PG8_SCHED __builtin_amdgcn_sched_barrier(0)
; template <class Epi, class Sched, bool ALIGN_EPI = false, bool SP2 = false, bool F16 = false>
; __device__ __forceinline__ void gemm_phase(PG8_LAS unsigned char* lds, const Gemm g, const Sched& S, const Epi& E) {
;     ...
;         for (int t = 0; t < nt; t += 2) {
;             const bool last = (t == nt - 2);
;             const char* a1 = cA + (size_t)(t + 1) * kstep;
;             const char* a2 = last ? nA : cA + (size_t)(t + 2) * kstep; const char* b2 = last ? nB : cB + (size_t)(t + 2) * kstep;
;             const char* a3 = a2 + kstep; const char* b3 = b2 + kstep;
;             if (last && has_next) S.a_ready(nxt);
;             if constexpr (SP2) {
;             PG8_LDB(B0, 0, 0); PG8_LDB(B1, 0, 1); PG8_SCHED; PG8_LDA(At, 0, 0); PG8_STAGE(PG8_SA(1, 1), a1 + hstepA, voffA);
;             PG8_WAIT_V(8); PG8_WAIT_L(0); PG8_BAR; PG8_MMA(0, 0, At, B0); PG8_MMA(0, 1, At, B1); PG8_BAR; PG8_SCHED;
;             PG8_LDA(At, 0, 1); PG8_STAGE(PG8_SB(0, 0), b2, voffB); PG8_STAGE(PG8_SB(0, 1), b2 + hstepB, voffB); PG8_STAGE(PG8_SA(0, 0), a2, voffA);
;             PG8_WAIT_V(8); PG8_WAIT_L(0); PG8_BAR; PG8_MMA(1, 0, At, B0); PG8_MMA(1, 1, At, B1); PG8_BAR; PG8_SCHED;
.Lpk_gu:
	s_add_i32 s82, s54, 2
	s_add_u32 s83, s52, 0x80
	s_addc_u32 s55, s53, 0
	s_add_i32 vcc_lo, 0, 0x10000
	s_cmp_eq_u32 s74, s54
	s_cselect_b32 s55, s39, s55
	s_cselect_b32 s54, s38, s83
	s_cselect_b32 s95, s47, s81
	s_cselect_b32 s94, s46, s80
	s_add_i32 s83, 0, 0x14000
	ds_read_b128 v[130:133], v139
	ds_read_b128 v[134:137], v139 offset:1024
	ds_read_b128 v[152:155], v139 offset:2048
	ds_read_b128 v[156:159], v139 offset:3072
	ds_read_b128 v[160:163], v141
	ds_read_b128 v[166:169], v141 offset:1024
	ds_read_b128 v[184:187], v141 offset:2048
	ds_read_b128 v[188:191], v141 offset:3072
	s_add_i32 m0, s22, 0xc000
	ds_read_b128 v[192:195], v183
	ds_read_b128 v[204:207], v183 offset:1024
	ds_read_b128 v[208:211], v183 offset:2048
	ds_read_b128 v[212:215], v183 offset:3072
	ds_read_b128 v[216:219], v183 offset:4096
	ds_read_b128 v[220:223], v183 offset:5120
	ds_read_b128 v[224:227], v183 offset:6144
	ds_read_b128 v[228:231], v183 offset:7168
	global_load_lds_dwordx4 v148, s[52:53]
	s_add_i32 m0, s22, 0xe000
	s_nop 0
	global_load_lds_dwordx4 v150, s[52:53]
	s_waitcnt vmcnt(8)
	s_waitcnt lgkmcnt(0)
	s_setprio 1
	s_barrier
	v_mfma_f32_16x16x32_f16 v[122:125], v[130:133], v[192:195], 0
	v_mfma_f32_16x16x32_f16 v[114:117], v[152:155], v[192:195], 0
	v_mfma_f32_16x16x32_f16 v[106:109], v[130:133], v[208:211], 0
	v_mfma_f32_16x16x32_f16 v[98:101], v[152:155], v[208:211], 0
	v_mfma_f32_16x16x32_f16 v[90:93], v[130:133], v[216:219], 0
	v_mfma_f32_16x16x32_f16 v[82:85], v[152:155], v[216:219], 0
	v_mfma_f32_16x16x32_f16 v[74:77], v[130:133], v[224:227], 0
	v_mfma_f32_16x16x32_f16 v[66:69], v[152:155], v[224:227], 0
	v_mfma_f32_16x16x32_f16 v[122:125], v[134:137], v[204:207], v[122:125]
	v_mfma_f32_16x16x32_f16 v[114:117], v[156:159], v[204:207], v[114:117]
	v_mfma_f32_16x16x32_f16 v[106:109], v[134:137], v[212:215], v[106:109]
	v_mfma_f32_16x16x32_f16 v[98:101], v[156:159], v[212:215], v[98:101]
	v_mfma_f32_16x16x32_f16 v[90:93], v[134:137], v[220:223], v[90:93]
	v_mfma_f32_16x16x32_f16 v[82:85], v[156:159], v[220:223], v[82:85]
	v_mfma_f32_16x16x32_f16 v[74:77], v[134:137], v[228:231], v[74:77]
	v_mfma_f32_16x16x32_f16 v[66:69], v[156:159], v[228:231], v[66:69]
	v_mfma_f32_16x16x32_f16 v[126:129], v[160:163], v[192:195], 0
	v_mfma_f32_16x16x32_f16 v[118:121], v[184:187], v[192:195], 0
	v_mfma_f32_16x16x32_f16 v[110:113], v[160:163], v[208:211], 0
	v_mfma_f32_16x16x32_f16 v[102:105], v[184:187], v[208:211], 0
	v_mfma_f32_16x16x32_f16 v[94:97], v[160:163], v[216:219], 0
	v_mfma_f32_16x16x32_f16 v[86:89], v[184:187], v[216:219], 0
	v_mfma_f32_16x16x32_f16 v[78:81], v[160:163], v[224:227], 0
	v_mfma_f32_16x16x32_f16 v[70:73], v[184:187], v[224:227], 0
	v_mfma_f32_16x16x32_f16 v[126:129], v[166:169], v[204:207], v[126:129]
	v_mfma_f32_16x16x32_f16 v[118:121], v[188:191], v[204:207], v[118:121]
	v_mfma_f32_16x16x32_f16 v[110:113], v[166:169], v[212:215], v[110:113]
	v_mfma_f32_16x16x32_f16 v[102:105], v[188:191], v[212:215], v[102:105]
	v_mfma_f32_16x16x32_f16 v[94:97], v[166:169], v[220:223], v[94:97]
	v_mfma_f32_16x16x32_f16 v[86:89], v[188:191], v[220:223], v[86:89]
	v_mfma_f32_16x16x32_f16 v[78:81], v[166:169], v[228:231], v[78:81]
	v_mfma_f32_16x16x32_f16 v[70:73], v[188:191], v[228:231], v[70:73]
	s_setprio 0
	s_barrier
	s_add_i32 vcc_lo, vcc_lo, s2
	s_mov_b32 m0, vcc_lo
	s_nop 0
	global_load_lds_dwordx4 v142, s[94:95]
	ds_read_b128 v[192:195], v183 offset:16384
	ds_read_b128 v[204:207], v183 offset:17408
	ds_read_b128 v[208:211], v183 offset:18432
	ds_read_b128 v[212:215], v183 offset:19456
	ds_read_b128 v[216:219], v183 offset:20480
	ds_read_b128 v[220:223], v183 offset:21504
	ds_read_b128 v[224:227], v183 offset:22528
	ds_read_b128 v[228:231], v183 offset:23552
	s_add_i32 m0, vcc_lo, 0x2000
	s_nop 0
	global_load_lds_dwordx4 v138, s[94:95]
	s_add_i32 s83, s83, s2
	s_add_u32 s94, s94, s48
	s_addc_u32 s95, s95, 0
	s_mov_b32 m0, s83
	s_nop 0
	global_load_lds_dwordx4 v142, s[94:95]
	s_add_i32 m0, s83, 0x2000
	s_nop 0
	global_load_lds_dwordx4 v138, s[94:95]
	s_mov_b32 m0, s22
	s_nop 0
	global_load_lds_dwordx4 v144, s[54:55]
	s_mov_b32 m0, s33
	s_nop 0
	global_load_lds_dwordx4 v140, s[54:55]
	s_waitcnt vmcnt(8)
	s_waitcnt lgkmcnt(0)
	s_setprio 1
	s_barrier
	v_mfma_f32_16x16x32_f16 v[58:61], v[130:133], v[192:195], 0
	v_mfma_f32_16x16x32_f16 v[50:53], v[152:155], v[192:195], 0
	v_mfma_f32_16x16x32_f16 v[42:45], v[130:133], v[208:211], 0
	v_mfma_f32_16x16x32_f16 v[34:37], v[152:155], v[208:211], 0
	v_mfma_f32_16x16x32_f16 v[26:29], v[130:133], v[216:219], 0
	v_mfma_f32_16x16x32_f16 v[18:21], v[152:155], v[216:219], 0
	v_mfma_f32_16x16x32_f16 v[10:13], v[130:133], v[224:227], 0
	v_mfma_f32_16x16x32_f16 v[6:9], v[152:155], v[224:227], 0
	v_mfma_f32_16x16x32_f16 v[58:61], v[134:137], v[204:207], v[58:61]
	v_mfma_f32_16x16x32_f16 v[50:53], v[156:159], v[204:207], v[50:53]
	v_mfma_f32_16x16x32_f16 v[42:45], v[134:137], v[212:215], v[42:45]
	v_mfma_f32_16x16x32_f16 v[34:37], v[156:159], v[212:215], v[34:37]
	v_mfma_f32_16x16x32_f16 v[26:29], v[134:137], v[220:223], v[26:29]
	v_mfma_f32_16x16x32_f16 v[18:21], v[156:159], v[220:223], v[18:21]
	v_mfma_f32_16x16x32_f16 v[10:13], v[134:137], v[228:231], v[10:13]
	v_mfma_f32_16x16x32_f16 v[6:9], v[156:159], v[228:231], v[6:9]
	v_mfma_f32_16x16x32_f16 v[62:65], v[160:163], v[192:195], 0
	v_mfma_f32_16x16x32_f16 v[54:57], v[184:187], v[192:195], 0
	v_mfma_f32_16x16x32_f16 v[46:49], v[160:163], v[208:211], 0
	v_mfma_f32_16x16x32_f16 v[38:41], v[184:187], v[208:211], 0
	v_mfma_f32_16x16x32_f16 v[30:33], v[160:163], v[216:219], 0
	v_mfma_f32_16x16x32_f16 v[22:25], v[184:187], v[216:219], 0
	v_mfma_f32_16x16x32_f16 v[14:17], v[160:163], v[224:227], 0
	v_mfma_f32_16x16x32_f16 v[2:5], v[184:187], v[224:227], 0
	v_mfma_f32_16x16x32_f16 v[62:65], v[166:169], v[204:207], v[62:65]
	v_mfma_f32_16x16x32_f16 v[54:57], v[188:191], v[204:207], v[54:57]
	v_mfma_f32_16x16x32_f16 v[46:49], v[166:169], v[212:215], v[46:49]
	v_mfma_f32_16x16x32_f16 v[38:41], v[188:191], v[212:215], v[38:41]
	v_mfma_f32_16x16x32_f16 v[30:33], v[166:169], v[220:223], v[30:33]
	v_mfma_f32_16x16x32_f16 v[22:25], v[188:191], v[220:223], v[22:25]
	v_mfma_f32_16x16x32_f16 v[14:17], v[166:169], v[228:231], v[14:17]
	v_mfma_f32_16x16x32_f16 v[2:5], v[188:191], v[228:231], v[2:5]
	s_setprio 0
	s_barrier
; #define PG8_STAGE(bufoff, gbase, voff) do { _Pragma("unroll") for (int _i = 0; _i < 2; ++_i) \
;         __builtin_amdgcn_global_load_lds((const unsigned*)((const char*)(gbase) + (voff)[_i]), (PG8_LAS unsigned*)(lds + (bufoff) + ldsw + _i * 8192), 16, 0, 0); } while (0)
; #define PG8_LDA(dst, b, h) do { _Pragma("unroll") for (int m = 0; m < 4; ++m) _Pragma("unroll") for (int k = 0; k < 2; ++k) dst[m][k] = *(const PG8_LAS bf16x8*)(lds + PG8_SA(b, h) + aoff + m * 2048 + k * 1024); } while (0)
; #define PG8_LDB(dst, b, h) do { _Pragma("unroll") for (int n = 0; n < 2; ++n) _Pragma("unroll") for (int k = 0; k < 2; ++k) dst[n][k] = *(const PG8_LAS bf16x8*)(lds + PG8_SB(b, h) + boff + n * 2048 + k * 1024); } while (0)
; #define PG8_WAIT_V(n) asm volatile("s_waitcnt vmcnt(" #n ")" ::: "memory")
; #define PG8_WAIT_L(n) asm volatile("s_waitcnt lgkmcnt(" #n ")" ::: "memory")
; #define PG8_BAR __builtin_amdgcn_s_barrier()
; #define PG8_SCHED __builtin_amdgcn_sched_barrier(0)
; template <class Epi, class Sched, bool ALIGN_EPI = false, bool SP2 = false, bool F16 = false>
; __device__ __forceinline__ void gemm_phase(PG8_LAS unsigned char* lds, const Gemm g, const Sched& S, const Epi& E) {
;     ...
;         for (int t = 0; t < nt; t += 2) {
;             const bool last = (t == nt - 2);
;             const char* a1 = cA + (size_t)(t + 1) * kstep;
;             const char* a2 = last ? nA : cA + (size_t)(t + 2) * kstep; const char* b2 = last ? nB : cB + (size_t)(t + 2) * kstep;
;             const char* a3 = a2 + kstep; const char* b3 = b2 + kstep;
;     ...
;             PG8_LDB(B0, 1, 0); PG8_LDB(B1, 1, 1); PG8_SCHED; PG8_LDA(At, 1, 0); PG8_STAGE(PG8_SA(0, 1), a2 + hstepA, voffA);
;             PG8_WAIT_V(8); PG8_WAIT_L(0); PG8_BAR; PG8_MMA(0, 0, At, B0); PG8_MMA(0, 1, At, B1); PG8_BAR; PG8_SCHED;
;             PG8_LDA(At, 1, 1); PG8_STAGE(PG8_SB(1, 0), b3, voffB); PG8_STAGE(PG8_SB(1, 1), b3 + hstepB, voffB); PG8_STAGE(PG8_SA(1, 0), a3, voffA);
;             PG8_WAIT_V(8); PG8_WAIT_L(0); PG8_BAR; PG8_MMA(1, 0, At, B0); PG8_MMA(1, 1, At, B1); PG8_BAR; PG8_SCHED;
	s_add_i32 s83, 0, 0x18000
	s_add_i32 s94, 0, 0x1c000
	ds_read_b128 v[130:133], v143
	ds_read_b128 v[134:137], v143 offset:1024
	ds_read_b128 v[152:155], v143 offset:2048
	ds_read_b128 v[156:159], v143 offset:3072
	ds_read_b128 v[160:163], v145
	ds_read_b128 v[166:169], v145 offset:1024
	ds_read_b128 v[184:187], v145 offset:2048
	ds_read_b128 v[188:191], v145 offset:3072
	s_add_u32 s54, s54, s8
	s_addc_u32 s55, s55, 0
	s_mov_b32 m0, s12
	ds_read_b128 v[192:195], v183 offset:32768
	ds_read_b128 v[204:207], v183 offset:33792
	ds_read_b128 v[208:211], v183 offset:34816
	ds_read_b128 v[212:215], v183 offset:35840
	ds_read_b128 v[216:219], v183 offset:36864
	ds_read_b128 v[220:223], v183 offset:37888
	ds_read_b128 v[224:227], v183 offset:38912
	ds_read_b128 v[228:231], v183 offset:39936
	global_load_lds_dwordx4 v144, s[54:55]
	s_mov_b32 m0, s13
	s_nop 0
	global_load_lds_dwordx4 v140, s[54:55]
	s_waitcnt vmcnt(8)
	s_waitcnt lgkmcnt(0)
	s_setprio 1
	s_barrier
	v_mfma_f32_16x16x32_f16 v[122:125], v[130:133], v[192:195], v[122:125]
	v_mfma_f32_16x16x32_f16 v[114:117], v[152:155], v[192:195], v[114:117]
	v_mfma_f32_16x16x32_f16 v[106:109], v[130:133], v[208:211], v[106:109]
	v_mfma_f32_16x16x32_f16 v[98:101], v[152:155], v[208:211], v[98:101]
	v_mfma_f32_16x16x32_f16 v[90:93], v[130:133], v[216:219], v[90:93]
	v_mfma_f32_16x16x32_f16 v[82:85], v[152:155], v[216:219], v[82:85]
	v_mfma_f32_16x16x32_f16 v[74:77], v[130:133], v[224:227], v[74:77]
	v_mfma_f32_16x16x32_f16 v[66:69], v[152:155], v[224:227], v[66:69]
	v_mfma_f32_16x16x32_f16 v[122:125], v[134:137], v[204:207], v[122:125]
	v_mfma_f32_16x16x32_f16 v[114:117], v[156:159], v[204:207], v[114:117]
	v_mfma_f32_16x16x32_f16 v[106:109], v[134:137], v[212:215], v[106:109]
	v_mfma_f32_16x16x32_f16 v[98:101], v[156:159], v[212:215], v[98:101]
	v_mfma_f32_16x16x32_f16 v[90:93], v[134:137], v[220:223], v[90:93]
	v_mfma_f32_16x16x32_f16 v[82:85], v[156:159], v[220:223], v[82:85]
	v_mfma_f32_16x16x32_f16 v[74:77], v[134:137], v[228:231], v[74:77]
	v_mfma_f32_16x16x32_f16 v[66:69], v[156:159], v[228:231], v[66:69]
	v_mfma_f32_16x16x32_f16 v[126:129], v[160:163], v[192:195], v[126:129]
	v_mfma_f32_16x16x32_f16 v[118:121], v[184:187], v[192:195], v[118:121]
	v_mfma_f32_16x16x32_f16 v[110:113], v[160:163], v[208:211], v[110:113]
	v_mfma_f32_16x16x32_f16 v[102:105], v[184:187], v[208:211], v[102:105]
	v_mfma_f32_16x16x32_f16 v[94:97], v[160:163], v[216:219], v[94:97]
	v_mfma_f32_16x16x32_f16 v[86:89], v[184:187], v[216:219], v[86:89]
	v_mfma_f32_16x16x32_f16 v[78:81], v[160:163], v[224:227], v[78:81]
	v_mfma_f32_16x16x32_f16 v[70:73], v[184:187], v[224:227], v[70:73]
	v_mfma_f32_16x16x32_f16 v[126:129], v[166:169], v[204:207], v[126:129]
	v_mfma_f32_16x16x32_f16 v[118:121], v[188:191], v[204:207], v[118:121]
	v_mfma_f32_16x16x32_f16 v[110:113], v[166:169], v[212:215], v[110:113]
	v_mfma_f32_16x16x32_f16 v[102:105], v[188:191], v[212:215], v[102:105]
	v_mfma_f32_16x16x32_f16 v[94:97], v[166:169], v[220:223], v[94:97]
	v_mfma_f32_16x16x32_f16 v[86:89], v[188:191], v[220:223], v[86:89]
	v_mfma_f32_16x16x32_f16 v[78:81], v[166:169], v[228:231], v[78:81]
	v_mfma_f32_16x16x32_f16 v[70:73], v[188:191], v[228:231], v[70:73]
	s_setprio 0
	s_barrier
	s_add_i32 s54, s83, s2
	s_add_i32 vcc_hi, s82, -2
	s_cmp_eq_u32 s74, vcc_hi
	s_cselect_b32 s99, s47, s81
	s_cselect_b32 s98, s46, s80
	s_add_u32 s98, s98, s92
	s_addc_u32 s99, s99, s93
	s_mov_b32 m0, s54
	s_nop 0
	global_load_lds_dwordx4 v142, s[98:99]
	ds_read_b128 v[192:195], v183 offset:49152
	ds_read_b128 v[204:207], v183 offset:50176
	ds_read_b128 v[208:211], v183 offset:51200
	ds_read_b128 v[212:215], v183 offset:52224
	ds_read_b128 v[216:219], v183 offset:53248
	ds_read_b128 v[220:223], v183 offset:54272
	ds_read_b128 v[224:227], v183 offset:55296
	ds_read_b128 v[228:231], v183 offset:56320
	s_add_i32 m0, s54, 0x2000
	s_nop 0
	global_load_lds_dwordx4 v138, s[98:99]
	s_add_i32 s54, s94, s2
	s_add_u32 s98, s98, s48
	s_addc_u32 s99, s99, 0
	s_mov_b32 m0, s54
	s_nop 0
	global_load_lds_dwordx4 v142, s[98:99]
	s_add_i32 m0, s54, 0x2000
	s_nop 0
	global_load_lds_dwordx4 v138, s[98:99]
	s_add_u32 s98, s52, 0x80
	s_addc_u32 s99, s53, 0
	s_cmp_eq_u32 s74, vcc_hi
	s_cselect_b32 s99, s39, s99
	s_cselect_b32 s98, s38, s98
	s_add_u32 s98, s98, s92
	s_addc_u32 s99, s99, s93
	s_mov_b32 m0, s35
	s_nop 0
	global_load_lds_dwordx4 v144, s[98:99]
	s_mov_b32 m0, s59
	s_nop 0
	global_load_lds_dwordx4 v140, s[98:99]
	s_waitcnt vmcnt(8)
	s_waitcnt lgkmcnt(0)
	s_setprio 1
	s_barrier
	v_mfma_f32_16x16x32_f16 v[58:61], v[130:133], v[192:195], v[58:61]
	v_mfma_f32_16x16x32_f16 v[50:53], v[152:155], v[192:195], v[50:53]
	v_mfma_f32_16x16x32_f16 v[42:45], v[130:133], v[208:211], v[42:45]
	v_mfma_f32_16x16x32_f16 v[34:37], v[152:155], v[208:211], v[34:37]
	v_mfma_f32_16x16x32_f16 v[26:29], v[130:133], v[216:219], v[26:29]
	v_mfma_f32_16x16x32_f16 v[18:21], v[152:155], v[216:219], v[18:21]
	v_mfma_f32_16x16x32_f16 v[10:13], v[130:133], v[224:227], v[10:13]
	v_mfma_f32_16x16x32_f16 v[6:9], v[152:155], v[224:227], v[6:9]
	v_mfma_f32_16x16x32_f16 v[58:61], v[134:137], v[204:207], v[58:61]
	v_mfma_f32_16x16x32_f16 v[50:53], v[156:159], v[204:207], v[50:53]
	v_mfma_f32_16x16x32_f16 v[42:45], v[134:137], v[212:215], v[42:45]
	v_mfma_f32_16x16x32_f16 v[34:37], v[156:159], v[212:215], v[34:37]
	v_mfma_f32_16x16x32_f16 v[26:29], v[134:137], v[220:223], v[26:29]
	v_mfma_f32_16x16x32_f16 v[18:21], v[156:159], v[220:223], v[18:21]
	v_mfma_f32_16x16x32_f16 v[10:13], v[134:137], v[228:231], v[10:13]
	v_mfma_f32_16x16x32_f16 v[6:9], v[156:159], v[228:231], v[6:9]
	v_mfma_f32_16x16x32_f16 v[62:65], v[160:163], v[192:195], v[62:65]
	v_mfma_f32_16x16x32_f16 v[54:57], v[184:187], v[192:195], v[54:57]
	v_mfma_f32_16x16x32_f16 v[46:49], v[160:163], v[208:211], v[46:49]
	v_mfma_f32_16x16x32_f16 v[38:41], v[184:187], v[208:211], v[38:41]
	v_mfma_f32_16x16x32_f16 v[30:33], v[160:163], v[216:219], v[30:33]
	v_mfma_f32_16x16x32_f16 v[22:25], v[184:187], v[216:219], v[22:25]
	v_mfma_f32_16x16x32_f16 v[14:17], v[160:163], v[224:227], v[14:17]
	v_mfma_f32_16x16x32_f16 v[2:5], v[184:187], v[224:227], v[2:5]
	v_mfma_f32_16x16x32_f16 v[62:65], v[166:169], v[204:207], v[62:65]
	v_mfma_f32_16x16x32_f16 v[54:57], v[188:191], v[204:207], v[54:57]
	v_mfma_f32_16x16x32_f16 v[46:49], v[166:169], v[212:215], v[46:49]
	v_mfma_f32_16x16x32_f16 v[38:41], v[188:191], v[212:215], v[38:41]
	v_mfma_f32_16x16x32_f16 v[30:33], v[166:169], v[220:223], v[30:33]
	v_mfma_f32_16x16x32_f16 v[22:25], v[188:191], v[220:223], v[22:25]
	v_mfma_f32_16x16x32_f16 v[14:17], v[166:169], v[228:231], v[14:17]
	v_mfma_f32_16x16x32_f16 v[2:5], v[188:191], v[228:231], v[2:5]
	s_setprio 0
	s_barrier
	s_add_u32 s52, s52, 0x100
	s_addc_u32 s53, s53, 0
	s_add_u32 s80, s80, 0x100
	s_addc_u32 s81, s81, 0
	s_cmp_ge_u32 s82, s65
	s_mov_b32 s54, s82
	s_cbranch_scc1 .LBB0_311
; #define PG8_STAGE(bufoff, gbase, voff) do { _Pragma("unroll") for (int _i = 0; _i < 2; ++_i) \
;         __builtin_amdgcn_global_load_lds((const unsigned*)((const char*)(gbase) + (voff)[_i]), (PG8_LAS unsigned*)(lds + (bufoff) + ldsw + _i * 8192), 16, 0, 0); } while (0)
; #define PG8_LDA(dst, b, h) do { _Pragma("unroll") for (int m = 0; m < 4; ++m) _Pragma("unroll") for (int k = 0; k < 2; ++k) dst[m][k] = *(const PG8_LAS bf16x8*)(lds + PG8_SA(b, h) + aoff + m * 2048 + k * 1024); } while (0)
; #define PG8_LDB(dst, b, h) do { _Pragma("unroll") for (int n = 0; n < 2; ++n) _Pragma("unroll") for (int k = 0; k < 2; ++k) dst[n][k] = *(const PG8_LAS bf16x8*)(lds + PG8_SB(b, h) + boff + n * 2048 + k * 1024); } while (0)
; #define PG8_WAIT_V(n) asm volatile("s_waitcnt vmcnt(" #n ")" ::: "memory")
; #define PG8_WAIT_L(n) asm volatile("s_waitcnt lgkmcnt(" #n ")" ::: "memory")
; #define PG8_BAR __builtin_amdgcn_s_barrier()
; #define PG8_SCHED __builtin_amdgcn_sched_barrier(0)
; template <class Epi, class Sched, bool ALIGN_EPI = false, bool SP2 = false, bool F16 = false>
; __device__ __forceinline__ void gemm_phase(PG8_LAS unsigned char* lds, const Gemm g, const Sched& S, const Epi& E) {
;     ...
;             const bool last = (t == nt - 2);
;             const char* a1 = cA + (size_t)(t + 1) * kstep;
;             const char* a2 = last ? nA : cA + (size_t)(t + 2) * kstep; const char* b2 = last ? nB : cB + (size_t)(t + 2) * kstep;
;             const char* a3 = a2 + kstep; const char* b3 = b2 + kstep;
;             if (last && has_next) S.a_ready(nxt);
;             if constexpr (SP2) {
;             PG8_LDB(B0, 0, 0); PG8_LDB(B1, 0, 1); PG8_SCHED; PG8_LDA(At, 0, 0); PG8_STAGE(PG8_SA(1, 1), a1 + hstepA, voffA);
;             PG8_WAIT_V(8); PG8_WAIT_L(0); PG8_BAR; PG8_MMA(0, 0, At, B0); PG8_MMA(0, 1, At, B1); PG8_BAR; PG8_SCHED;
;             PG8_LDA(At, 0, 1); PG8_STAGE(PG8_SB(0, 0), b2, voffB); PG8_STAGE(PG8_SB(0, 1), b2 + hstepB, voffB); PG8_STAGE(PG8_SA(0, 0), a2, voffA);
;             PG8_WAIT_V(8); PG8_WAIT_L(0); PG8_BAR; PG8_MMA(1, 0, At, B0); PG8_MMA(1, 1, At, B1); PG8_BAR; PG8_SCHED;
.LBB0_310:
	s_add_i32 s82, s54, 2
	s_add_u32 s83, s52, 0x80
	s_addc_u32 s55, s53, 0
	s_add_i32 vcc_lo, 0, 0x10000
	s_cmp_eq_u32 s74, s54
	s_cselect_b32 s55, s39, s55
	s_cselect_b32 s54, s38, s83
	s_cselect_b32 s95, s47, s81
	s_cselect_b32 s94, s46, s80
	s_add_i32 s83, 0, 0x14000
	ds_read_b128 v[130:133], v139
	ds_read_b128 v[134:137], v139 offset:1024
	ds_read_b128 v[152:155], v139 offset:2048
	ds_read_b128 v[156:159], v139 offset:3072
	ds_read_b128 v[160:163], v141
	ds_read_b128 v[166:169], v141 offset:1024
	ds_read_b128 v[184:187], v141 offset:2048
	ds_read_b128 v[188:191], v141 offset:3072
	s_add_i32 m0, s22, 0xc000
	ds_read_b128 v[192:195], v183
	ds_read_b128 v[204:207], v183 offset:1024
	ds_read_b128 v[208:211], v183 offset:2048
	ds_read_b128 v[212:215], v183 offset:3072
	ds_read_b128 v[216:219], v183 offset:4096
	ds_read_b128 v[220:223], v183 offset:5120
	ds_read_b128 v[224:227], v183 offset:6144
	ds_read_b128 v[228:231], v183 offset:7168
	global_load_lds_dwordx4 v148, s[52:53]
	s_add_i32 m0, s22, 0xe000
	s_nop 0
	global_load_lds_dwordx4 v150, s[52:53]
	s_waitcnt vmcnt(8)
	s_waitcnt lgkmcnt(0)
	s_setprio 1
	s_barrier
	v_mfma_f32_16x16x32_f16 v[122:125], v[130:133], v[192:195], v[122:125]
	v_mfma_f32_16x16x32_f16 v[114:117], v[152:155], v[192:195], v[114:117]
	v_mfma_f32_16x16x32_f16 v[106:109], v[130:133], v[208:211], v[106:109]
	v_mfma_f32_16x16x32_f16 v[98:101], v[152:155], v[208:211], v[98:101]
	v_mfma_f32_16x16x32_f16 v[90:93], v[130:133], v[216:219], v[90:93]
	v_mfma_f32_16x16x32_f16 v[82:85], v[152:155], v[216:219], v[82:85]
	v_mfma_f32_16x16x32_f16 v[74:77], v[130:133], v[224:227], v[74:77]
	v_mfma_f32_16x16x32_f16 v[66:69], v[152:155], v[224:227], v[66:69]
	v_mfma_f32_16x16x32_f16 v[122:125], v[134:137], v[204:207], v[122:125]
	v_mfma_f32_16x16x32_f16 v[114:117], v[156:159], v[204:207], v[114:117]
	v_mfma_f32_16x16x32_f16 v[106:109], v[134:137], v[212:215], v[106:109]
	v_mfma_f32_16x16x32_f16 v[98:101], v[156:159], v[212:215], v[98:101]
	v_mfma_f32_16x16x32_f16 v[90:93], v[134:137], v[220:223], v[90:93]
	v_mfma_f32_16x16x32_f16 v[82:85], v[156:159], v[220:223], v[82:85]
	v_mfma_f32_16x16x32_f16 v[74:77], v[134:137], v[228:231], v[74:77]
	v_mfma_f32_16x16x32_f16 v[66:69], v[156:159], v[228:231], v[66:69]
	v_mfma_f32_16x16x32_f16 v[126:129], v[160:163], v[192:195], v[126:129]
	v_mfma_f32_16x16x32_f16 v[118:121], v[184:187], v[192:195], v[118:121]
	v_mfma_f32_16x16x32_f16 v[110:113], v[160:163], v[208:211], v[110:113]
	v_mfma_f32_16x16x32_f16 v[102:105], v[184:187], v[208:211], v[102:105]
	v_mfma_f32_16x16x32_f16 v[94:97], v[160:163], v[216:219], v[94:97]
	v_mfma_f32_16x16x32_f16 v[86:89], v[184:187], v[216:219], v[86:89]
	v_mfma_f32_16x16x32_f16 v[78:81], v[160:163], v[224:227], v[78:81]
	v_mfma_f32_16x16x32_f16 v[70:73], v[184:187], v[224:227], v[70:73]
	v_mfma_f32_16x16x32_f16 v[126:129], v[166:169], v[204:207], v[126:129]
	v_mfma_f32_16x16x32_f16 v[118:121], v[188:191], v[204:207], v[118:121]
	v_mfma_f32_16x16x32_f16 v[110:113], v[166:169], v[212:215], v[110:113]
	v_mfma_f32_16x16x32_f16 v[102:105], v[188:191], v[212:215], v[102:105]
	v_mfma_f32_16x16x32_f16 v[94:97], v[166:169], v[220:223], v[94:97]
	v_mfma_f32_16x16x32_f16 v[86:89], v[188:191], v[220:223], v[86:89]
	v_mfma_f32_16x16x32_f16 v[78:81], v[166:169], v[228:231], v[78:81]
	v_mfma_f32_16x16x32_f16 v[70:73], v[188:191], v[228:231], v[70:73]
	s_setprio 0
	s_barrier
	s_add_i32 vcc_lo, vcc_lo, s2
	s_mov_b32 m0, vcc_lo
	s_nop 0
	global_load_lds_dwordx4 v142, s[94:95]
	ds_read_b128 v[192:195], v183 offset:16384
	ds_read_b128 v[204:207], v183 offset:17408
	ds_read_b128 v[208:211], v183 offset:18432
	ds_read_b128 v[212:215], v183 offset:19456
	ds_read_b128 v[216:219], v183 offset:20480
	ds_read_b128 v[220:223], v183 offset:21504
	ds_read_b128 v[224:227], v183 offset:22528
	ds_read_b128 v[228:231], v183 offset:23552
	s_add_i32 m0, vcc_lo, 0x2000
	s_nop 0
	global_load_lds_dwordx4 v138, s[94:95]
	s_add_i32 s83, s83, s2
	s_add_u32 s94, s94, s48
	s_addc_u32 s95, s95, 0
	s_mov_b32 m0, s83
	s_nop 0
	global_load_lds_dwordx4 v142, s[94:95]
	s_add_i32 m0, s83, 0x2000
	s_nop 0
	global_load_lds_dwordx4 v138, s[94:95]
	s_mov_b32 m0, s22
	s_nop 0
	global_load_lds_dwordx4 v144, s[54:55]
	s_mov_b32 m0, s33
	s_nop 0
	global_load_lds_dwordx4 v140, s[54:55]
	s_waitcnt vmcnt(8)
	s_waitcnt lgkmcnt(0)
	s_setprio 1
	s_barrier
	v_mfma_f32_16x16x32_f16 v[58:61], v[130:133], v[192:195], v[58:61]
	v_mfma_f32_16x16x32_f16 v[50:53], v[152:155], v[192:195], v[50:53]
	v_mfma_f32_16x16x32_f16 v[42:45], v[130:133], v[208:211], v[42:45]
	v_mfma_f32_16x16x32_f16 v[34:37], v[152:155], v[208:211], v[34:37]
	v_mfma_f32_16x16x32_f16 v[26:29], v[130:133], v[216:219], v[26:29]
	v_mfma_f32_16x16x32_f16 v[18:21], v[152:155], v[216:219], v[18:21]
	v_mfma_f32_16x16x32_f16 v[10:13], v[130:133], v[224:227], v[10:13]
	v_mfma_f32_16x16x32_f16 v[6:9], v[152:155], v[224:227], v[6:9]
	v_mfma_f32_16x16x32_f16 v[58:61], v[134:137], v[204:207], v[58:61]
	v_mfma_f32_16x16x32_f16 v[50:53], v[156:159], v[204:207], v[50:53]
	v_mfma_f32_16x16x32_f16 v[42:45], v[134:137], v[212:215], v[42:45]
	v_mfma_f32_16x16x32_f16 v[34:37], v[156:159], v[212:215], v[34:37]
	v_mfma_f32_16x16x32_f16 v[26:29], v[134:137], v[220:223], v[26:29]
	v_mfma_f32_16x16x32_f16 v[18:21], v[156:159], v[220:223], v[18:21]
	v_mfma_f32_16x16x32_f16 v[10:13], v[134:137], v[228:231], v[10:13]
	v_mfma_f32_16x16x32_f16 v[6:9], v[156:159], v[228:231], v[6:9]
	v_mfma_f32_16x16x32_f16 v[62:65], v[160:163], v[192:195], v[62:65]
	v_mfma_f32_16x16x32_f16 v[54:57], v[184:187], v[192:195], v[54:57]
	v_mfma_f32_16x16x32_f16 v[46:49], v[160:163], v[208:211], v[46:49]
	v_mfma_f32_16x16x32_f16 v[38:41], v[184:187], v[208:211], v[38:41]
	v_mfma_f32_16x16x32_f16 v[30:33], v[160:163], v[216:219], v[30:33]
	v_mfma_f32_16x16x32_f16 v[22:25], v[184:187], v[216:219], v[22:25]
	v_mfma_f32_16x16x32_f16 v[14:17], v[160:163], v[224:227], v[14:17]
	v_mfma_f32_16x16x32_f16 v[2:5], v[184:187], v[224:227], v[2:5]
	v_mfma_f32_16x16x32_f16 v[62:65], v[166:169], v[204:207], v[62:65]
	v_mfma_f32_16x16x32_f16 v[54:57], v[188:191], v[204:207], v[54:57]
	v_mfma_f32_16x16x32_f16 v[46:49], v[166:169], v[212:215], v[46:49]
	v_mfma_f32_16x16x32_f16 v[38:41], v[188:191], v[212:215], v[38:41]
	v_mfma_f32_16x16x32_f16 v[30:33], v[166:169], v[220:223], v[30:33]
	v_mfma_f32_16x16x32_f16 v[22:25], v[188:191], v[220:223], v[22:25]
	v_mfma_f32_16x16x32_f16 v[14:17], v[166:169], v[228:231], v[14:17]
	v_mfma_f32_16x16x32_f16 v[2:5], v[188:191], v[228:231], v[2:5]
	s_setprio 0
	s_barrier
; #define PG8_STAGE(bufoff, gbase, voff) do { _Pragma("unroll") for (int _i = 0; _i < 2; ++_i) \
;         __builtin_amdgcn_global_load_lds((const unsigned*)((const char*)(gbase) + (voff)[_i]), (PG8_LAS unsigned*)(lds + (bufoff) + ldsw + _i * 8192), 16, 0, 0); } while (0)
; #define PG8_LDA(dst, b, h) do { _Pragma("unroll") for (int m = 0; m < 4; ++m) _Pragma("unroll") for (int k = 0; k < 2; ++k) dst[m][k] = *(const PG8_LAS bf16x8*)(lds + PG8_SA(b, h) + aoff + m * 2048 + k * 1024); } while (0)
; #define PG8_LDB(dst, b, h) do { _Pragma("unroll") for (int n = 0; n < 2; ++n) _Pragma("unroll") for (int k = 0; k < 2; ++k) dst[n][k] = *(const PG8_LAS bf16x8*)(lds + PG8_SB(b, h) + boff + n * 2048 + k * 1024); } while (0)
; #define PG8_WAIT_V(n) asm volatile("s_waitcnt vmcnt(" #n ")" ::: "memory")
; #define PG8_WAIT_L(n) asm volatile("s_waitcnt lgkmcnt(" #n ")" ::: "memory")
; #define PG8_BAR __builtin_amdgcn_s_barrier()
; #define PG8_SCHED __builtin_amdgcn_sched_barrier(0)
; template <class Epi, class Sched, bool ALIGN_EPI = false, bool SP2 = false, bool F16 = false>
; __device__ __forceinline__ void gemm_phase(PG8_LAS unsigned char* lds, const Gemm g, const Sched& S, const Epi& E) {
;     ...
;         for (int t = 0; t < nt; t += 2) {
;             const bool last = (t == nt - 2);
;             const char* a1 = cA + (size_t)(t + 1) * kstep;
;             const char* a2 = last ? nA : cA + (size_t)(t + 2) * kstep; const char* b2 = last ? nB : cB + (size_t)(t + 2) * kstep;
;             const char* a3 = a2 + kstep; const char* b3 = b2 + kstep;
;     ...
;             PG8_LDB(B0, 1, 0); PG8_LDB(B1, 1, 1); PG8_SCHED; PG8_LDA(At, 1, 0); PG8_STAGE(PG8_SA(0, 1), a2 + hstepA, voffA);
;             PG8_WAIT_V(8); PG8_WAIT_L(0); PG8_BAR; PG8_MMA(0, 0, At, B0); PG8_MMA(0, 1, At, B1); PG8_BAR; PG8_SCHED;
;             PG8_LDA(At, 1, 1); PG8_STAGE(PG8_SB(1, 0), b3, voffB); PG8_STAGE(PG8_SB(1, 1), b3 + hstepB, voffB); PG8_STAGE(PG8_SA(1, 0), a3, voffA);
;             PG8_WAIT_V(8); PG8_WAIT_L(0); PG8_BAR; PG8_MMA(1, 0, At, B0); PG8_MMA(1, 1, At, B1); PG8_BAR; PG8_SCHED;
	s_add_i32 s83, 0, 0x18000
	s_add_i32 s94, 0, 0x1c000
	ds_read_b128 v[130:133], v143
	ds_read_b128 v[134:137], v143 offset:1024
	ds_read_b128 v[152:155], v143 offset:2048
	ds_read_b128 v[156:159], v143 offset:3072
	ds_read_b128 v[160:163], v145
	ds_read_b128 v[166:169], v145 offset:1024
	ds_read_b128 v[184:187], v145 offset:2048
	ds_read_b128 v[188:191], v145 offset:3072
	s_add_u32 s54, s54, s8
	s_addc_u32 s55, s55, 0
	s_mov_b32 m0, s12
	ds_read_b128 v[192:195], v183 offset:32768
	ds_read_b128 v[204:207], v183 offset:33792
	ds_read_b128 v[208:211], v183 offset:34816
	ds_read_b128 v[212:215], v183 offset:35840
	ds_read_b128 v[216:219], v183 offset:36864
	ds_read_b128 v[220:223], v183 offset:37888
	ds_read_b128 v[224:227], v183 offset:38912
	ds_read_b128 v[228:231], v183 offset:39936
	global_load_lds_dwordx4 v144, s[54:55]
	s_mov_b32 m0, s13
	s_nop 0
	global_load_lds_dwordx4 v140, s[54:55]
	s_waitcnt vmcnt(8)
	s_waitcnt lgkmcnt(0)
	s_setprio 1
	s_barrier
	v_mfma_f32_16x16x32_f16 v[122:125], v[130:133], v[192:195], v[122:125]
	v_mfma_f32_16x16x32_f16 v[114:117], v[152:155], v[192:195], v[114:117]
	v_mfma_f32_16x16x32_f16 v[106:109], v[130:133], v[208:211], v[106:109]
	v_mfma_f32_16x16x32_f16 v[98:101], v[152:155], v[208:211], v[98:101]
	v_mfma_f32_16x16x32_f16 v[90:93], v[130:133], v[216:219], v[90:93]
	v_mfma_f32_16x16x32_f16 v[82:85], v[152:155], v[216:219], v[82:85]
	v_mfma_f32_16x16x32_f16 v[74:77], v[130:133], v[224:227], v[74:77]
	v_mfma_f32_16x16x32_f16 v[66:69], v[152:155], v[224:227], v[66:69]
	v_mfma_f32_16x16x32_f16 v[122:125], v[134:137], v[204:207], v[122:125]
	v_mfma_f32_16x16x32_f16 v[114:117], v[156:159], v[204:207], v[114:117]
	v_mfma_f32_16x16x32_f16 v[106:109], v[134:137], v[212:215], v[106:109]
	v_mfma_f32_16x16x32_f16 v[98:101], v[156:159], v[212:215], v[98:101]
	v_mfma_f32_16x16x32_f16 v[90:93], v[134:137], v[220:223], v[90:93]
	v_mfma_f32_16x16x32_f16 v[82:85], v[156:159], v[220:223], v[82:85]
	v_mfma_f32_16x16x32_f16 v[74:77], v[134:137], v[228:231], v[74:77]
	v_mfma_f32_16x16x32_f16 v[66:69], v[156:159], v[228:231], v[66:69]
	v_mfma_f32_16x16x32_f16 v[126:129], v[160:163], v[192:195], v[126:129]
	v_mfma_f32_16x16x32_f16 v[118:121], v[184:187], v[192:195], v[118:121]
	v_mfma_f32_16x16x32_f16 v[110:113], v[160:163], v[208:211], v[110:113]
	v_mfma_f32_16x16x32_f16 v[102:105], v[184:187], v[208:211], v[102:105]
	v_mfma_f32_16x16x32_f16 v[94:97], v[160:163], v[216:219], v[94:97]
	v_mfma_f32_16x16x32_f16 v[86:89], v[184:187], v[216:219], v[86:89]
	v_mfma_f32_16x16x32_f16 v[78:81], v[160:163], v[224:227], v[78:81]
	v_mfma_f32_16x16x32_f16 v[70:73], v[184:187], v[224:227], v[70:73]
	v_mfma_f32_16x16x32_f16 v[126:129], v[166:169], v[204:207], v[126:129]
	v_mfma_f32_16x16x32_f16 v[118:121], v[188:191], v[204:207], v[118:121]
	v_mfma_f32_16x16x32_f16 v[110:113], v[166:169], v[212:215], v[110:113]
	v_mfma_f32_16x16x32_f16 v[102:105], v[188:191], v[212:215], v[102:105]
	v_mfma_f32_16x16x32_f16 v[94:97], v[166:169], v[220:223], v[94:97]
	v_mfma_f32_16x16x32_f16 v[86:89], v[188:191], v[220:223], v[86:89]
	v_mfma_f32_16x16x32_f16 v[78:81], v[166:169], v[228:231], v[78:81]
	v_mfma_f32_16x16x32_f16 v[70:73], v[188:191], v[228:231], v[70:73]
	s_setprio 0
	s_barrier
	s_add_i32 s54, s83, s2
	s_add_i32 vcc_hi, s82, -2
	s_cmp_eq_u32 s74, vcc_hi
	s_cselect_b32 s99, s47, s81
	s_cselect_b32 s98, s46, s80
	s_add_u32 s98, s98, s92
	s_addc_u32 s99, s99, s93
	s_mov_b32 m0, s54
	s_nop 0
	global_load_lds_dwordx4 v142, s[98:99]
	ds_read_b128 v[192:195], v183 offset:49152
	ds_read_b128 v[204:207], v183 offset:50176
	ds_read_b128 v[208:211], v183 offset:51200
	ds_read_b128 v[212:215], v183 offset:52224
	ds_read_b128 v[216:219], v183 offset:53248
	ds_read_b128 v[220:223], v183 offset:54272
	ds_read_b128 v[224:227], v183 offset:55296
	ds_read_b128 v[228:231], v183 offset:56320
	s_add_i32 m0, s54, 0x2000
	s_nop 0
	global_load_lds_dwordx4 v138, s[98:99]
	s_add_i32 s54, s94, s2
	s_add_u32 s98, s98, s48
	s_addc_u32 s99, s99, 0
	s_mov_b32 m0, s54
	s_nop 0
	global_load_lds_dwordx4 v142, s[98:99]
	s_add_i32 m0, s54, 0x2000
	s_nop 0
	global_load_lds_dwordx4 v138, s[98:99]
	s_add_u32 s98, s52, 0x80
	s_addc_u32 s99, s53, 0
	s_cmp_eq_u32 s74, vcc_hi
	s_cselect_b32 s99, s39, s99
	s_cselect_b32 s98, s38, s98
	s_add_u32 s98, s98, s92
	s_addc_u32 s99, s99, s93
	s_mov_b32 m0, s35
	s_nop 0
	global_load_lds_dwordx4 v144, s[98:99]
	s_mov_b32 m0, s59
	s_nop 0
	global_load_lds_dwordx4 v140, s[98:99]
	s_waitcnt vmcnt(8)
	s_waitcnt lgkmcnt(0)
	s_setprio 1
	s_barrier
	v_mfma_f32_16x16x32_f16 v[58:61], v[130:133], v[192:195], v[58:61]
	v_mfma_f32_16x16x32_f16 v[50:53], v[152:155], v[192:195], v[50:53]
	v_mfma_f32_16x16x32_f16 v[42:45], v[130:133], v[208:211], v[42:45]
	v_mfma_f32_16x16x32_f16 v[34:37], v[152:155], v[208:211], v[34:37]
	v_mfma_f32_16x16x32_f16 v[26:29], v[130:133], v[216:219], v[26:29]
	v_mfma_f32_16x16x32_f16 v[18:21], v[152:155], v[216:219], v[18:21]
	v_mfma_f32_16x16x32_f16 v[10:13], v[130:133], v[224:227], v[10:13]
	v_mfma_f32_16x16x32_f16 v[6:9], v[152:155], v[224:227], v[6:9]
	v_mfma_f32_16x16x32_f16 v[58:61], v[134:137], v[204:207], v[58:61]
	v_mfma_f32_16x16x32_f16 v[50:53], v[156:159], v[204:207], v[50:53]
	v_mfma_f32_16x16x32_f16 v[42:45], v[134:137], v[212:215], v[42:45]
	v_mfma_f32_16x16x32_f16 v[34:37], v[156:159], v[212:215], v[34:37]
	v_mfma_f32_16x16x32_f16 v[26:29], v[134:137], v[220:223], v[26:29]
	v_mfma_f32_16x16x32_f16 v[18:21], v[156:159], v[220:223], v[18:21]
	v_mfma_f32_16x16x32_f16 v[10:13], v[134:137], v[228:231], v[10:13]
	v_mfma_f32_16x16x32_f16 v[6:9], v[156:159], v[228:231], v[6:9]
	v_mfma_f32_16x16x32_f16 v[62:65], v[160:163], v[192:195], v[62:65]
	v_mfma_f32_16x16x32_f16 v[54:57], v[184:187], v[192:195], v[54:57]
	v_mfma_f32_16x16x32_f16 v[46:49], v[160:163], v[208:211], v[46:49]
	v_mfma_f32_16x16x32_f16 v[38:41], v[184:187], v[208:211], v[38:41]
	v_mfma_f32_16x16x32_f16 v[30:33], v[160:163], v[216:219], v[30:33]
	v_mfma_f32_16x16x32_f16 v[22:25], v[184:187], v[216:219], v[22:25]
	v_mfma_f32_16x16x32_f16 v[14:17], v[160:163], v[224:227], v[14:17]
	v_mfma_f32_16x16x32_f16 v[2:5], v[184:187], v[224:227], v[2:5]
	v_mfma_f32_16x16x32_f16 v[62:65], v[166:169], v[204:207], v[62:65]
	v_mfma_f32_16x16x32_f16 v[54:57], v[188:191], v[204:207], v[54:57]
	v_mfma_f32_16x16x32_f16 v[46:49], v[166:169], v[212:215], v[46:49]
	v_mfma_f32_16x16x32_f16 v[38:41], v[188:191], v[212:215], v[38:41]
	v_mfma_f32_16x16x32_f16 v[30:33], v[166:169], v[220:223], v[30:33]
	v_mfma_f32_16x16x32_f16 v[22:25], v[188:191], v[220:223], v[22:25]
	v_mfma_f32_16x16x32_f16 v[14:17], v[166:169], v[228:231], v[14:17]
	v_mfma_f32_16x16x32_f16 v[2:5], v[188:191], v[228:231], v[2:5]
	s_setprio 0
	s_barrier
	s_add_u32 s52, s52, 0x100
	s_addc_u32 s53, s53, 0
	s_add_u32 s80, s80, 0x100
	s_addc_u32 s81, s81, 0
	s_cmp_ge_u32 s82, s65
	s_mov_b32 s54, s82
	s_cbranch_scc0 .LBB0_310

; #define PG8_STAGE(bufoff, gbase, voff) do { _Pragma("unroll") for (int _i = 0; _i < 2; ++_i) \
;         __builtin_amdgcn_global_load_lds((const unsigned*)((const char*)(gbase) + (voff)[_i]), (PG8_LAS unsigned*)(lds + (bufoff) + ldsw + _i * 8192), 16, 0, 0); } while (0)
; #define PG8_LDA(dst, b, h) do { _Pragma("unroll") for (int m = 0; m < 4; ++m) _Pragma("unroll") for (int k = 0; k < 2; ++k) dst[m][k] = *(const PG8_LAS bf16x8*)(lds + PG8_SA(b, h) + aoff + m * 2048 + k * 1024); } while (0)
; #define PG8_LDB(dst, b, h) do { _Pragma("unroll") for (int n = 0; n < 2; ++n) _Pragma("unroll") for (int k = 0; k < 2; ++k) dst[n][k] = *(const PG8_LAS bf16x8*)(lds + PG8_SB(b, h) + boff + n * 2048 + k * 1024); } while (0)
; #define PG8_WAIT_V(n) asm volatile("s_waitcnt vmcnt(" #n ")" ::: "memory")
; #define PG8_WAIT_L(n) asm volatile("s_waitcnt lgkmcnt(" #n ")" ::: "memory")
; #define PG8_BAR __builtin_amdgcn_s_barrier()
; #define PG8_SCHED __builtin_amdgcn_sched_barrier(0)
; template <class Epi, class Sched, bool ALIGN_EPI = false, bool SP2 = false, bool F16 = false>
; __device__ __forceinline__ void gemm_phase(PG8_LAS unsigned char* lds, const Gemm g, const Sched& S, const Epi& E) {
;     ...
;         for (int t = 0; t < nt; t += 2) {
;             const bool last = (t == nt - 2);
;             const char* a1 = cA + (size_t)(t + 1) * kstep;
;             const char* a2 = last ? nA : cA + (size_t)(t + 2) * kstep; const char* b2 = last ? nB : cB + (size_t)(t + 2) * kstep;
;             const char* a3 = a2 + kstep; const char* b3 = b2 + kstep;
;             if (last && has_next) S.a_ready(nxt);
;             if constexpr (SP2) {
;             PG8_LDB(B0, 0, 0); PG8_LDB(B1, 0, 1); PG8_SCHED; PG8_LDA(At, 0, 0); PG8_STAGE(PG8_SA(1, 1), a1 + hstepA, voffA);
;             PG8_WAIT_V(8); PG8_WAIT_L(0); PG8_BAR; PG8_MMA(0, 0, At, B0); PG8_MMA(0, 1, At, B1); PG8_BAR; PG8_SCHED;
;             PG8_LDA(At, 0, 1); PG8_STAGE(PG8_SB(0, 0), b2, voffB); PG8_STAGE(PG8_SB(0, 1), b2 + hstepB, voffB); PG8_STAGE(PG8_SA(0, 0), a2, voffA);
;             PG8_WAIT_V(8); PG8_WAIT_L(0); PG8_BAR; PG8_MMA(1, 0, At, B0); PG8_MMA(1, 1, At, B1); PG8_BAR; PG8_SCHED;
.Lpk_rs:
	s_add_i32 s81, s54, 2
	s_add_u32 s82, s52, 0x80
	s_addc_u32 s55, s53, 0
	s_add_i32 s94, 0, 0x10000
	s_cmp_eq_u32 s74, s54
	s_cselect_b32 s55, s41, s55
	s_cselect_b32 s54, s40, s82
	s_cselect_b32 s83, s47, s80
	s_cselect_b32 s82, s46, s79
	s_add_i32 s95, 0, 0x14000
	ds_read_b128 v[130:133], v139
	ds_read_b128 v[134:137], v139 offset:1024
	ds_read_b128 v[148:151], v139 offset:2048
	ds_read_b128 v[152:155], v139 offset:3072
	ds_read_b128 v[162:165], v141
	ds_read_b128 v[166:169], v141 offset:1024
	ds_read_b128 v[170:173], v141 offset:2048
	ds_read_b128 v[182:185], v141 offset:3072
	s_add_i32 m0, s3, 0xc000
	ds_read_b128 v[186:189], v160
	ds_read_b128 v[190:193], v160 offset:1024
	ds_read_b128 v[194:197], v160 offset:2048
	ds_read_b128 v[204:207], v160 offset:3072
	ds_read_b128 v[208:211], v160 offset:4096
	ds_read_b128 v[212:215], v160 offset:5120
	ds_read_b128 v[216:219], v160 offset:6144
	ds_read_b128 v[220:223], v160 offset:7168
	global_load_lds_dwordx4 v144, s[52:53]
	s_add_i32 m0, s3, 0xe000
	s_nop 0
	global_load_lds_dwordx4 v146, s[52:53]
	s_waitcnt vmcnt(8)
	s_waitcnt lgkmcnt(0)
	s_setprio 1
	s_barrier
	v_mfma_f32_16x16x32_bf16 v[122:125], v[130:133], v[186:189], 0
	v_mfma_f32_16x16x32_bf16 v[126:129], v[148:151], v[186:189], 0
	v_mfma_f32_16x16x32_bf16 v[110:113], v[130:133], v[194:197], 0
	v_mfma_f32_16x16x32_bf16 v[106:109], v[148:151], v[194:197], 0
	v_mfma_f32_16x16x32_bf16 v[94:97], v[130:133], v[208:211], 0
	v_mfma_f32_16x16x32_bf16 v[90:93], v[148:151], v[208:211], 0
	v_mfma_f32_16x16x32_bf16 v[78:81], v[130:133], v[216:219], 0
	v_mfma_f32_16x16x32_bf16 v[74:77], v[148:151], v[216:219], 0
	v_mfma_f32_16x16x32_bf16 v[122:125], v[134:137], v[190:193], v[122:125]
	v_mfma_f32_16x16x32_bf16 v[126:129], v[152:155], v[190:193], v[126:129]
	v_mfma_f32_16x16x32_bf16 v[110:113], v[134:137], v[204:207], v[110:113]
	v_mfma_f32_16x16x32_bf16 v[106:109], v[152:155], v[204:207], v[106:109]
	v_mfma_f32_16x16x32_bf16 v[94:97], v[134:137], v[212:215], v[94:97]
	v_mfma_f32_16x16x32_bf16 v[90:93], v[152:155], v[212:215], v[90:93]
	v_mfma_f32_16x16x32_bf16 v[78:81], v[134:137], v[220:223], v[78:81]
	v_mfma_f32_16x16x32_bf16 v[74:77], v[152:155], v[220:223], v[74:77]
	v_mfma_f32_16x16x32_bf16 v[118:121], v[162:165], v[186:189], 0
	v_mfma_f32_16x16x32_bf16 v[114:117], v[170:173], v[186:189], 0
	v_mfma_f32_16x16x32_bf16 v[102:105], v[162:165], v[194:197], 0
	v_mfma_f32_16x16x32_bf16 v[98:101], v[170:173], v[194:197], 0
	v_mfma_f32_16x16x32_bf16 v[86:89], v[162:165], v[208:211], 0
	v_mfma_f32_16x16x32_bf16 v[82:85], v[170:173], v[208:211], 0
	v_mfma_f32_16x16x32_bf16 v[70:73], v[162:165], v[216:219], 0
	v_mfma_f32_16x16x32_bf16 v[66:69], v[170:173], v[216:219], 0
	v_mfma_f32_16x16x32_bf16 v[118:121], v[166:169], v[190:193], v[118:121]
	v_mfma_f32_16x16x32_bf16 v[114:117], v[182:185], v[190:193], v[114:117]
	v_mfma_f32_16x16x32_bf16 v[102:105], v[166:169], v[204:207], v[102:105]
	v_mfma_f32_16x16x32_bf16 v[98:101], v[182:185], v[204:207], v[98:101]
	v_mfma_f32_16x16x32_bf16 v[86:89], v[166:169], v[212:215], v[86:89]
	v_mfma_f32_16x16x32_bf16 v[82:85], v[182:185], v[212:215], v[82:85]
	v_mfma_f32_16x16x32_bf16 v[70:73], v[166:169], v[220:223], v[70:73]
	v_mfma_f32_16x16x32_bf16 v[66:69], v[182:185], v[220:223], v[66:69]
	s_setprio 0
	s_barrier
	s_add_i32 s94, s94, s2
	s_mov_b32 m0, s94
	s_nop 0
	global_load_lds_dwordx4 v174, s[82:83]
	ds_read_b128 v[186:189], v160 offset:16384
	ds_read_b128 v[190:193], v160 offset:17408
	ds_read_b128 v[194:197], v160 offset:18432
	ds_read_b128 v[204:207], v160 offset:19456
	ds_read_b128 v[208:211], v160 offset:20480
	ds_read_b128 v[212:215], v160 offset:21504
	ds_read_b128 v[216:219], v160 offset:22528
	ds_read_b128 v[220:223], v160 offset:23552
	s_add_i32 m0, s94, 0x2000
	s_nop 0
	global_load_lds_dwordx4 v142, s[82:83]
	s_add_i32 s94, s95, s2
	s_add_u32 s82, s82, s48
	s_addc_u32 s83, s83, 0
	s_mov_b32 m0, s94
	s_nop 0
	global_load_lds_dwordx4 v174, s[82:83]
	s_add_i32 m0, s94, 0x2000
	s_nop 0
	global_load_lds_dwordx4 v142, s[82:83]
	s_mov_b32 m0, s3
	s_nop 0
	global_load_lds_dwordx4 v138, s[54:55]
	s_mov_b32 m0, s12
	s_nop 0
	global_load_lds_dwordx4 v140, s[54:55]
	s_waitcnt vmcnt(8)
	s_waitcnt lgkmcnt(0)
	s_setprio 1
	s_barrier
	v_mfma_f32_16x16x32_bf16 v[62:65], v[130:133], v[186:189], 0
	v_mfma_f32_16x16x32_bf16 v[58:61], v[148:151], v[186:189], 0
	v_mfma_f32_16x16x32_bf16 v[46:49], v[130:133], v[194:197], 0
	v_mfma_f32_16x16x32_bf16 v[42:45], v[148:151], v[194:197], 0
	v_mfma_f32_16x16x32_bf16 v[30:33], v[130:133], v[208:211], 0
	v_mfma_f32_16x16x32_bf16 v[26:29], v[148:151], v[208:211], 0
	v_mfma_f32_16x16x32_bf16 v[14:17], v[130:133], v[216:219], 0
	v_mfma_f32_16x16x32_bf16 v[10:13], v[148:151], v[216:219], 0
	v_mfma_f32_16x16x32_bf16 v[62:65], v[134:137], v[190:193], v[62:65]
	v_mfma_f32_16x16x32_bf16 v[58:61], v[152:155], v[190:193], v[58:61]
	v_mfma_f32_16x16x32_bf16 v[46:49], v[134:137], v[204:207], v[46:49]
	v_mfma_f32_16x16x32_bf16 v[42:45], v[152:155], v[204:207], v[42:45]
	v_mfma_f32_16x16x32_bf16 v[30:33], v[134:137], v[212:215], v[30:33]
	v_mfma_f32_16x16x32_bf16 v[26:29], v[152:155], v[212:215], v[26:29]
	v_mfma_f32_16x16x32_bf16 v[14:17], v[134:137], v[220:223], v[14:17]
	v_mfma_f32_16x16x32_bf16 v[10:13], v[152:155], v[220:223], v[10:13]
	v_mfma_f32_16x16x32_bf16 v[54:57], v[162:165], v[186:189], 0
	v_mfma_f32_16x16x32_bf16 v[50:53], v[170:173], v[186:189], 0
	v_mfma_f32_16x16x32_bf16 v[38:41], v[162:165], v[194:197], 0
	v_mfma_f32_16x16x32_bf16 v[34:37], v[170:173], v[194:197], 0
	v_mfma_f32_16x16x32_bf16 v[22:25], v[162:165], v[208:211], 0
	v_mfma_f32_16x16x32_bf16 v[18:21], v[170:173], v[208:211], 0
	v_mfma_f32_16x16x32_bf16 v[6:9], v[162:165], v[216:219], 0
	v_mfma_f32_16x16x32_bf16 v[2:5], v[170:173], v[216:219], 0
	v_mfma_f32_16x16x32_bf16 v[54:57], v[166:169], v[190:193], v[54:57]
	v_mfma_f32_16x16x32_bf16 v[50:53], v[182:185], v[190:193], v[50:53]
	v_mfma_f32_16x16x32_bf16 v[38:41], v[166:169], v[204:207], v[38:41]
	v_mfma_f32_16x16x32_bf16 v[34:37], v[182:185], v[204:207], v[34:37]
	v_mfma_f32_16x16x32_bf16 v[22:25], v[166:169], v[212:215], v[22:25]
	v_mfma_f32_16x16x32_bf16 v[18:21], v[182:185], v[212:215], v[18:21]
	v_mfma_f32_16x16x32_bf16 v[6:9], v[166:169], v[220:223], v[6:9]
	v_mfma_f32_16x16x32_bf16 v[2:5], v[182:185], v[220:223], v[2:5]
	s_setprio 0
	s_barrier
; #define PG8_STAGE(bufoff, gbase, voff) do { _Pragma("unroll") for (int _i = 0; _i < 2; ++_i) \
;         __builtin_amdgcn_global_load_lds((const unsigned*)((const char*)(gbase) + (voff)[_i]), (PG8_LAS unsigned*)(lds + (bufoff) + ldsw + _i * 8192), 16, 0, 0); } while (0)
; #define PG8_LDA(dst, b, h) do { _Pragma("unroll") for (int m = 0; m < 4; ++m) _Pragma("unroll") for (int k = 0; k < 2; ++k) dst[m][k] = *(const PG8_LAS bf16x8*)(lds + PG8_SA(b, h) + aoff + m * 2048 + k * 1024); } while (0)
; #define PG8_LDB(dst, b, h) do { _Pragma("unroll") for (int n = 0; n < 2; ++n) _Pragma("unroll") for (int k = 0; k < 2; ++k) dst[n][k] = *(const PG8_LAS bf16x8*)(lds + PG8_SB(b, h) + boff + n * 2048 + k * 1024); } while (0)
; #define PG8_WAIT_V(n) asm volatile("s_waitcnt vmcnt(" #n ")" ::: "memory")
; #define PG8_WAIT_L(n) asm volatile("s_waitcnt lgkmcnt(" #n ")" ::: "memory")
; #define PG8_BAR __builtin_amdgcn_s_barrier()
; #define PG8_SCHED __builtin_amdgcn_sched_barrier(0)
; template <class Epi, class Sched, bool ALIGN_EPI = false, bool SP2 = false, bool F16 = false>
; __device__ __forceinline__ void gemm_phase(PG8_LAS unsigned char* lds, const Gemm g, const Sched& S, const Epi& E) {
;     ...
;         for (int t = 0; t < nt; t += 2) {
;             const bool last = (t == nt - 2);
;             const char* a1 = cA + (size_t)(t + 1) * kstep;
;             const char* a2 = last ? nA : cA + (size_t)(t + 2) * kstep; const char* b2 = last ? nB : cB + (size_t)(t + 2) * kstep;
;             const char* a3 = a2 + kstep; const char* b3 = b2 + kstep;
;     ...
;             PG8_LDB(B0, 1, 0); PG8_LDB(B1, 1, 1); PG8_SCHED; PG8_LDA(At, 1, 0); PG8_STAGE(PG8_SA(0, 1), a2 + hstepA, voffA);
;             PG8_WAIT_V(8); PG8_WAIT_L(0); PG8_BAR; PG8_MMA(0, 0, At, B0); PG8_MMA(0, 1, At, B1); PG8_BAR; PG8_SCHED;
;             PG8_LDA(At, 1, 1); PG8_STAGE(PG8_SB(1, 0), b3, voffB); PG8_STAGE(PG8_SB(1, 1), b3 + hstepB, voffB); PG8_STAGE(PG8_SA(1, 0), a3, voffA);
;             PG8_WAIT_V(8); PG8_WAIT_L(0); PG8_BAR; PG8_MMA(1, 0, At, B0); PG8_MMA(1, 1, At, B1); PG8_BAR; PG8_SCHED;
	s_add_i32 s82, 0, 0x18000
	s_add_i32 s83, 0, 0x1c000
	ds_read_b128 v[130:133], v143
	ds_read_b128 v[134:137], v143 offset:1024
	ds_read_b128 v[148:151], v143 offset:2048
	ds_read_b128 v[152:155], v143 offset:3072
	ds_read_b128 v[162:165], v157
	ds_read_b128 v[166:169], v157 offset:1024
	ds_read_b128 v[170:173], v157 offset:2048
	ds_read_b128 v[182:185], v157 offset:3072
	s_add_u32 s54, s54, s8
	s_addc_u32 s55, s55, 0
	s_mov_b32 m0, s13
	ds_read_b128 v[186:189], v160 offset:32768
	ds_read_b128 v[190:193], v160 offset:33792
	ds_read_b128 v[194:197], v160 offset:34816
	ds_read_b128 v[204:207], v160 offset:35840
	ds_read_b128 v[208:211], v160 offset:36864
	ds_read_b128 v[212:215], v160 offset:37888
	ds_read_b128 v[216:219], v160 offset:38912
	ds_read_b128 v[220:223], v160 offset:39936
	global_load_lds_dwordx4 v138, s[54:55]
	s_mov_b32 m0, s22
	s_nop 0
	global_load_lds_dwordx4 v140, s[54:55]
	s_waitcnt vmcnt(8)
	s_waitcnt lgkmcnt(0)
	s_setprio 1
	s_barrier
	v_mfma_f32_16x16x32_bf16 v[122:125], v[130:133], v[186:189], v[122:125]
	v_mfma_f32_16x16x32_bf16 v[126:129], v[148:151], v[186:189], v[126:129]
	v_mfma_f32_16x16x32_bf16 v[110:113], v[130:133], v[194:197], v[110:113]
	v_mfma_f32_16x16x32_bf16 v[106:109], v[148:151], v[194:197], v[106:109]
	v_mfma_f32_16x16x32_bf16 v[94:97], v[130:133], v[208:211], v[94:97]
	v_mfma_f32_16x16x32_bf16 v[90:93], v[148:151], v[208:211], v[90:93]
	v_mfma_f32_16x16x32_bf16 v[78:81], v[130:133], v[216:219], v[78:81]
	v_mfma_f32_16x16x32_bf16 v[74:77], v[148:151], v[216:219], v[74:77]
	v_mfma_f32_16x16x32_bf16 v[122:125], v[134:137], v[190:193], v[122:125]
	v_mfma_f32_16x16x32_bf16 v[126:129], v[152:155], v[190:193], v[126:129]
	v_mfma_f32_16x16x32_bf16 v[110:113], v[134:137], v[204:207], v[110:113]
	v_mfma_f32_16x16x32_bf16 v[106:109], v[152:155], v[204:207], v[106:109]
	v_mfma_f32_16x16x32_bf16 v[94:97], v[134:137], v[212:215], v[94:97]
	v_mfma_f32_16x16x32_bf16 v[90:93], v[152:155], v[212:215], v[90:93]
	v_mfma_f32_16x16x32_bf16 v[78:81], v[134:137], v[220:223], v[78:81]
	v_mfma_f32_16x16x32_bf16 v[74:77], v[152:155], v[220:223], v[74:77]
	v_mfma_f32_16x16x32_bf16 v[118:121], v[162:165], v[186:189], v[118:121]
	v_mfma_f32_16x16x32_bf16 v[114:117], v[170:173], v[186:189], v[114:117]
	v_mfma_f32_16x16x32_bf16 v[102:105], v[162:165], v[194:197], v[102:105]
	v_mfma_f32_16x16x32_bf16 v[98:101], v[170:173], v[194:197], v[98:101]
	v_mfma_f32_16x16x32_bf16 v[86:89], v[162:165], v[208:211], v[86:89]
	v_mfma_f32_16x16x32_bf16 v[82:85], v[170:173], v[208:211], v[82:85]
	v_mfma_f32_16x16x32_bf16 v[70:73], v[162:165], v[216:219], v[70:73]
	v_mfma_f32_16x16x32_bf16 v[66:69], v[170:173], v[216:219], v[66:69]
	v_mfma_f32_16x16x32_bf16 v[118:121], v[166:169], v[190:193], v[118:121]
	v_mfma_f32_16x16x32_bf16 v[114:117], v[182:185], v[190:193], v[114:117]
	v_mfma_f32_16x16x32_bf16 v[102:105], v[166:169], v[204:207], v[102:105]
	v_mfma_f32_16x16x32_bf16 v[98:101], v[182:185], v[204:207], v[98:101]
	v_mfma_f32_16x16x32_bf16 v[86:89], v[166:169], v[212:215], v[86:89]
	v_mfma_f32_16x16x32_bf16 v[82:85], v[182:185], v[212:215], v[82:85]
	v_mfma_f32_16x16x32_bf16 v[70:73], v[166:169], v[220:223], v[70:73]
	v_mfma_f32_16x16x32_bf16 v[66:69], v[182:185], v[220:223], v[66:69]
	s_setprio 0
	s_barrier
	s_add_i32 s54, s82, s2
	s_add_i32 vcc_hi, s81, -2
	s_cmp_eq_u32 s74, vcc_hi
	s_cselect_b32 s99, s47, s80
	s_cselect_b32 s98, s46, s79
	s_add_u32 s98, s98, s92
	s_addc_u32 s99, s99, s93
	s_mov_b32 m0, s54
	s_nop 0
	global_load_lds_dwordx4 v174, s[98:99]
	ds_read_b128 v[186:189], v160 offset:49152
	ds_read_b128 v[190:193], v160 offset:50176
	ds_read_b128 v[194:197], v160 offset:51200
	ds_read_b128 v[204:207], v160 offset:52224
	ds_read_b128 v[208:211], v160 offset:53248
	ds_read_b128 v[212:215], v160 offset:54272
	ds_read_b128 v[216:219], v160 offset:55296
	ds_read_b128 v[220:223], v160 offset:56320
	s_add_i32 m0, s54, 0x2000
	s_nop 0
	global_load_lds_dwordx4 v142, s[98:99]
	s_add_i32 s54, s83, s2
	s_add_u32 s98, s98, s48
	s_addc_u32 s99, s99, 0
	s_mov_b32 m0, s54
	s_nop 0
	global_load_lds_dwordx4 v174, s[98:99]
	s_add_i32 m0, s54, 0x2000
	s_nop 0
	global_load_lds_dwordx4 v142, s[98:99]
	s_add_u32 s98, s52, 0x80
	s_addc_u32 s99, s53, 0
	s_cmp_eq_u32 s74, vcc_hi
	s_cselect_b32 s99, s41, s99
	s_cselect_b32 s98, s40, s98
	s_add_u32 s98, s98, s92
	s_addc_u32 s99, s99, s93
	s_mov_b32 m0, s33
	s_nop 0
	global_load_lds_dwordx4 v138, s[98:99]
	s_mov_b32 m0, s35
	s_nop 0
	global_load_lds_dwordx4 v140, s[98:99]
	s_waitcnt vmcnt(8)
	s_waitcnt lgkmcnt(0)
	s_setprio 1
	s_barrier
	v_mfma_f32_16x16x32_bf16 v[62:65], v[130:133], v[186:189], v[62:65]
	v_mfma_f32_16x16x32_bf16 v[58:61], v[148:151], v[186:189], v[58:61]
	v_mfma_f32_16x16x32_bf16 v[46:49], v[130:133], v[194:197], v[46:49]
	v_mfma_f32_16x16x32_bf16 v[42:45], v[148:151], v[194:197], v[42:45]
	v_mfma_f32_16x16x32_bf16 v[30:33], v[130:133], v[208:211], v[30:33]
	v_mfma_f32_16x16x32_bf16 v[26:29], v[148:151], v[208:211], v[26:29]
	v_mfma_f32_16x16x32_bf16 v[14:17], v[130:133], v[216:219], v[14:17]
	v_mfma_f32_16x16x32_bf16 v[10:13], v[148:151], v[216:219], v[10:13]
	v_mfma_f32_16x16x32_bf16 v[62:65], v[134:137], v[190:193], v[62:65]
	v_mfma_f32_16x16x32_bf16 v[58:61], v[152:155], v[190:193], v[58:61]
	v_mfma_f32_16x16x32_bf16 v[46:49], v[134:137], v[204:207], v[46:49]
	v_mfma_f32_16x16x32_bf16 v[42:45], v[152:155], v[204:207], v[42:45]
	v_mfma_f32_16x16x32_bf16 v[30:33], v[134:137], v[212:215], v[30:33]
	v_mfma_f32_16x16x32_bf16 v[26:29], v[152:155], v[212:215], v[26:29]
	v_mfma_f32_16x16x32_bf16 v[14:17], v[134:137], v[220:223], v[14:17]
	v_mfma_f32_16x16x32_bf16 v[10:13], v[152:155], v[220:223], v[10:13]
	v_mfma_f32_16x16x32_bf16 v[54:57], v[162:165], v[186:189], v[54:57]
	v_mfma_f32_16x16x32_bf16 v[50:53], v[170:173], v[186:189], v[50:53]
	v_mfma_f32_16x16x32_bf16 v[38:41], v[162:165], v[194:197], v[38:41]
	v_mfma_f32_16x16x32_bf16 v[34:37], v[170:173], v[194:197], v[34:37]
	v_mfma_f32_16x16x32_bf16 v[22:25], v[162:165], v[208:211], v[22:25]
	v_mfma_f32_16x16x32_bf16 v[18:21], v[170:173], v[208:211], v[18:21]
	v_mfma_f32_16x16x32_bf16 v[6:9], v[162:165], v[216:219], v[6:9]
	v_mfma_f32_16x16x32_bf16 v[2:5], v[170:173], v[216:219], v[2:5]
	v_mfma_f32_16x16x32_bf16 v[54:57], v[166:169], v[190:193], v[54:57]
	v_mfma_f32_16x16x32_bf16 v[50:53], v[182:185], v[190:193], v[50:53]
	v_mfma_f32_16x16x32_bf16 v[38:41], v[166:169], v[204:207], v[38:41]
	v_mfma_f32_16x16x32_bf16 v[34:37], v[182:185], v[204:207], v[34:37]
	v_mfma_f32_16x16x32_bf16 v[22:25], v[166:169], v[212:215], v[22:25]
	v_mfma_f32_16x16x32_bf16 v[18:21], v[182:185], v[212:215], v[18:21]
	v_mfma_f32_16x16x32_bf16 v[6:9], v[166:169], v[220:223], v[6:9]
	v_mfma_f32_16x16x32_bf16 v[2:5], v[182:185], v[220:223], v[2:5]
	s_setprio 0
	s_barrier
	s_add_u32 s52, s52, 0x100
	s_addc_u32 s53, s53, 0
	s_add_u32 s79, s79, 0x100
	s_addc_u32 s80, s80, 0
	s_cmp_ge_u32 s81, s65
	s_mov_b32 s54, s81
	s_cbranch_scc1 .LBB0_346
; #define PG8_STAGE(bufoff, gbase, voff) do { _Pragma("unroll") for (int _i = 0; _i < 2; ++_i) \
;         __builtin_amdgcn_global_load_lds((const unsigned*)((const char*)(gbase) + (voff)[_i]), (PG8_LAS unsigned*)(lds + (bufoff) + ldsw + _i * 8192), 16, 0, 0); } while (0)
; #define PG8_LDA(dst, b, h) do { _Pragma("unroll") for (int m = 0; m < 4; ++m) _Pragma("unroll") for (int k = 0; k < 2; ++k) dst[m][k] = *(const PG8_LAS bf16x8*)(lds + PG8_SA(b, h) + aoff + m * 2048 + k * 1024); } while (0)
; #define PG8_LDB(dst, b, h) do { _Pragma("unroll") for (int n = 0; n < 2; ++n) _Pragma("unroll") for (int k = 0; k < 2; ++k) dst[n][k] = *(const PG8_LAS bf16x8*)(lds + PG8_SB(b, h) + boff + n * 2048 + k * 1024); } while (0)
; #define PG8_WAIT_V(n) asm volatile("s_waitcnt vmcnt(" #n ")" ::: "memory")
; #define PG8_WAIT_L(n) asm volatile("s_waitcnt lgkmcnt(" #n ")" ::: "memory")
; #define PG8_BAR __builtin_amdgcn_s_barrier()
; #define PG8_SCHED __builtin_amdgcn_sched_barrier(0)
; template <class Epi, class Sched, bool ALIGN_EPI = false, bool SP2 = false, bool F16 = false>
; __device__ __forceinline__ void gemm_phase(PG8_LAS unsigned char* lds, const Gemm g, const Sched& S, const Epi& E) {
;     ...
;             const bool last = (t == nt - 2);
;             const char* a1 = cA + (size_t)(t + 1) * kstep;
;             const char* a2 = last ? nA : cA + (size_t)(t + 2) * kstep; const char* b2 = last ? nB : cB + (size_t)(t + 2) * kstep;
;             const char* a3 = a2 + kstep; const char* b3 = b2 + kstep;
;             if (last && has_next) S.a_ready(nxt);
;             if constexpr (SP2) {
;             PG8_LDB(B0, 0, 0); PG8_LDB(B1, 0, 1); PG8_SCHED; PG8_LDA(At, 0, 0); PG8_STAGE(PG8_SA(1, 1), a1 + hstepA, voffA);
;             PG8_WAIT_V(8); PG8_WAIT_L(0); PG8_BAR; PG8_MMA(0, 0, At, B0); PG8_MMA(0, 1, At, B1); PG8_BAR; PG8_SCHED;
;             PG8_LDA(At, 0, 1); PG8_STAGE(PG8_SB(0, 0), b2, voffB); PG8_STAGE(PG8_SB(0, 1), b2 + hstepB, voffB); PG8_STAGE(PG8_SA(0, 0), a2, voffA);
;             PG8_WAIT_V(8); PG8_WAIT_L(0); PG8_BAR; PG8_MMA(1, 0, At, B0); PG8_MMA(1, 1, At, B1); PG8_BAR; PG8_SCHED;
.LBB0_345:
	s_add_i32 s81, s54, 2
	s_add_u32 s82, s52, 0x80
	s_addc_u32 s55, s53, 0
	s_add_i32 s94, 0, 0x10000
	s_cmp_eq_u32 s74, s54
	s_cselect_b32 s55, s41, s55
	s_cselect_b32 s54, s40, s82
	s_cselect_b32 s83, s47, s80
	s_cselect_b32 s82, s46, s79
	s_add_i32 s95, 0, 0x14000
	ds_read_b128 v[130:133], v139
	ds_read_b128 v[134:137], v139 offset:1024
	ds_read_b128 v[148:151], v139 offset:2048
	ds_read_b128 v[152:155], v139 offset:3072
	ds_read_b128 v[162:165], v141
	ds_read_b128 v[166:169], v141 offset:1024
	ds_read_b128 v[170:173], v141 offset:2048
	ds_read_b128 v[182:185], v141 offset:3072
	s_add_i32 m0, s3, 0xc000
	ds_read_b128 v[186:189], v160
	ds_read_b128 v[190:193], v160 offset:1024
	ds_read_b128 v[194:197], v160 offset:2048
	ds_read_b128 v[204:207], v160 offset:3072
	ds_read_b128 v[208:211], v160 offset:4096
	ds_read_b128 v[212:215], v160 offset:5120
	ds_read_b128 v[216:219], v160 offset:6144
	ds_read_b128 v[220:223], v160 offset:7168
	global_load_lds_dwordx4 v144, s[52:53]
	s_add_i32 m0, s3, 0xe000
	s_nop 0
	global_load_lds_dwordx4 v146, s[52:53]
	s_waitcnt vmcnt(8)
	s_waitcnt lgkmcnt(0)
	s_setprio 1
	s_barrier
	v_mfma_f32_16x16x32_bf16 v[122:125], v[130:133], v[186:189], v[122:125]
	v_mfma_f32_16x16x32_bf16 v[126:129], v[148:151], v[186:189], v[126:129]
	v_mfma_f32_16x16x32_bf16 v[110:113], v[130:133], v[194:197], v[110:113]
	v_mfma_f32_16x16x32_bf16 v[106:109], v[148:151], v[194:197], v[106:109]
	v_mfma_f32_16x16x32_bf16 v[94:97], v[130:133], v[208:211], v[94:97]
	v_mfma_f32_16x16x32_bf16 v[90:93], v[148:151], v[208:211], v[90:93]
	v_mfma_f32_16x16x32_bf16 v[78:81], v[130:133], v[216:219], v[78:81]
	v_mfma_f32_16x16x32_bf16 v[74:77], v[148:151], v[216:219], v[74:77]
	v_mfma_f32_16x16x32_bf16 v[122:125], v[134:137], v[190:193], v[122:125]
	v_mfma_f32_16x16x32_bf16 v[126:129], v[152:155], v[190:193], v[126:129]
	v_mfma_f32_16x16x32_bf16 v[110:113], v[134:137], v[204:207], v[110:113]
	v_mfma_f32_16x16x32_bf16 v[106:109], v[152:155], v[204:207], v[106:109]
	v_mfma_f32_16x16x32_bf16 v[94:97], v[134:137], v[212:215], v[94:97]
	v_mfma_f32_16x16x32_bf16 v[90:93], v[152:155], v[212:215], v[90:93]
	v_mfma_f32_16x16x32_bf16 v[78:81], v[134:137], v[220:223], v[78:81]
	v_mfma_f32_16x16x32_bf16 v[74:77], v[152:155], v[220:223], v[74:77]
	v_mfma_f32_16x16x32_bf16 v[118:121], v[162:165], v[186:189], v[118:121]
	v_mfma_f32_16x16x32_bf16 v[114:117], v[170:173], v[186:189], v[114:117]
	v_mfma_f32_16x16x32_bf16 v[102:105], v[162:165], v[194:197], v[102:105]
	v_mfma_f32_16x16x32_bf16 v[98:101], v[170:173], v[194:197], v[98:101]
	v_mfma_f32_16x16x32_bf16 v[86:89], v[162:165], v[208:211], v[86:89]
	v_mfma_f32_16x16x32_bf16 v[82:85], v[170:173], v[208:211], v[82:85]
	v_mfma_f32_16x16x32_bf16 v[70:73], v[162:165], v[216:219], v[70:73]
	v_mfma_f32_16x16x32_bf16 v[66:69], v[170:173], v[216:219], v[66:69]
	v_mfma_f32_16x16x32_bf16 v[118:121], v[166:169], v[190:193], v[118:121]
	v_mfma_f32_16x16x32_bf16 v[114:117], v[182:185], v[190:193], v[114:117]
	v_mfma_f32_16x16x32_bf16 v[102:105], v[166:169], v[204:207], v[102:105]
	v_mfma_f32_16x16x32_bf16 v[98:101], v[182:185], v[204:207], v[98:101]
	v_mfma_f32_16x16x32_bf16 v[86:89], v[166:169], v[212:215], v[86:89]
	v_mfma_f32_16x16x32_bf16 v[82:85], v[182:185], v[212:215], v[82:85]
	v_mfma_f32_16x16x32_bf16 v[70:73], v[166:169], v[220:223], v[70:73]
	v_mfma_f32_16x16x32_bf16 v[66:69], v[182:185], v[220:223], v[66:69]
	s_setprio 0
	s_barrier
	s_add_i32 s94, s94, s2
	s_mov_b32 m0, s94
	s_nop 0
	global_load_lds_dwordx4 v174, s[82:83]
	ds_read_b128 v[186:189], v160 offset:16384
	ds_read_b128 v[190:193], v160 offset:17408
	ds_read_b128 v[194:197], v160 offset:18432
	ds_read_b128 v[204:207], v160 offset:19456
	ds_read_b128 v[208:211], v160 offset:20480
	ds_read_b128 v[212:215], v160 offset:21504
	ds_read_b128 v[216:219], v160 offset:22528
	ds_read_b128 v[220:223], v160 offset:23552
	s_add_i32 m0, s94, 0x2000
	s_nop 0
	global_load_lds_dwordx4 v142, s[82:83]
	s_add_i32 s94, s95, s2
	s_add_u32 s82, s82, s48
	s_addc_u32 s83, s83, 0
	s_mov_b32 m0, s94
	s_nop 0
	global_load_lds_dwordx4 v174, s[82:83]
	s_add_i32 m0, s94, 0x2000
	s_nop 0
	global_load_lds_dwordx4 v142, s[82:83]
	s_mov_b32 m0, s3
	s_nop 0
	global_load_lds_dwordx4 v138, s[54:55]
	s_mov_b32 m0, s12
	s_nop 0
	global_load_lds_dwordx4 v140, s[54:55]
	s_waitcnt vmcnt(8)
	s_waitcnt lgkmcnt(0)
	s_setprio 1
	s_barrier
	v_mfma_f32_16x16x32_bf16 v[62:65], v[130:133], v[186:189], v[62:65]
	v_mfma_f32_16x16x32_bf16 v[58:61], v[148:151], v[186:189], v[58:61]
	v_mfma_f32_16x16x32_bf16 v[46:49], v[130:133], v[194:197], v[46:49]
	v_mfma_f32_16x16x32_bf16 v[42:45], v[148:151], v[194:197], v[42:45]
	v_mfma_f32_16x16x32_bf16 v[30:33], v[130:133], v[208:211], v[30:33]
	v_mfma_f32_16x16x32_bf16 v[26:29], v[148:151], v[208:211], v[26:29]
	v_mfma_f32_16x16x32_bf16 v[14:17], v[130:133], v[216:219], v[14:17]
	v_mfma_f32_16x16x32_bf16 v[10:13], v[148:151], v[216:219], v[10:13]
	v_mfma_f32_16x16x32_bf16 v[62:65], v[134:137], v[190:193], v[62:65]
	v_mfma_f32_16x16x32_bf16 v[58:61], v[152:155], v[190:193], v[58:61]
	v_mfma_f32_16x16x32_bf16 v[46:49], v[134:137], v[204:207], v[46:49]
	v_mfma_f32_16x16x32_bf16 v[42:45], v[152:155], v[204:207], v[42:45]
	v_mfma_f32_16x16x32_bf16 v[30:33], v[134:137], v[212:215], v[30:33]
	v_mfma_f32_16x16x32_bf16 v[26:29], v[152:155], v[212:215], v[26:29]
	v_mfma_f32_16x16x32_bf16 v[14:17], v[134:137], v[220:223], v[14:17]
	v_mfma_f32_16x16x32_bf16 v[10:13], v[152:155], v[220:223], v[10:13]
	v_mfma_f32_16x16x32_bf16 v[54:57], v[162:165], v[186:189], v[54:57]
	v_mfma_f32_16x16x32_bf16 v[50:53], v[170:173], v[186:189], v[50:53]
	v_mfma_f32_16x16x32_bf16 v[38:41], v[162:165], v[194:197], v[38:41]
	v_mfma_f32_16x16x32_bf16 v[34:37], v[170:173], v[194:197], v[34:37]
	v_mfma_f32_16x16x32_bf16 v[22:25], v[162:165], v[208:211], v[22:25]
	v_mfma_f32_16x16x32_bf16 v[18:21], v[170:173], v[208:211], v[18:21]
	v_mfma_f32_16x16x32_bf16 v[6:9], v[162:165], v[216:219], v[6:9]
	v_mfma_f32_16x16x32_bf16 v[2:5], v[170:173], v[216:219], v[2:5]
	v_mfma_f32_16x16x32_bf16 v[54:57], v[166:169], v[190:193], v[54:57]
	v_mfma_f32_16x16x32_bf16 v[50:53], v[182:185], v[190:193], v[50:53]
	v_mfma_f32_16x16x32_bf16 v[38:41], v[166:169], v[204:207], v[38:41]
	v_mfma_f32_16x16x32_bf16 v[34:37], v[182:185], v[204:207], v[34:37]
	v_mfma_f32_16x16x32_bf16 v[22:25], v[166:169], v[212:215], v[22:25]
	v_mfma_f32_16x16x32_bf16 v[18:21], v[182:185], v[212:215], v[18:21]
	v_mfma_f32_16x16x32_bf16 v[6:9], v[166:169], v[220:223], v[6:9]
	v_mfma_f32_16x16x32_bf16 v[2:5], v[182:185], v[220:223], v[2:5]
	s_setprio 0
	s_barrier
; #define PG8_STAGE(bufoff, gbase, voff) do { _Pragma("unroll") for (int _i = 0; _i < 2; ++_i) \
;         __builtin_amdgcn_global_load_lds((const unsigned*)((const char*)(gbase) + (voff)[_i]), (PG8_LAS unsigned*)(lds + (bufoff) + ldsw + _i * 8192), 16, 0, 0); } while (0)
; #define PG8_LDA(dst, b, h) do { _Pragma("unroll") for (int m = 0; m < 4; ++m) _Pragma("unroll") for (int k = 0; k < 2; ++k) dst[m][k] = *(const PG8_LAS bf16x8*)(lds + PG8_SA(b, h) + aoff + m * 2048 + k * 1024); } while (0)
; #define PG8_LDB(dst, b, h) do { _Pragma("unroll") for (int n = 0; n < 2; ++n) _Pragma("unroll") for (int k = 0; k < 2; ++k) dst[n][k] = *(const PG8_LAS bf16x8*)(lds + PG8_SB(b, h) + boff + n * 2048 + k * 1024); } while (0)
; #define PG8_WAIT_V(n) asm volatile("s_waitcnt vmcnt(" #n ")" ::: "memory")
; #define PG8_WAIT_L(n) asm volatile("s_waitcnt lgkmcnt(" #n ")" ::: "memory")
; #define PG8_BAR __builtin_amdgcn_s_barrier()
; #define PG8_SCHED __builtin_amdgcn_sched_barrier(0)
; template <class Epi, class Sched, bool ALIGN_EPI = false, bool SP2 = false, bool F16 = false>
; __device__ __forceinline__ void gemm_phase(PG8_LAS unsigned char* lds, const Gemm g, const Sched& S, const Epi& E) {
;     ...
;         for (int t = 0; t < nt; t += 2) {
;             const bool last = (t == nt - 2);
;             const char* a1 = cA + (size_t)(t + 1) * kstep;
;             const char* a2 = last ? nA : cA + (size_t)(t + 2) * kstep; const char* b2 = last ? nB : cB + (size_t)(t + 2) * kstep;
;             const char* a3 = a2 + kstep; const char* b3 = b2 + kstep;
;     ...
;             PG8_LDB(B0, 1, 0); PG8_LDB(B1, 1, 1); PG8_SCHED; PG8_LDA(At, 1, 0); PG8_STAGE(PG8_SA(0, 1), a2 + hstepA, voffA);
;             PG8_WAIT_V(8); PG8_WAIT_L(0); PG8_BAR; PG8_MMA(0, 0, At, B0); PG8_MMA(0, 1, At, B1); PG8_BAR; PG8_SCHED;
;             PG8_LDA(At, 1, 1); PG8_STAGE(PG8_SB(1, 0), b3, voffB); PG8_STAGE(PG8_SB(1, 1), b3 + hstepB, voffB); PG8_STAGE(PG8_SA(1, 0), a3, voffA);
;             PG8_WAIT_V(8); PG8_WAIT_L(0); PG8_BAR; PG8_MMA(1, 0, At, B0); PG8_MMA(1, 1, At, B1); PG8_BAR; PG8_SCHED;
	s_add_i32 s82, 0, 0x18000
	s_add_i32 s83, 0, 0x1c000
	ds_read_b128 v[130:133], v143
	ds_read_b128 v[134:137], v143 offset:1024
	ds_read_b128 v[148:151], v143 offset:2048
	ds_read_b128 v[152:155], v143 offset:3072
	ds_read_b128 v[162:165], v157
	ds_read_b128 v[166:169], v157 offset:1024
	ds_read_b128 v[170:173], v157 offset:2048
	ds_read_b128 v[182:185], v157 offset:3072
	s_add_u32 s54, s54, s8
	s_addc_u32 s55, s55, 0
	s_mov_b32 m0, s13
	ds_read_b128 v[186:189], v160 offset:32768
	ds_read_b128 v[190:193], v160 offset:33792
	ds_read_b128 v[194:197], v160 offset:34816
	ds_read_b128 v[204:207], v160 offset:35840
	ds_read_b128 v[208:211], v160 offset:36864
	ds_read_b128 v[212:215], v160 offset:37888
	ds_read_b128 v[216:219], v160 offset:38912
	ds_read_b128 v[220:223], v160 offset:39936
	global_load_lds_dwordx4 v138, s[54:55]
	s_mov_b32 m0, s22
	s_nop 0
	global_load_lds_dwordx4 v140, s[54:55]
	s_waitcnt vmcnt(8)
	s_waitcnt lgkmcnt(0)
	s_setprio 1
	s_barrier
	v_mfma_f32_16x16x32_bf16 v[122:125], v[130:133], v[186:189], v[122:125]
	v_mfma_f32_16x16x32_bf16 v[126:129], v[148:151], v[186:189], v[126:129]
	v_mfma_f32_16x16x32_bf16 v[110:113], v[130:133], v[194:197], v[110:113]
	v_mfma_f32_16x16x32_bf16 v[106:109], v[148:151], v[194:197], v[106:109]
	v_mfma_f32_16x16x32_bf16 v[94:97], v[130:133], v[208:211], v[94:97]
	v_mfma_f32_16x16x32_bf16 v[90:93], v[148:151], v[208:211], v[90:93]
	v_mfma_f32_16x16x32_bf16 v[78:81], v[130:133], v[216:219], v[78:81]
	v_mfma_f32_16x16x32_bf16 v[74:77], v[148:151], v[216:219], v[74:77]
	v_mfma_f32_16x16x32_bf16 v[122:125], v[134:137], v[190:193], v[122:125]
	v_mfma_f32_16x16x32_bf16 v[126:129], v[152:155], v[190:193], v[126:129]
	v_mfma_f32_16x16x32_bf16 v[110:113], v[134:137], v[204:207], v[110:113]
	v_mfma_f32_16x16x32_bf16 v[106:109], v[152:155], v[204:207], v[106:109]
	v_mfma_f32_16x16x32_bf16 v[94:97], v[134:137], v[212:215], v[94:97]
	v_mfma_f32_16x16x32_bf16 v[90:93], v[152:155], v[212:215], v[90:93]
	v_mfma_f32_16x16x32_bf16 v[78:81], v[134:137], v[220:223], v[78:81]
	v_mfma_f32_16x16x32_bf16 v[74:77], v[152:155], v[220:223], v[74:77]
	v_mfma_f32_16x16x32_bf16 v[118:121], v[162:165], v[186:189], v[118:121]
	v_mfma_f32_16x16x32_bf16 v[114:117], v[170:173], v[186:189], v[114:117]
	v_mfma_f32_16x16x32_bf16 v[102:105], v[162:165], v[194:197], v[102:105]
	v_mfma_f32_16x16x32_bf16 v[98:101], v[170:173], v[194:197], v[98:101]
	v_mfma_f32_16x16x32_bf16 v[86:89], v[162:165], v[208:211], v[86:89]
	v_mfma_f32_16x16x32_bf16 v[82:85], v[170:173], v[208:211], v[82:85]
	v_mfma_f32_16x16x32_bf16 v[70:73], v[162:165], v[216:219], v[70:73]
	v_mfma_f32_16x16x32_bf16 v[66:69], v[170:173], v[216:219], v[66:69]
	v_mfma_f32_16x16x32_bf16 v[118:121], v[166:169], v[190:193], v[118:121]
	v_mfma_f32_16x16x32_bf16 v[114:117], v[182:185], v[190:193], v[114:117]
	v_mfma_f32_16x16x32_bf16 v[102:105], v[166:169], v[204:207], v[102:105]
	v_mfma_f32_16x16x32_bf16 v[98:101], v[182:185], v[204:207], v[98:101]
	v_mfma_f32_16x16x32_bf16 v[86:89], v[166:169], v[212:215], v[86:89]
	v_mfma_f32_16x16x32_bf16 v[82:85], v[182:185], v[212:215], v[82:85]
	v_mfma_f32_16x16x32_bf16 v[70:73], v[166:169], v[220:223], v[70:73]
	v_mfma_f32_16x16x32_bf16 v[66:69], v[182:185], v[220:223], v[66:69]
	s_setprio 0
	s_barrier
	s_add_i32 s54, s82, s2
	s_add_i32 vcc_hi, s81, -2
	s_cmp_eq_u32 s74, vcc_hi
	s_cselect_b32 s99, s47, s80
	s_cselect_b32 s98, s46, s79
	s_add_u32 s98, s98, s92
	s_addc_u32 s99, s99, s93
	s_mov_b32 m0, s54
	s_nop 0
	global_load_lds_dwordx4 v174, s[98:99]
	ds_read_b128 v[186:189], v160 offset:49152
	ds_read_b128 v[190:193], v160 offset:50176
	ds_read_b128 v[194:197], v160 offset:51200
	ds_read_b128 v[204:207], v160 offset:52224
	ds_read_b128 v[208:211], v160 offset:53248
	ds_read_b128 v[212:215], v160 offset:54272
	ds_read_b128 v[216:219], v160 offset:55296
	ds_read_b128 v[220:223], v160 offset:56320
	s_add_i32 m0, s54, 0x2000
	s_nop 0
	global_load_lds_dwordx4 v142, s[98:99]
	s_add_i32 s54, s83, s2
	s_add_u32 s98, s98, s48
	s_addc_u32 s99, s99, 0
	s_mov_b32 m0, s54
	s_nop 0
	global_load_lds_dwordx4 v174, s[98:99]
	s_add_i32 m0, s54, 0x2000
	s_nop 0
	global_load_lds_dwordx4 v142, s[98:99]
	s_add_u32 s98, s52, 0x80
	s_addc_u32 s99, s53, 0
	s_cmp_eq_u32 s74, vcc_hi
	s_cselect_b32 s99, s41, s99
	s_cselect_b32 s98, s40, s98
	s_add_u32 s98, s98, s92
	s_addc_u32 s99, s99, s93
	s_mov_b32 m0, s33
	s_nop 0
	global_load_lds_dwordx4 v138, s[98:99]
	s_mov_b32 m0, s35
	s_nop 0
	global_load_lds_dwordx4 v140, s[98:99]
	s_waitcnt vmcnt(8)
	s_waitcnt lgkmcnt(0)
	s_setprio 1
	s_barrier
	v_mfma_f32_16x16x32_bf16 v[62:65], v[130:133], v[186:189], v[62:65]
	v_mfma_f32_16x16x32_bf16 v[58:61], v[148:151], v[186:189], v[58:61]
	v_mfma_f32_16x16x32_bf16 v[46:49], v[130:133], v[194:197], v[46:49]
	v_mfma_f32_16x16x32_bf16 v[42:45], v[148:151], v[194:197], v[42:45]
	v_mfma_f32_16x16x32_bf16 v[30:33], v[130:133], v[208:211], v[30:33]
	v_mfma_f32_16x16x32_bf16 v[26:29], v[148:151], v[208:211], v[26:29]
	v_mfma_f32_16x16x32_bf16 v[14:17], v[130:133], v[216:219], v[14:17]
	v_mfma_f32_16x16x32_bf16 v[10:13], v[148:151], v[216:219], v[10:13]
	v_mfma_f32_16x16x32_bf16 v[62:65], v[134:137], v[190:193], v[62:65]
	v_mfma_f32_16x16x32_bf16 v[58:61], v[152:155], v[190:193], v[58:61]
	v_mfma_f32_16x16x32_bf16 v[46:49], v[134:137], v[204:207], v[46:49]
	v_mfma_f32_16x16x32_bf16 v[42:45], v[152:155], v[204:207], v[42:45]
	v_mfma_f32_16x16x32_bf16 v[30:33], v[134:137], v[212:215], v[30:33]
	v_mfma_f32_16x16x32_bf16 v[26:29], v[152:155], v[212:215], v[26:29]
	v_mfma_f32_16x16x32_bf16 v[14:17], v[134:137], v[220:223], v[14:17]
	v_mfma_f32_16x16x32_bf16 v[10:13], v[152:155], v[220:223], v[10:13]
	v_mfma_f32_16x16x32_bf16 v[54:57], v[162:165], v[186:189], v[54:57]
	v_mfma_f32_16x16x32_bf16 v[50:53], v[170:173], v[186:189], v[50:53]
	v_mfma_f32_16x16x32_bf16 v[38:41], v[162:165], v[194:197], v[38:41]
	v_mfma_f32_16x16x32_bf16 v[34:37], v[170:173], v[194:197], v[34:37]
	v_mfma_f32_16x16x32_bf16 v[22:25], v[162:165], v[208:211], v[22:25]
	v_mfma_f32_16x16x32_bf16 v[18:21], v[170:173], v[208:211], v[18:21]
	v_mfma_f32_16x16x32_bf16 v[6:9], v[162:165], v[216:219], v[6:9]
	v_mfma_f32_16x16x32_bf16 v[2:5], v[170:173], v[216:219], v[2:5]
	v_mfma_f32_16x16x32_bf16 v[54:57], v[166:169], v[190:193], v[54:57]
	v_mfma_f32_16x16x32_bf16 v[50:53], v[182:185], v[190:193], v[50:53]
	v_mfma_f32_16x16x32_bf16 v[38:41], v[166:169], v[204:207], v[38:41]
	v_mfma_f32_16x16x32_bf16 v[34:37], v[182:185], v[204:207], v[34:37]
	v_mfma_f32_16x16x32_bf16 v[22:25], v[166:169], v[212:215], v[22:25]
	v_mfma_f32_16x16x32_bf16 v[18:21], v[182:185], v[212:215], v[18:21]
	v_mfma_f32_16x16x32_bf16 v[6:9], v[166:169], v[220:223], v[6:9]
	v_mfma_f32_16x16x32_bf16 v[2:5], v[182:185], v[220:223], v[2:5]
	s_setprio 0
	s_barrier
	s_add_u32 s52, s52, 0x100
	s_addc_u32 s53, s53, 0
	s_add_u32 s79, s79, 0x100
	s_addc_u32 s80, s80, 0
	s_cmp_ge_u32 s81, s65
	s_mov_b32 s54, s81
	s_cbranch_scc0 .LBB0_345

; #define PG8_STAGE(bufoff, gbase, voff) do { _Pragma("unroll") for (int _i = 0; _i < 2; ++_i) \
;         __builtin_amdgcn_global_load_lds((const unsigned*)((const char*)(gbase) + (voff)[_i]), (PG8_LAS unsigned*)(lds + (bufoff) + ldsw + _i * 8192), 16, 0, 0); } while (0)
; #define PG8_LDA(dst, b, h) do { _Pragma("unroll") for (int m = 0; m < 4; ++m) _Pragma("unroll") for (int k = 0; k < 2; ++k) dst[m][k] = *(const PG8_LAS bf16x8*)(lds + PG8_SA(b, h) + aoff + m * 2048 + k * 1024); } while (0)
; #define PG8_LDB(dst, b, h) do { _Pragma("unroll") for (int n = 0; n < 2; ++n) _Pragma("unroll") for (int k = 0; k < 2; ++k) dst[n][k] = *(const PG8_LAS bf16x8*)(lds + PG8_SB(b, h) + boff + n * 2048 + k * 1024); } while (0)
; #define PG8_WAIT_V(n) asm volatile("s_waitcnt vmcnt(" #n ")" ::: "memory")
; #define PG8_WAIT_L(n) asm volatile("s_waitcnt lgkmcnt(" #n ")" ::: "memory")
; #define PG8_BAR __builtin_amdgcn_s_barrier()
; #define PG8_SCHED __builtin_amdgcn_sched_barrier(0)
; template <class Epi, class Sched, bool ALIGN_EPI = false, bool SP2 = false, bool F16 = false>
; __device__ __forceinline__ void gemm_phase(PG8_LAS unsigned char* lds, const Gemm g, const Sched& S, const Epi& E) {
;     ...
;         for (int t = 0; t < nt; t += 2) {
;             const bool last = (t == nt - 2);
;             const char* a1 = cA + (size_t)(t + 1) * kstep;
;             const char* a2 = last ? nA : cA + (size_t)(t + 2) * kstep; const char* b2 = last ? nB : cB + (size_t)(t + 2) * kstep;
;             const char* a3 = a2 + kstep; const char* b3 = b2 + kstep;
;             if (last && has_next) S.a_ready(nxt);
;             if constexpr (SP2) {
;             PG8_LDB(B0, 0, 0); PG8_LDB(B1, 0, 1); PG8_SCHED; PG8_LDA(At, 0, 0); PG8_STAGE(PG8_SA(1, 1), a1 + hstepA, voffA);
;             PG8_WAIT_V(8); PG8_WAIT_L(0); PG8_BAR; PG8_MMA(0, 0, At, B0); PG8_MMA(0, 1, At, B1); PG8_BAR; PG8_SCHED;
;             PG8_LDA(At, 0, 1); PG8_STAGE(PG8_SB(0, 0), b2, voffB); PG8_STAGE(PG8_SB(0, 1), b2 + hstepB, voffB); PG8_STAGE(PG8_SA(0, 0), a2, voffA);
;             PG8_WAIT_V(8); PG8_WAIT_L(0); PG8_BAR; PG8_MMA(1, 0, At, B0); PG8_MMA(1, 1, At, B1); PG8_BAR; PG8_SCHED;
.Lpk_bf:
	s_add_i32 s78, s72, 2
	s_add_u32 s79, s46, 0x80
	s_addc_u32 s73, s47, 0
	s_add_i32 vcc_lo, 0, 0x10000
	s_cmp_eq_u32 s74, s72
	s_cselect_b32 s73, s55, s73
	s_cselect_b32 s72, s54, s79
	s_cselect_b32 s95, s53, s24
	s_cselect_b32 s94, s52, s13
	s_add_i32 s79, 0, 0x14000
	ds_read_b128 v[130:133], v155
	ds_read_b128 v[134:137], v155 offset:1024
	ds_read_b128 v[138:141], v155 offset:2048
	ds_read_b128 v[142:145], v155 offset:3072
	ds_read_b128 v[146:149], v157
	ds_read_b128 v[150:153], v157 offset:1024
	ds_read_b128 v[182:185], v157 offset:2048
	ds_read_b128 v[186:189], v157 offset:3072
	s_add_i32 m0, s36, 0xc000
	ds_read_b128 v[190:193], v204
	ds_read_b128 v[194:197], v204 offset:1024
	ds_read_b128 v[206:209], v204 offset:2048
	ds_read_b128 v[210:213], v204 offset:3072
	ds_read_b128 v[214:217], v204 offset:4096
	ds_read_b128 v[218:221], v204 offset:5120
	ds_read_b128 v[222:225], v204 offset:6144
	ds_read_b128 v[226:229], v204 offset:7168
	global_load_lds_dwordx4 v168, s[46:47]
	s_add_i32 m0, s36, 0xe000
	s_nop 0
	global_load_lds_dwordx4 v170, s[46:47]
	s_waitcnt vmcnt(8)
	s_waitcnt lgkmcnt(0)
	s_setprio 1
	s_barrier
	v_mfma_f32_16x16x32_bf16 v[122:125], v[130:133], v[190:193], 0
	v_mfma_f32_16x16x32_bf16 v[126:129], v[138:141], v[190:193], 0
	v_mfma_f32_16x16x32_bf16 v[110:113], v[130:133], v[206:209], 0
	v_mfma_f32_16x16x32_bf16 v[106:109], v[138:141], v[206:209], 0
	v_mfma_f32_16x16x32_bf16 v[94:97], v[130:133], v[214:217], 0
	v_mfma_f32_16x16x32_bf16 v[90:93], v[138:141], v[214:217], 0
	v_mfma_f32_16x16x32_bf16 v[78:81], v[130:133], v[222:225], 0
	v_mfma_f32_16x16x32_bf16 v[74:77], v[138:141], v[222:225], 0
	v_mfma_f32_16x16x32_bf16 v[122:125], v[134:137], v[194:197], v[122:125]
	v_mfma_f32_16x16x32_bf16 v[126:129], v[142:145], v[194:197], v[126:129]
	v_mfma_f32_16x16x32_bf16 v[110:113], v[134:137], v[210:213], v[110:113]
	v_mfma_f32_16x16x32_bf16 v[106:109], v[142:145], v[210:213], v[106:109]
	v_mfma_f32_16x16x32_bf16 v[94:97], v[134:137], v[218:221], v[94:97]
	v_mfma_f32_16x16x32_bf16 v[90:93], v[142:145], v[218:221], v[90:93]
	v_mfma_f32_16x16x32_bf16 v[78:81], v[134:137], v[226:229], v[78:81]
	v_mfma_f32_16x16x32_bf16 v[74:77], v[142:145], v[226:229], v[74:77]
	v_mfma_f32_16x16x32_bf16 v[118:121], v[146:149], v[190:193], 0
	v_mfma_f32_16x16x32_bf16 v[114:117], v[182:185], v[190:193], 0
	v_mfma_f32_16x16x32_bf16 v[102:105], v[146:149], v[206:209], 0
	v_mfma_f32_16x16x32_bf16 v[98:101], v[182:185], v[206:209], 0
	v_mfma_f32_16x16x32_bf16 v[86:89], v[146:149], v[214:217], 0
	v_mfma_f32_16x16x32_bf16 v[82:85], v[182:185], v[214:217], 0
	v_mfma_f32_16x16x32_bf16 v[70:73], v[146:149], v[222:225], 0
	v_mfma_f32_16x16x32_bf16 v[66:69], v[182:185], v[222:225], 0
	v_mfma_f32_16x16x32_bf16 v[118:121], v[150:153], v[194:197], v[118:121]
	v_mfma_f32_16x16x32_bf16 v[114:117], v[186:189], v[194:197], v[114:117]
	v_mfma_f32_16x16x32_bf16 v[102:105], v[150:153], v[210:213], v[102:105]
	v_mfma_f32_16x16x32_bf16 v[98:101], v[186:189], v[210:213], v[98:101]
	v_mfma_f32_16x16x32_bf16 v[86:89], v[150:153], v[218:221], v[86:89]
	v_mfma_f32_16x16x32_bf16 v[82:85], v[186:189], v[218:221], v[82:85]
	v_mfma_f32_16x16x32_bf16 v[70:73], v[150:153], v[226:229], v[70:73]
	v_mfma_f32_16x16x32_bf16 v[66:69], v[186:189], v[226:229], v[66:69]
	s_setprio 0
	s_barrier
	s_add_i32 vcc_lo, vcc_lo, s75
	s_mov_b32 m0, vcc_lo
	s_nop 0
	global_load_lds_dwordx4 v156, s[94:95]
	ds_read_b128 v[190:193], v204 offset:16384
	ds_read_b128 v[194:197], v204 offset:17408
	ds_read_b128 v[206:209], v204 offset:18432
	ds_read_b128 v[210:213], v204 offset:19456
	ds_read_b128 v[214:217], v204 offset:20480
	ds_read_b128 v[218:221], v204 offset:21504
	ds_read_b128 v[222:225], v204 offset:22528
	ds_read_b128 v[226:229], v204 offset:23552
	s_add_i32 m0, vcc_lo, 0x2000
	s_nop 0
	global_load_lds_dwordx4 v160, s[94:95]
	s_add_i32 s79, s79, s75
	s_add_u32 s94, s94, s48
	s_addc_u32 s95, s95, 0
	s_mov_b32 m0, s79
	s_nop 0
	global_load_lds_dwordx4 v156, s[94:95]
	s_add_i32 m0, s79, 0x2000
	s_nop 0
	global_load_lds_dwordx4 v160, s[94:95]
	s_mov_b32 m0, s36
	s_nop 0
	global_load_lds_dwordx4 v154, s[72:73]
	s_mov_b32 m0, s37
	s_nop 0
	global_load_lds_dwordx4 v158, s[72:73]
	s_waitcnt vmcnt(8)
	s_waitcnt lgkmcnt(0)
	s_setprio 1
	s_barrier
	v_mfma_f32_16x16x32_bf16 v[62:65], v[130:133], v[190:193], 0
	v_mfma_f32_16x16x32_bf16 v[58:61], v[138:141], v[190:193], 0
	v_mfma_f32_16x16x32_bf16 v[46:49], v[130:133], v[206:209], 0
	v_mfma_f32_16x16x32_bf16 v[42:45], v[138:141], v[206:209], 0
	v_mfma_f32_16x16x32_bf16 v[30:33], v[130:133], v[214:217], 0
	v_mfma_f32_16x16x32_bf16 v[26:29], v[138:141], v[214:217], 0
	v_mfma_f32_16x16x32_bf16 v[14:17], v[130:133], v[222:225], 0
	v_mfma_f32_16x16x32_bf16 v[10:13], v[138:141], v[222:225], 0
	v_mfma_f32_16x16x32_bf16 v[62:65], v[134:137], v[194:197], v[62:65]
	v_mfma_f32_16x16x32_bf16 v[58:61], v[142:145], v[194:197], v[58:61]
	v_mfma_f32_16x16x32_bf16 v[46:49], v[134:137], v[210:213], v[46:49]
	v_mfma_f32_16x16x32_bf16 v[42:45], v[142:145], v[210:213], v[42:45]
	v_mfma_f32_16x16x32_bf16 v[30:33], v[134:137], v[218:221], v[30:33]
	v_mfma_f32_16x16x32_bf16 v[26:29], v[142:145], v[218:221], v[26:29]
	v_mfma_f32_16x16x32_bf16 v[14:17], v[134:137], v[226:229], v[14:17]
	v_mfma_f32_16x16x32_bf16 v[10:13], v[142:145], v[226:229], v[10:13]
	v_mfma_f32_16x16x32_bf16 v[54:57], v[146:149], v[190:193], 0
	v_mfma_f32_16x16x32_bf16 v[50:53], v[182:185], v[190:193], 0
	v_mfma_f32_16x16x32_bf16 v[38:41], v[146:149], v[206:209], 0
	v_mfma_f32_16x16x32_bf16 v[34:37], v[182:185], v[206:209], 0
	v_mfma_f32_16x16x32_bf16 v[22:25], v[146:149], v[214:217], 0
	v_mfma_f32_16x16x32_bf16 v[18:21], v[182:185], v[214:217], 0
	v_mfma_f32_16x16x32_bf16 v[6:9], v[146:149], v[222:225], 0
	v_mfma_f32_16x16x32_bf16 v[2:5], v[182:185], v[222:225], 0
	v_mfma_f32_16x16x32_bf16 v[54:57], v[150:153], v[194:197], v[54:57]
	v_mfma_f32_16x16x32_bf16 v[50:53], v[186:189], v[194:197], v[50:53]
	v_mfma_f32_16x16x32_bf16 v[38:41], v[150:153], v[210:213], v[38:41]
	v_mfma_f32_16x16x32_bf16 v[34:37], v[186:189], v[210:213], v[34:37]
	v_mfma_f32_16x16x32_bf16 v[22:25], v[150:153], v[218:221], v[22:25]
	v_mfma_f32_16x16x32_bf16 v[18:21], v[186:189], v[218:221], v[18:21]
	v_mfma_f32_16x16x32_bf16 v[6:9], v[150:153], v[226:229], v[6:9]
	v_mfma_f32_16x16x32_bf16 v[2:5], v[186:189], v[226:229], v[2:5]
	s_setprio 0
	s_barrier
; #define PG8_STAGE(bufoff, gbase, voff) do { _Pragma("unroll") for (int _i = 0; _i < 2; ++_i) \
;         __builtin_amdgcn_global_load_lds((const unsigned*)((const char*)(gbase) + (voff)[_i]), (PG8_LAS unsigned*)(lds + (bufoff) + ldsw + _i * 8192), 16, 0, 0); } while (0)
; #define PG8_LDA(dst, b, h) do { _Pragma("unroll") for (int m = 0; m < 4; ++m) _Pragma("unroll") for (int k = 0; k < 2; ++k) dst[m][k] = *(const PG8_LAS bf16x8*)(lds + PG8_SA(b, h) + aoff + m * 2048 + k * 1024); } while (0)
; #define PG8_LDB(dst, b, h) do { _Pragma("unroll") for (int n = 0; n < 2; ++n) _Pragma("unroll") for (int k = 0; k < 2; ++k) dst[n][k] = *(const PG8_LAS bf16x8*)(lds + PG8_SB(b, h) + boff + n * 2048 + k * 1024); } while (0)
; #define PG8_WAIT_V(n) asm volatile("s_waitcnt vmcnt(" #n ")" ::: "memory")
; #define PG8_WAIT_L(n) asm volatile("s_waitcnt lgkmcnt(" #n ")" ::: "memory")
; #define PG8_BAR __builtin_amdgcn_s_barrier()
; #define PG8_SCHED __builtin_amdgcn_sched_barrier(0)
; template <class Epi, class Sched, bool ALIGN_EPI = false, bool SP2 = false, bool F16 = false>
; __device__ __forceinline__ void gemm_phase(PG8_LAS unsigned char* lds, const Gemm g, const Sched& S, const Epi& E) {
;     ...
;         for (int t = 0; t < nt; t += 2) {
;             const bool last = (t == nt - 2);
;             const char* a1 = cA + (size_t)(t + 1) * kstep;
;             const char* a2 = last ? nA : cA + (size_t)(t + 2) * kstep; const char* b2 = last ? nB : cB + (size_t)(t + 2) * kstep;
;             const char* a3 = a2 + kstep; const char* b3 = b2 + kstep;
;     ...
;             PG8_LDB(B0, 1, 0); PG8_LDB(B1, 1, 1); PG8_SCHED; PG8_LDA(At, 1, 0); PG8_STAGE(PG8_SA(0, 1), a2 + hstepA, voffA);
;             PG8_WAIT_V(8); PG8_WAIT_L(0); PG8_BAR; PG8_MMA(0, 0, At, B0); PG8_MMA(0, 1, At, B1); PG8_BAR; PG8_SCHED;
;             PG8_LDA(At, 1, 1); PG8_STAGE(PG8_SB(1, 0), b3, voffB); PG8_STAGE(PG8_SB(1, 1), b3 + hstepB, voffB); PG8_STAGE(PG8_SA(1, 0), a3, voffA);
;             PG8_WAIT_V(8); PG8_WAIT_L(0); PG8_BAR; PG8_MMA(1, 0, At, B0); PG8_MMA(1, 1, At, B1); PG8_BAR; PG8_SCHED;
	s_add_i32 s79, 0, 0x18000
	s_add_i32 s94, 0, 0x1c000
	ds_read_b128 v[130:133], v159
	ds_read_b128 v[134:137], v159 offset:1024
	ds_read_b128 v[138:141], v159 offset:2048
	ds_read_b128 v[142:145], v159 offset:3072
	ds_read_b128 v[146:149], v161
	ds_read_b128 v[150:153], v161 offset:1024
	ds_read_b128 v[182:185], v161 offset:2048
	ds_read_b128 v[186:189], v161 offset:3072
	s_add_u32 s72, s72, s8
	s_addc_u32 s73, s73, 0
	s_mov_b32 m0, s35
	ds_read_b128 v[190:193], v204 offset:32768
	ds_read_b128 v[194:197], v204 offset:33792
	ds_read_b128 v[206:209], v204 offset:34816
	ds_read_b128 v[210:213], v204 offset:35840
	ds_read_b128 v[214:217], v204 offset:36864
	ds_read_b128 v[218:221], v204 offset:37888
	ds_read_b128 v[222:225], v204 offset:38912
	ds_read_b128 v[226:229], v204 offset:39936
	global_load_lds_dwordx4 v154, s[72:73]
	s_mov_b32 m0, s2
	s_nop 0
	global_load_lds_dwordx4 v158, s[72:73]
	s_waitcnt vmcnt(8)
	s_waitcnt lgkmcnt(0)
	s_setprio 1
	s_barrier
	v_mfma_f32_16x16x32_bf16 v[122:125], v[130:133], v[190:193], v[122:125]
	v_mfma_f32_16x16x32_bf16 v[126:129], v[138:141], v[190:193], v[126:129]
	v_mfma_f32_16x16x32_bf16 v[110:113], v[130:133], v[206:209], v[110:113]
	v_mfma_f32_16x16x32_bf16 v[106:109], v[138:141], v[206:209], v[106:109]
	v_mfma_f32_16x16x32_bf16 v[94:97], v[130:133], v[214:217], v[94:97]
	v_mfma_f32_16x16x32_bf16 v[90:93], v[138:141], v[214:217], v[90:93]
	v_mfma_f32_16x16x32_bf16 v[78:81], v[130:133], v[222:225], v[78:81]
	v_mfma_f32_16x16x32_bf16 v[74:77], v[138:141], v[222:225], v[74:77]
	v_mfma_f32_16x16x32_bf16 v[122:125], v[134:137], v[194:197], v[122:125]
	v_mfma_f32_16x16x32_bf16 v[126:129], v[142:145], v[194:197], v[126:129]
	v_mfma_f32_16x16x32_bf16 v[110:113], v[134:137], v[210:213], v[110:113]
	v_mfma_f32_16x16x32_bf16 v[106:109], v[142:145], v[210:213], v[106:109]
	v_mfma_f32_16x16x32_bf16 v[94:97], v[134:137], v[218:221], v[94:97]
	v_mfma_f32_16x16x32_bf16 v[90:93], v[142:145], v[218:221], v[90:93]
	v_mfma_f32_16x16x32_bf16 v[78:81], v[134:137], v[226:229], v[78:81]
	v_mfma_f32_16x16x32_bf16 v[74:77], v[142:145], v[226:229], v[74:77]
	v_mfma_f32_16x16x32_bf16 v[118:121], v[146:149], v[190:193], v[118:121]
	v_mfma_f32_16x16x32_bf16 v[114:117], v[182:185], v[190:193], v[114:117]
	v_mfma_f32_16x16x32_bf16 v[102:105], v[146:149], v[206:209], v[102:105]
	v_mfma_f32_16x16x32_bf16 v[98:101], v[182:185], v[206:209], v[98:101]
	v_mfma_f32_16x16x32_bf16 v[86:89], v[146:149], v[214:217], v[86:89]
	v_mfma_f32_16x16x32_bf16 v[82:85], v[182:185], v[214:217], v[82:85]
	v_mfma_f32_16x16x32_bf16 v[70:73], v[146:149], v[222:225], v[70:73]
	v_mfma_f32_16x16x32_bf16 v[66:69], v[182:185], v[222:225], v[66:69]
	v_mfma_f32_16x16x32_bf16 v[118:121], v[150:153], v[194:197], v[118:121]
	v_mfma_f32_16x16x32_bf16 v[114:117], v[186:189], v[194:197], v[114:117]
	v_mfma_f32_16x16x32_bf16 v[102:105], v[150:153], v[210:213], v[102:105]
	v_mfma_f32_16x16x32_bf16 v[98:101], v[186:189], v[210:213], v[98:101]
	v_mfma_f32_16x16x32_bf16 v[86:89], v[150:153], v[218:221], v[86:89]
	v_mfma_f32_16x16x32_bf16 v[82:85], v[186:189], v[218:221], v[82:85]
	v_mfma_f32_16x16x32_bf16 v[70:73], v[150:153], v[226:229], v[70:73]
	v_mfma_f32_16x16x32_bf16 v[66:69], v[186:189], v[226:229], v[66:69]
	s_setprio 0
	s_barrier
	s_add_i32 s72, s79, s75
	s_add_i32 vcc_hi, s78, -2
	s_cmp_eq_u32 s74, vcc_hi
	s_cselect_b32 s99, s53, s24
	s_cselect_b32 s98, s52, s13
	s_add_u32 s98, s98, s92
	s_addc_u32 s99, s99, s93
	s_mov_b32 m0, s72
	s_nop 0
	global_load_lds_dwordx4 v156, s[98:99]
	ds_read_b128 v[190:193], v204 offset:49152
	ds_read_b128 v[194:197], v204 offset:50176
	ds_read_b128 v[206:209], v204 offset:51200
	ds_read_b128 v[210:213], v204 offset:52224
	ds_read_b128 v[214:217], v204 offset:53248
	ds_read_b128 v[218:221], v204 offset:54272
	ds_read_b128 v[222:225], v204 offset:55296
	ds_read_b128 v[226:229], v204 offset:56320
	s_add_i32 m0, s72, 0x2000
	s_nop 0
	global_load_lds_dwordx4 v160, s[98:99]
	s_add_i32 s72, s94, s75
	s_add_u32 s98, s98, s48
	s_addc_u32 s99, s99, 0
	s_mov_b32 m0, s72
	s_nop 0
	global_load_lds_dwordx4 v156, s[98:99]
	s_add_i32 m0, s72, 0x2000
	s_nop 0
	global_load_lds_dwordx4 v160, s[98:99]
	s_add_u32 s98, s46, 0x80
	s_addc_u32 s99, s47, 0
	s_cmp_eq_u32 s74, vcc_hi
	s_cselect_b32 s99, s55, s99
	s_cselect_b32 s98, s54, s98
	s_add_u32 s98, s98, s92
	s_addc_u32 s99, s99, s93
	s_mov_b32 m0, s22
	s_nop 0
	global_load_lds_dwordx4 v154, s[98:99]
	s_mov_b32 m0, s23
	s_nop 0
	global_load_lds_dwordx4 v158, s[98:99]
	s_waitcnt vmcnt(8)
	s_waitcnt lgkmcnt(0)
	s_setprio 1
	s_barrier
	v_mfma_f32_16x16x32_bf16 v[62:65], v[130:133], v[190:193], v[62:65]
	v_mfma_f32_16x16x32_bf16 v[58:61], v[138:141], v[190:193], v[58:61]
	v_mfma_f32_16x16x32_bf16 v[46:49], v[130:133], v[206:209], v[46:49]
	v_mfma_f32_16x16x32_bf16 v[42:45], v[138:141], v[206:209], v[42:45]
	v_mfma_f32_16x16x32_bf16 v[30:33], v[130:133], v[214:217], v[30:33]
	v_mfma_f32_16x16x32_bf16 v[26:29], v[138:141], v[214:217], v[26:29]
	v_mfma_f32_16x16x32_bf16 v[14:17], v[130:133], v[222:225], v[14:17]
	v_mfma_f32_16x16x32_bf16 v[10:13], v[138:141], v[222:225], v[10:13]
	v_mfma_f32_16x16x32_bf16 v[62:65], v[134:137], v[194:197], v[62:65]
	v_mfma_f32_16x16x32_bf16 v[58:61], v[142:145], v[194:197], v[58:61]
	v_mfma_f32_16x16x32_bf16 v[46:49], v[134:137], v[210:213], v[46:49]
	v_mfma_f32_16x16x32_bf16 v[42:45], v[142:145], v[210:213], v[42:45]
	v_mfma_f32_16x16x32_bf16 v[30:33], v[134:137], v[218:221], v[30:33]
	v_mfma_f32_16x16x32_bf16 v[26:29], v[142:145], v[218:221], v[26:29]
	v_mfma_f32_16x16x32_bf16 v[14:17], v[134:137], v[226:229], v[14:17]
	v_mfma_f32_16x16x32_bf16 v[10:13], v[142:145], v[226:229], v[10:13]
	v_mfma_f32_16x16x32_bf16 v[54:57], v[146:149], v[190:193], v[54:57]
	v_mfma_f32_16x16x32_bf16 v[50:53], v[182:185], v[190:193], v[50:53]
	v_mfma_f32_16x16x32_bf16 v[38:41], v[146:149], v[206:209], v[38:41]
	v_mfma_f32_16x16x32_bf16 v[34:37], v[182:185], v[206:209], v[34:37]
	v_mfma_f32_16x16x32_bf16 v[22:25], v[146:149], v[214:217], v[22:25]
	v_mfma_f32_16x16x32_bf16 v[18:21], v[182:185], v[214:217], v[18:21]
	v_mfma_f32_16x16x32_bf16 v[6:9], v[146:149], v[222:225], v[6:9]
	v_mfma_f32_16x16x32_bf16 v[2:5], v[182:185], v[222:225], v[2:5]
	v_mfma_f32_16x16x32_bf16 v[54:57], v[150:153], v[194:197], v[54:57]
	v_mfma_f32_16x16x32_bf16 v[50:53], v[186:189], v[194:197], v[50:53]
	v_mfma_f32_16x16x32_bf16 v[38:41], v[150:153], v[210:213], v[38:41]
	v_mfma_f32_16x16x32_bf16 v[34:37], v[186:189], v[210:213], v[34:37]
	v_mfma_f32_16x16x32_bf16 v[22:25], v[150:153], v[218:221], v[22:25]
	v_mfma_f32_16x16x32_bf16 v[18:21], v[186:189], v[218:221], v[18:21]
	v_mfma_f32_16x16x32_bf16 v[6:9], v[150:153], v[226:229], v[6:9]
	v_mfma_f32_16x16x32_bf16 v[2:5], v[186:189], v[226:229], v[2:5]
	s_setprio 0
	s_barrier
	s_add_u32 s46, s46, 0x100
	s_addc_u32 s47, s47, 0
	s_add_u32 s13, s13, 0x100
	s_addc_u32 s24, s24, 0
	s_cmp_ge_u32 s78, s65
	s_mov_b32 s72, s78
	s_cbranch_scc1 .LBB0_399
; #define PG8_STAGE(bufoff, gbase, voff) do { _Pragma("unroll") for (int _i = 0; _i < 2; ++_i) \
;         __builtin_amdgcn_global_load_lds((const unsigned*)((const char*)(gbase) + (voff)[_i]), (PG8_LAS unsigned*)(lds + (bufoff) + ldsw + _i * 8192), 16, 0, 0); } while (0)
; #define PG8_LDA(dst, b, h) do { _Pragma("unroll") for (int m = 0; m < 4; ++m) _Pragma("unroll") for (int k = 0; k < 2; ++k) dst[m][k] = *(const PG8_LAS bf16x8*)(lds + PG8_SA(b, h) + aoff + m * 2048 + k * 1024); } while (0)
; #define PG8_LDB(dst, b, h) do { _Pragma("unroll") for (int n = 0; n < 2; ++n) _Pragma("unroll") for (int k = 0; k < 2; ++k) dst[n][k] = *(const PG8_LAS bf16x8*)(lds + PG8_SB(b, h) + boff + n * 2048 + k * 1024); } while (0)
; #define PG8_WAIT_V(n) asm volatile("s_waitcnt vmcnt(" #n ")" ::: "memory")
; #define PG8_WAIT_L(n) asm volatile("s_waitcnt lgkmcnt(" #n ")" ::: "memory")
; #define PG8_BAR __builtin_amdgcn_s_barrier()
; #define PG8_SCHED __builtin_amdgcn_sched_barrier(0)
; template <class Epi, class Sched, bool ALIGN_EPI = false, bool SP2 = false, bool F16 = false>
; __device__ __forceinline__ void gemm_phase(PG8_LAS unsigned char* lds, const Gemm g, const Sched& S, const Epi& E) {
;     ...
;             const bool last = (t == nt - 2);
;             const char* a1 = cA + (size_t)(t + 1) * kstep;
;             const char* a2 = last ? nA : cA + (size_t)(t + 2) * kstep; const char* b2 = last ? nB : cB + (size_t)(t + 2) * kstep;
;             const char* a3 = a2 + kstep; const char* b3 = b2 + kstep;
;             if (last && has_next) S.a_ready(nxt);
;             if constexpr (SP2) {
;             PG8_LDB(B0, 0, 0); PG8_LDB(B1, 0, 1); PG8_SCHED; PG8_LDA(At, 0, 0); PG8_STAGE(PG8_SA(1, 1), a1 + hstepA, voffA);
;             PG8_WAIT_V(8); PG8_WAIT_L(0); PG8_BAR; PG8_MMA(0, 0, At, B0); PG8_MMA(0, 1, At, B1); PG8_BAR; PG8_SCHED;
;             PG8_LDA(At, 0, 1); PG8_STAGE(PG8_SB(0, 0), b2, voffB); PG8_STAGE(PG8_SB(0, 1), b2 + hstepB, voffB); PG8_STAGE(PG8_SA(0, 0), a2, voffA);
;             PG8_WAIT_V(8); PG8_WAIT_L(0); PG8_BAR; PG8_MMA(1, 0, At, B0); PG8_MMA(1, 1, At, B1); PG8_BAR; PG8_SCHED;
.LBB0_398:
	s_add_i32 s78, s72, 2
	s_add_u32 s79, s46, 0x80
	s_addc_u32 s73, s47, 0
	s_add_i32 vcc_lo, 0, 0x10000
	s_cmp_eq_u32 s74, s72
	s_cselect_b32 s73, s55, s73
	s_cselect_b32 s72, s54, s79
	s_cselect_b32 s95, s53, s24
	s_cselect_b32 s94, s52, s13
	s_add_i32 s79, 0, 0x14000
	ds_read_b128 v[130:133], v155
	ds_read_b128 v[134:137], v155 offset:1024
	ds_read_b128 v[138:141], v155 offset:2048
	ds_read_b128 v[142:145], v155 offset:3072
	ds_read_b128 v[146:149], v157
	ds_read_b128 v[150:153], v157 offset:1024
	ds_read_b128 v[182:185], v157 offset:2048
	ds_read_b128 v[186:189], v157 offset:3072
	s_add_i32 m0, s36, 0xc000
	ds_read_b128 v[190:193], v204
	ds_read_b128 v[194:197], v204 offset:1024
	ds_read_b128 v[206:209], v204 offset:2048
	ds_read_b128 v[210:213], v204 offset:3072
	ds_read_b128 v[214:217], v204 offset:4096
	ds_read_b128 v[218:221], v204 offset:5120
	ds_read_b128 v[222:225], v204 offset:6144
	ds_read_b128 v[226:229], v204 offset:7168
	global_load_lds_dwordx4 v168, s[46:47]
	s_add_i32 m0, s36, 0xe000
	s_nop 0
	global_load_lds_dwordx4 v170, s[46:47]
	s_waitcnt vmcnt(8)
	s_waitcnt lgkmcnt(0)
	s_setprio 1
	s_barrier
	v_mfma_f32_16x16x32_bf16 v[122:125], v[130:133], v[190:193], v[122:125]
	v_mfma_f32_16x16x32_bf16 v[126:129], v[138:141], v[190:193], v[126:129]
	v_mfma_f32_16x16x32_bf16 v[110:113], v[130:133], v[206:209], v[110:113]
	v_mfma_f32_16x16x32_bf16 v[106:109], v[138:141], v[206:209], v[106:109]
	v_mfma_f32_16x16x32_bf16 v[94:97], v[130:133], v[214:217], v[94:97]
	v_mfma_f32_16x16x32_bf16 v[90:93], v[138:141], v[214:217], v[90:93]
	v_mfma_f32_16x16x32_bf16 v[78:81], v[130:133], v[222:225], v[78:81]
	v_mfma_f32_16x16x32_bf16 v[74:77], v[138:141], v[222:225], v[74:77]
	v_mfma_f32_16x16x32_bf16 v[122:125], v[134:137], v[194:197], v[122:125]
	v_mfma_f32_16x16x32_bf16 v[126:129], v[142:145], v[194:197], v[126:129]
	v_mfma_f32_16x16x32_bf16 v[110:113], v[134:137], v[210:213], v[110:113]
	v_mfma_f32_16x16x32_bf16 v[106:109], v[142:145], v[210:213], v[106:109]
	v_mfma_f32_16x16x32_bf16 v[94:97], v[134:137], v[218:221], v[94:97]
	v_mfma_f32_16x16x32_bf16 v[90:93], v[142:145], v[218:221], v[90:93]
	v_mfma_f32_16x16x32_bf16 v[78:81], v[134:137], v[226:229], v[78:81]
	v_mfma_f32_16x16x32_bf16 v[74:77], v[142:145], v[226:229], v[74:77]
	v_mfma_f32_16x16x32_bf16 v[118:121], v[146:149], v[190:193], v[118:121]
	v_mfma_f32_16x16x32_bf16 v[114:117], v[182:185], v[190:193], v[114:117]
	v_mfma_f32_16x16x32_bf16 v[102:105], v[146:149], v[206:209], v[102:105]
	v_mfma_f32_16x16x32_bf16 v[98:101], v[182:185], v[206:209], v[98:101]
	v_mfma_f32_16x16x32_bf16 v[86:89], v[146:149], v[214:217], v[86:89]
	v_mfma_f32_16x16x32_bf16 v[82:85], v[182:185], v[214:217], v[82:85]
	v_mfma_f32_16x16x32_bf16 v[70:73], v[146:149], v[222:225], v[70:73]
	v_mfma_f32_16x16x32_bf16 v[66:69], v[182:185], v[222:225], v[66:69]
	v_mfma_f32_16x16x32_bf16 v[118:121], v[150:153], v[194:197], v[118:121]
	v_mfma_f32_16x16x32_bf16 v[114:117], v[186:189], v[194:197], v[114:117]
	v_mfma_f32_16x16x32_bf16 v[102:105], v[150:153], v[210:213], v[102:105]
	v_mfma_f32_16x16x32_bf16 v[98:101], v[186:189], v[210:213], v[98:101]
	v_mfma_f32_16x16x32_bf16 v[86:89], v[150:153], v[218:221], v[86:89]
	v_mfma_f32_16x16x32_bf16 v[82:85], v[186:189], v[218:221], v[82:85]
	v_mfma_f32_16x16x32_bf16 v[70:73], v[150:153], v[226:229], v[70:73]
	v_mfma_f32_16x16x32_bf16 v[66:69], v[186:189], v[226:229], v[66:69]
	s_setprio 0
	s_barrier
	s_add_i32 vcc_lo, vcc_lo, s75
	s_mov_b32 m0, vcc_lo
	s_nop 0
	global_load_lds_dwordx4 v156, s[94:95]
	ds_read_b128 v[190:193], v204 offset:16384
	ds_read_b128 v[194:197], v204 offset:17408
	ds_read_b128 v[206:209], v204 offset:18432
	ds_read_b128 v[210:213], v204 offset:19456
	ds_read_b128 v[214:217], v204 offset:20480
	ds_read_b128 v[218:221], v204 offset:21504
	ds_read_b128 v[222:225], v204 offset:22528
	ds_read_b128 v[226:229], v204 offset:23552
	s_add_i32 m0, vcc_lo, 0x2000
	s_nop 0
	global_load_lds_dwordx4 v160, s[94:95]
	s_add_i32 s79, s79, s75
	s_add_u32 s94, s94, s48
	s_addc_u32 s95, s95, 0
	s_mov_b32 m0, s79
	s_nop 0
	global_load_lds_dwordx4 v156, s[94:95]
	s_add_i32 m0, s79, 0x2000
	s_nop 0
	global_load_lds_dwordx4 v160, s[94:95]
	s_mov_b32 m0, s36
	s_nop 0
	global_load_lds_dwordx4 v154, s[72:73]
	s_mov_b32 m0, s37
	s_nop 0
	global_load_lds_dwordx4 v158, s[72:73]
	s_waitcnt vmcnt(8)
	s_waitcnt lgkmcnt(0)
	s_setprio 1
	s_barrier
	v_mfma_f32_16x16x32_bf16 v[62:65], v[130:133], v[190:193], v[62:65]
	v_mfma_f32_16x16x32_bf16 v[58:61], v[138:141], v[190:193], v[58:61]
	v_mfma_f32_16x16x32_bf16 v[46:49], v[130:133], v[206:209], v[46:49]
	v_mfma_f32_16x16x32_bf16 v[42:45], v[138:141], v[206:209], v[42:45]
	v_mfma_f32_16x16x32_bf16 v[30:33], v[130:133], v[214:217], v[30:33]
	v_mfma_f32_16x16x32_bf16 v[26:29], v[138:141], v[214:217], v[26:29]
	v_mfma_f32_16x16x32_bf16 v[14:17], v[130:133], v[222:225], v[14:17]
	v_mfma_f32_16x16x32_bf16 v[10:13], v[138:141], v[222:225], v[10:13]
	v_mfma_f32_16x16x32_bf16 v[62:65], v[134:137], v[194:197], v[62:65]
	v_mfma_f32_16x16x32_bf16 v[58:61], v[142:145], v[194:197], v[58:61]
	v_mfma_f32_16x16x32_bf16 v[46:49], v[134:137], v[210:213], v[46:49]
	v_mfma_f32_16x16x32_bf16 v[42:45], v[142:145], v[210:213], v[42:45]
	v_mfma_f32_16x16x32_bf16 v[30:33], v[134:137], v[218:221], v[30:33]
	v_mfma_f32_16x16x32_bf16 v[26:29], v[142:145], v[218:221], v[26:29]
	v_mfma_f32_16x16x32_bf16 v[14:17], v[134:137], v[226:229], v[14:17]
	v_mfma_f32_16x16x32_bf16 v[10:13], v[142:145], v[226:229], v[10:13]
	v_mfma_f32_16x16x32_bf16 v[54:57], v[146:149], v[190:193], v[54:57]
	v_mfma_f32_16x16x32_bf16 v[50:53], v[182:185], v[190:193], v[50:53]
	v_mfma_f32_16x16x32_bf16 v[38:41], v[146:149], v[206:209], v[38:41]
	v_mfma_f32_16x16x32_bf16 v[34:37], v[182:185], v[206:209], v[34:37]
	v_mfma_f32_16x16x32_bf16 v[22:25], v[146:149], v[214:217], v[22:25]
	v_mfma_f32_16x16x32_bf16 v[18:21], v[182:185], v[214:217], v[18:21]
	v_mfma_f32_16x16x32_bf16 v[6:9], v[146:149], v[222:225], v[6:9]
	v_mfma_f32_16x16x32_bf16 v[2:5], v[182:185], v[222:225], v[2:5]
	v_mfma_f32_16x16x32_bf16 v[54:57], v[150:153], v[194:197], v[54:57]
	v_mfma_f32_16x16x32_bf16 v[50:53], v[186:189], v[194:197], v[50:53]
	v_mfma_f32_16x16x32_bf16 v[38:41], v[150:153], v[210:213], v[38:41]
	v_mfma_f32_16x16x32_bf16 v[34:37], v[186:189], v[210:213], v[34:37]
	v_mfma_f32_16x16x32_bf16 v[22:25], v[150:153], v[218:221], v[22:25]
	v_mfma_f32_16x16x32_bf16 v[18:21], v[186:189], v[218:221], v[18:21]
	v_mfma_f32_16x16x32_bf16 v[6:9], v[150:153], v[226:229], v[6:9]
	v_mfma_f32_16x16x32_bf16 v[2:5], v[186:189], v[226:229], v[2:5]
	s_setprio 0
	s_barrier
; #define PG8_STAGE(bufoff, gbase, voff) do { _Pragma("unroll") for (int _i = 0; _i < 2; ++_i) \
;         __builtin_amdgcn_global_load_lds((const unsigned*)((const char*)(gbase) + (voff)[_i]), (PG8_LAS unsigned*)(lds + (bufoff) + ldsw + _i * 8192), 16, 0, 0); } while (0)
; #define PG8_LDA(dst, b, h) do { _Pragma("unroll") for (int m = 0; m < 4; ++m) _Pragma("unroll") for (int k = 0; k < 2; ++k) dst[m][k] = *(const PG8_LAS bf16x8*)(lds + PG8_SA(b, h) + aoff + m * 2048 + k * 1024); } while (0)
; #define PG8_LDB(dst, b, h) do { _Pragma("unroll") for (int n = 0; n < 2; ++n) _Pragma("unroll") for (int k = 0; k < 2; ++k) dst[n][k] = *(const PG8_LAS bf16x8*)(lds + PG8_SB(b, h) + boff + n * 2048 + k * 1024); } while (0)
; #define PG8_WAIT_V(n) asm volatile("s_waitcnt vmcnt(" #n ")" ::: "memory")
; #define PG8_WAIT_L(n) asm volatile("s_waitcnt lgkmcnt(" #n ")" ::: "memory")
; #define PG8_BAR __builtin_amdgcn_s_barrier()
; #define PG8_SCHED __builtin_amdgcn_sched_barrier(0)
; template <class Epi, class Sched, bool ALIGN_EPI = false, bool SP2 = false, bool F16 = false>
; __device__ __forceinline__ void gemm_phase(PG8_LAS unsigned char* lds, const Gemm g, const Sched& S, const Epi& E) {
;     ...
;         for (int t = 0; t < nt; t += 2) {
;             const bool last = (t == nt - 2);
;             const char* a1 = cA + (size_t)(t + 1) * kstep;
;             const char* a2 = last ? nA : cA + (size_t)(t + 2) * kstep; const char* b2 = last ? nB : cB + (size_t)(t + 2) * kstep;
;     ...
;             PG8_LDB(B0, 1, 0); PG8_LDB(B1, 1, 1); PG8_SCHED; PG8_LDA(At, 1, 0); PG8_STAGE(PG8_SA(0, 1), a2 + hstepA, voffA);
;             PG8_WAIT_V(8); PG8_WAIT_L(0); PG8_BAR; PG8_MMA(0, 0, At, B0); PG8_MMA(0, 1, At, B1); PG8_BAR; PG8_SCHED;
;             PG8_LDA(At, 1, 1); PG8_STAGE(PG8_SB(1, 0), b3, voffB); PG8_STAGE(PG8_SB(1, 1), b3 + hstepB, voffB); PG8_STAGE(PG8_SA(1, 0), a3, voffA);
;             PG8_WAIT_V(8); PG8_WAIT_L(0); PG8_BAR; PG8_MMA(1, 0, At, B0); PG8_MMA(1, 1, At, B1); PG8_BAR; PG8_SCHED;
	s_add_i32 s79, 0, 0x18000
	s_add_i32 s94, 0, 0x1c000
	ds_read_b128 v[130:133], v159
	ds_read_b128 v[134:137], v159 offset:1024
	ds_read_b128 v[138:141], v159 offset:2048
	ds_read_b128 v[142:145], v159 offset:3072
	ds_read_b128 v[146:149], v161
	ds_read_b128 v[150:153], v161 offset:1024
	ds_read_b128 v[182:185], v161 offset:2048
	ds_read_b128 v[186:189], v161 offset:3072
	s_add_u32 s72, s72, s8
	s_addc_u32 s73, s73, 0
	s_mov_b32 m0, s35
	ds_read_b128 v[190:193], v204 offset:32768
	ds_read_b128 v[194:197], v204 offset:33792
	ds_read_b128 v[206:209], v204 offset:34816
	ds_read_b128 v[210:213], v204 offset:35840
	ds_read_b128 v[214:217], v204 offset:36864
	ds_read_b128 v[218:221], v204 offset:37888
	ds_read_b128 v[222:225], v204 offset:38912
	ds_read_b128 v[226:229], v204 offset:39936
	global_load_lds_dwordx4 v154, s[72:73]
	s_mov_b32 m0, s2
	s_nop 0
	global_load_lds_dwordx4 v158, s[72:73]
	s_waitcnt vmcnt(8)
	s_waitcnt lgkmcnt(0)
	s_setprio 1
	s_barrier
	v_mfma_f32_16x16x32_bf16 v[122:125], v[130:133], v[190:193], v[122:125]
	v_mfma_f32_16x16x32_bf16 v[126:129], v[138:141], v[190:193], v[126:129]
	v_mfma_f32_16x16x32_bf16 v[110:113], v[130:133], v[206:209], v[110:113]
	v_mfma_f32_16x16x32_bf16 v[106:109], v[138:141], v[206:209], v[106:109]
	v_mfma_f32_16x16x32_bf16 v[94:97], v[130:133], v[214:217], v[94:97]
	v_mfma_f32_16x16x32_bf16 v[90:93], v[138:141], v[214:217], v[90:93]
	v_mfma_f32_16x16x32_bf16 v[78:81], v[130:133], v[222:225], v[78:81]
	v_mfma_f32_16x16x32_bf16 v[74:77], v[138:141], v[222:225], v[74:77]
	v_mfma_f32_16x16x32_bf16 v[122:125], v[134:137], v[194:197], v[122:125]
	v_mfma_f32_16x16x32_bf16 v[126:129], v[142:145], v[194:197], v[126:129]
	v_mfma_f32_16x16x32_bf16 v[110:113], v[134:137], v[210:213], v[110:113]
	v_mfma_f32_16x16x32_bf16 v[106:109], v[142:145], v[210:213], v[106:109]
	v_mfma_f32_16x16x32_bf16 v[94:97], v[134:137], v[218:221], v[94:97]
	v_mfma_f32_16x16x32_bf16 v[90:93], v[142:145], v[218:221], v[90:93]
	v_mfma_f32_16x16x32_bf16 v[78:81], v[134:137], v[226:229], v[78:81]
	v_mfma_f32_16x16x32_bf16 v[74:77], v[142:145], v[226:229], v[74:77]
	v_mfma_f32_16x16x32_bf16 v[118:121], v[146:149], v[190:193], v[118:121]
	v_mfma_f32_16x16x32_bf16 v[114:117], v[182:185], v[190:193], v[114:117]
	v_mfma_f32_16x16x32_bf16 v[102:105], v[146:149], v[206:209], v[102:105]
	v_mfma_f32_16x16x32_bf16 v[98:101], v[182:185], v[206:209], v[98:101]
	v_mfma_f32_16x16x32_bf16 v[86:89], v[146:149], v[214:217], v[86:89]
	v_mfma_f32_16x16x32_bf16 v[82:85], v[182:185], v[214:217], v[82:85]
	v_mfma_f32_16x16x32_bf16 v[70:73], v[146:149], v[222:225], v[70:73]
	v_mfma_f32_16x16x32_bf16 v[66:69], v[182:185], v[222:225], v[66:69]
	v_mfma_f32_16x16x32_bf16 v[118:121], v[150:153], v[194:197], v[118:121]
	v_mfma_f32_16x16x32_bf16 v[114:117], v[186:189], v[194:197], v[114:117]
	v_mfma_f32_16x16x32_bf16 v[102:105], v[150:153], v[210:213], v[102:105]
	v_mfma_f32_16x16x32_bf16 v[98:101], v[186:189], v[210:213], v[98:101]
	v_mfma_f32_16x16x32_bf16 v[86:89], v[150:153], v[218:221], v[86:89]
	v_mfma_f32_16x16x32_bf16 v[82:85], v[186:189], v[218:221], v[82:85]
	v_mfma_f32_16x16x32_bf16 v[70:73], v[150:153], v[226:229], v[70:73]
	v_mfma_f32_16x16x32_bf16 v[66:69], v[186:189], v[226:229], v[66:69]
	s_setprio 0
	s_barrier
	s_add_i32 s72, s79, s75
	s_add_i32 vcc_hi, s78, -2
	s_cmp_eq_u32 s74, vcc_hi
	s_cselect_b32 s99, s53, s24
	s_cselect_b32 s98, s52, s13
	s_add_u32 s98, s98, s92
	s_addc_u32 s99, s99, s93
	s_mov_b32 m0, s72
	s_nop 0
	global_load_lds_dwordx4 v156, s[98:99]
	ds_read_b128 v[190:193], v204 offset:49152
	ds_read_b128 v[194:197], v204 offset:50176
	ds_read_b128 v[206:209], v204 offset:51200
	ds_read_b128 v[210:213], v204 offset:52224
	ds_read_b128 v[214:217], v204 offset:53248
	ds_read_b128 v[218:221], v204 offset:54272
	ds_read_b128 v[222:225], v204 offset:55296
	ds_read_b128 v[226:229], v204 offset:56320
	s_add_i32 m0, s72, 0x2000
	s_nop 0
	global_load_lds_dwordx4 v160, s[98:99]
	s_add_i32 s72, s94, s75
	s_add_u32 s98, s98, s48
	s_addc_u32 s99, s99, 0
	s_mov_b32 m0, s72
	s_nop 0
	global_load_lds_dwordx4 v156, s[98:99]
	s_add_i32 m0, s72, 0x2000
	s_nop 0
	global_load_lds_dwordx4 v160, s[98:99]
	s_add_u32 s98, s46, 0x80
	s_addc_u32 s99, s47, 0
	s_cmp_eq_u32 s74, vcc_hi
	s_cselect_b32 s99, s55, s99
	s_cselect_b32 s98, s54, s98
	s_add_u32 s98, s98, s92
	s_addc_u32 s99, s99, s93
	s_mov_b32 m0, s22
	s_nop 0
	global_load_lds_dwordx4 v154, s[98:99]
	s_mov_b32 m0, s23
	s_nop 0
	global_load_lds_dwordx4 v158, s[98:99]
	s_waitcnt vmcnt(8)
	s_waitcnt lgkmcnt(0)
	s_setprio 1
	s_barrier
	v_mfma_f32_16x16x32_bf16 v[62:65], v[130:133], v[190:193], v[62:65]
	v_mfma_f32_16x16x32_bf16 v[58:61], v[138:141], v[190:193], v[58:61]
	v_mfma_f32_16x16x32_bf16 v[46:49], v[130:133], v[206:209], v[46:49]
	v_mfma_f32_16x16x32_bf16 v[42:45], v[138:141], v[206:209], v[42:45]
	v_mfma_f32_16x16x32_bf16 v[30:33], v[130:133], v[214:217], v[30:33]
	v_mfma_f32_16x16x32_bf16 v[26:29], v[138:141], v[214:217], v[26:29]
	v_mfma_f32_16x16x32_bf16 v[14:17], v[130:133], v[222:225], v[14:17]
	v_mfma_f32_16x16x32_bf16 v[10:13], v[138:141], v[222:225], v[10:13]
	v_mfma_f32_16x16x32_bf16 v[62:65], v[134:137], v[194:197], v[62:65]
	v_mfma_f32_16x16x32_bf16 v[58:61], v[142:145], v[194:197], v[58:61]
	v_mfma_f32_16x16x32_bf16 v[46:49], v[134:137], v[210:213], v[46:49]
	v_mfma_f32_16x16x32_bf16 v[42:45], v[142:145], v[210:213], v[42:45]
	v_mfma_f32_16x16x32_bf16 v[30:33], v[134:137], v[218:221], v[30:33]
	v_mfma_f32_16x16x32_bf16 v[26:29], v[142:145], v[218:221], v[26:29]
	v_mfma_f32_16x16x32_bf16 v[14:17], v[134:137], v[226:229], v[14:17]
	v_mfma_f32_16x16x32_bf16 v[10:13], v[142:145], v[226:229], v[10:13]
	v_mfma_f32_16x16x32_bf16 v[54:57], v[146:149], v[190:193], v[54:57]
	v_mfma_f32_16x16x32_bf16 v[50:53], v[182:185], v[190:193], v[50:53]
	v_mfma_f32_16x16x32_bf16 v[38:41], v[146:149], v[206:209], v[38:41]
	v_mfma_f32_16x16x32_bf16 v[34:37], v[182:185], v[206:209], v[34:37]
	v_mfma_f32_16x16x32_bf16 v[22:25], v[146:149], v[214:217], v[22:25]
	v_mfma_f32_16x16x32_bf16 v[18:21], v[182:185], v[214:217], v[18:21]
	v_mfma_f32_16x16x32_bf16 v[6:9], v[146:149], v[222:225], v[6:9]
	v_mfma_f32_16x16x32_bf16 v[2:5], v[182:185], v[222:225], v[2:5]
	v_mfma_f32_16x16x32_bf16 v[54:57], v[150:153], v[194:197], v[54:57]
	v_mfma_f32_16x16x32_bf16 v[50:53], v[186:189], v[194:197], v[50:53]
	v_mfma_f32_16x16x32_bf16 v[38:41], v[150:153], v[210:213], v[38:41]
	v_mfma_f32_16x16x32_bf16 v[34:37], v[186:189], v[210:213], v[34:37]
	v_mfma_f32_16x16x32_bf16 v[22:25], v[150:153], v[218:221], v[22:25]
	v_mfma_f32_16x16x32_bf16 v[18:21], v[186:189], v[218:221], v[18:21]
	v_mfma_f32_16x16x32_bf16 v[6:9], v[150:153], v[226:229], v[6:9]
	v_mfma_f32_16x16x32_bf16 v[2:5], v[186:189], v[226:229], v[2:5]
	s_setprio 0
	s_barrier
	s_add_u32 s46, s46, 0x100
	s_addc_u32 s47, s47, 0
	s_add_u32 s13, s13, 0x100
	s_addc_u32 s24, s24, 0
	s_cmp_ge_u32 s78, s65
	s_mov_b32 s72, s78
	s_cbranch_scc0 .LBB0_398

; #define PG8_STAGE(bufoff, gbase, voff) do { _Pragma("unroll") for (int _i = 0; _i < 2; ++_i) \
;         __builtin_amdgcn_global_load_lds((const unsigned*)((const char*)(gbase) + (voff)[_i]), (PG8_LAS unsigned*)(lds + (bufoff) + ldsw + _i * 8192), 16, 0, 0); } while (0)
; #define PG8_LDA(dst, b, h) do { _Pragma("unroll") for (int m = 0; m < 4; ++m) _Pragma("unroll") for (int k = 0; k < 2; ++k) dst[m][k] = *(const PG8_LAS bf16x8*)(lds + PG8_SA(b, h) + aoff + m * 2048 + k * 1024); } while (0)
; #define PG8_LDB(dst, b, h) do { _Pragma("unroll") for (int n = 0; n < 2; ++n) _Pragma("unroll") for (int k = 0; k < 2; ++k) dst[n][k] = *(const PG8_LAS bf16x8*)(lds + PG8_SB(b, h) + boff + n * 2048 + k * 1024); } while (0)
; #define PG8_WAIT_V(n) asm volatile("s_waitcnt vmcnt(" #n ")" ::: "memory")
; #define PG8_WAIT_L(n) asm volatile("s_waitcnt lgkmcnt(" #n ")" ::: "memory")
; #define PG8_BAR __builtin_amdgcn_s_barrier()
; #define PG8_SCHED __builtin_amdgcn_sched_barrier(0)
; template <class Epi, class Sched, bool ALIGN_EPI = false, bool SP2 = false, bool F16 = false>
; __device__ __forceinline__ void gemm_phase(PG8_LAS unsigned char* lds, const Gemm g, const Sched& S, const Epi& E) {
;     ...
;             PG8_LDB(B0, 0, 0); PG8_LDB(B1, 0, 1); PG8_SCHED; PG8_LDA(At, 0, 0); PG8_STAGE(PG8_SA(1, 1), a1 + hstepA, voffA);
;             PG8_WAIT_V(8); PG8_WAIT_L(0); PG8_BAR; PG8_MMA(0, 0, At, B0); PG8_MMA(0, 1, At, B1); PG8_BAR; PG8_SCHED;
;             PG8_LDA(At, 0, 1); PG8_STAGE(PG8_SB(0, 0), b2, voffB); PG8_STAGE(PG8_SB(0, 1), b2 + hstepB, voffB); PG8_STAGE(PG8_SA(0, 0), a2, voffA);
;             PG8_WAIT_V(8); PG8_WAIT_L(0); PG8_BAR; PG8_MMA(1, 0, At, B0); PG8_MMA(1, 1, At, B1); PG8_BAR; PG8_SCHED;
.Lpk_bh:
	s_add_i32 s73, s52, 2
	s_add_u32 s82, s44, 0x80
	s_addc_u32 s53, s45, 0
	s_add_i32 s94, 0, 0x10000
	s_cmp_eq_u32 s74, s52
	s_cselect_b32 s53, s79, s53
	s_cselect_b32 s52, s78, s82
	s_cselect_b32 s83, s55, s72
	s_cselect_b32 s82, s54, s24
	s_add_i32 s95, 0, 0x14000
	ds_read_b128 v[130:133], v155
	ds_read_b128 v[134:137], v155 offset:1024
	ds_read_b128 v[138:141], v155 offset:2048
	ds_read_b128 v[142:145], v155 offset:3072
	ds_read_b128 v[146:149], v157
	ds_read_b128 v[150:153], v157 offset:1024
	ds_read_b128 v[182:185], v157 offset:2048
	ds_read_b128 v[186:189], v157 offset:3072
	s_add_i32 m0, s35, 0xc000
	ds_read_b128 v[190:193], v204
	ds_read_b128 v[194:197], v204 offset:1024
	ds_read_b128 v[206:209], v204 offset:2048
	ds_read_b128 v[210:213], v204 offset:3072
	ds_read_b128 v[214:217], v204 offset:4096
	ds_read_b128 v[218:221], v204 offset:5120
	ds_read_b128 v[222:225], v204 offset:6144
	ds_read_b128 v[226:229], v204 offset:7168
	global_load_lds_dwordx4 v168, s[44:45]
	s_add_i32 m0, s35, 0xe000
	s_nop 0
	global_load_lds_dwordx4 v170, s[44:45]
	s_waitcnt vmcnt(8)
	s_waitcnt lgkmcnt(0)
	s_setprio 1
	s_barrier
	v_mfma_f32_16x16x32_f16 v[122:125], v[130:133], v[190:193], 0
	v_mfma_f32_16x16x32_f16 v[126:129], v[138:141], v[190:193], 0
	v_mfma_f32_16x16x32_f16 v[110:113], v[130:133], v[206:209], 0
	v_mfma_f32_16x16x32_f16 v[106:109], v[138:141], v[206:209], 0
	v_mfma_f32_16x16x32_f16 v[94:97], v[130:133], v[214:217], 0
	v_mfma_f32_16x16x32_f16 v[90:93], v[138:141], v[214:217], 0
	v_mfma_f32_16x16x32_f16 v[78:81], v[130:133], v[222:225], 0
	v_mfma_f32_16x16x32_f16 v[74:77], v[138:141], v[222:225], 0
	v_mfma_f32_16x16x32_f16 v[122:125], v[134:137], v[194:197], v[122:125]
	v_mfma_f32_16x16x32_f16 v[126:129], v[142:145], v[194:197], v[126:129]
	v_mfma_f32_16x16x32_f16 v[110:113], v[134:137], v[210:213], v[110:113]
	v_mfma_f32_16x16x32_f16 v[106:109], v[142:145], v[210:213], v[106:109]
	v_mfma_f32_16x16x32_f16 v[94:97], v[134:137], v[218:221], v[94:97]
	v_mfma_f32_16x16x32_f16 v[90:93], v[142:145], v[218:221], v[90:93]
	v_mfma_f32_16x16x32_f16 v[78:81], v[134:137], v[226:229], v[78:81]
	v_mfma_f32_16x16x32_f16 v[74:77], v[142:145], v[226:229], v[74:77]
	v_mfma_f32_16x16x32_f16 v[118:121], v[146:149], v[190:193], 0
	v_mfma_f32_16x16x32_f16 v[114:117], v[182:185], v[190:193], 0
	v_mfma_f32_16x16x32_f16 v[102:105], v[146:149], v[206:209], 0
	v_mfma_f32_16x16x32_f16 v[98:101], v[182:185], v[206:209], 0
	v_mfma_f32_16x16x32_f16 v[86:89], v[146:149], v[214:217], 0
	v_mfma_f32_16x16x32_f16 v[82:85], v[182:185], v[214:217], 0
	v_mfma_f32_16x16x32_f16 v[70:73], v[146:149], v[222:225], 0
	v_mfma_f32_16x16x32_f16 v[66:69], v[182:185], v[222:225], 0
	v_mfma_f32_16x16x32_f16 v[118:121], v[150:153], v[194:197], v[118:121]
	v_mfma_f32_16x16x32_f16 v[114:117], v[186:189], v[194:197], v[114:117]
	v_mfma_f32_16x16x32_f16 v[102:105], v[150:153], v[210:213], v[102:105]
	v_mfma_f32_16x16x32_f16 v[98:101], v[186:189], v[210:213], v[98:101]
	v_mfma_f32_16x16x32_f16 v[86:89], v[150:153], v[218:221], v[86:89]
	v_mfma_f32_16x16x32_f16 v[82:85], v[186:189], v[218:221], v[82:85]
	v_mfma_f32_16x16x32_f16 v[70:73], v[150:153], v[226:229], v[70:73]
	v_mfma_f32_16x16x32_f16 v[66:69], v[186:189], v[226:229], v[66:69]
	s_setprio 0
	s_barrier
	s_add_i32 s94, s94, s75
	s_mov_b32 m0, s94
	s_nop 0
	global_load_lds_dwordx4 v156, s[82:83]
	ds_read_b128 v[190:193], v204 offset:16384
	ds_read_b128 v[194:197], v204 offset:17408
	ds_read_b128 v[206:209], v204 offset:18432
	ds_read_b128 v[210:213], v204 offset:19456
	ds_read_b128 v[214:217], v204 offset:20480
	ds_read_b128 v[218:221], v204 offset:21504
	ds_read_b128 v[222:225], v204 offset:22528
	ds_read_b128 v[226:229], v204 offset:23552
	s_add_i32 m0, s94, 0x2000
	s_nop 0
	global_load_lds_dwordx4 v160, s[82:83]
	s_add_i32 s94, s95, s75
	s_add_u32 s82, s82, s48
	s_addc_u32 s83, s83, 0
	s_mov_b32 m0, s94
	s_nop 0
	global_load_lds_dwordx4 v156, s[82:83]
	s_add_i32 m0, s94, 0x2000
	s_nop 0
	global_load_lds_dwordx4 v160, s[82:83]
	s_mov_b32 m0, s35
	s_nop 0
	global_load_lds_dwordx4 v154, s[52:53]
	s_mov_b32 m0, s2
	s_nop 0
	global_load_lds_dwordx4 v158, s[52:53]
	s_waitcnt vmcnt(8)
	s_waitcnt lgkmcnt(0)
	s_setprio 1
	s_barrier
	v_mfma_f32_16x16x32_f16 v[62:65], v[130:133], v[190:193], 0
	v_mfma_f32_16x16x32_f16 v[58:61], v[138:141], v[190:193], 0
	v_mfma_f32_16x16x32_f16 v[46:49], v[130:133], v[206:209], 0
	v_mfma_f32_16x16x32_f16 v[42:45], v[138:141], v[206:209], 0
	v_mfma_f32_16x16x32_f16 v[30:33], v[130:133], v[214:217], 0
	v_mfma_f32_16x16x32_f16 v[26:29], v[138:141], v[214:217], 0
	v_mfma_f32_16x16x32_f16 v[14:17], v[130:133], v[222:225], 0
	v_mfma_f32_16x16x32_f16 v[10:13], v[138:141], v[222:225], 0
	v_mfma_f32_16x16x32_f16 v[62:65], v[134:137], v[194:197], v[62:65]
	v_mfma_f32_16x16x32_f16 v[58:61], v[142:145], v[194:197], v[58:61]
	v_mfma_f32_16x16x32_f16 v[46:49], v[134:137], v[210:213], v[46:49]
	v_mfma_f32_16x16x32_f16 v[42:45], v[142:145], v[210:213], v[42:45]
	v_mfma_f32_16x16x32_f16 v[30:33], v[134:137], v[218:221], v[30:33]
	v_mfma_f32_16x16x32_f16 v[26:29], v[142:145], v[218:221], v[26:29]
	v_mfma_f32_16x16x32_f16 v[14:17], v[134:137], v[226:229], v[14:17]
	v_mfma_f32_16x16x32_f16 v[10:13], v[142:145], v[226:229], v[10:13]
	v_mfma_f32_16x16x32_f16 v[54:57], v[146:149], v[190:193], 0
	v_mfma_f32_16x16x32_f16 v[50:53], v[182:185], v[190:193], 0
	v_mfma_f32_16x16x32_f16 v[38:41], v[146:149], v[206:209], 0
	v_mfma_f32_16x16x32_f16 v[34:37], v[182:185], v[206:209], 0
	v_mfma_f32_16x16x32_f16 v[22:25], v[146:149], v[214:217], 0
	v_mfma_f32_16x16x32_f16 v[18:21], v[182:185], v[214:217], 0
	v_mfma_f32_16x16x32_f16 v[6:9], v[146:149], v[222:225], 0
	v_mfma_f32_16x16x32_f16 v[2:5], v[182:185], v[222:225], 0
	v_mfma_f32_16x16x32_f16 v[54:57], v[150:153], v[194:197], v[54:57]
	v_mfma_f32_16x16x32_f16 v[50:53], v[186:189], v[194:197], v[50:53]
	v_mfma_f32_16x16x32_f16 v[38:41], v[150:153], v[210:213], v[38:41]
	v_mfma_f32_16x16x32_f16 v[34:37], v[186:189], v[210:213], v[34:37]
	v_mfma_f32_16x16x32_f16 v[22:25], v[150:153], v[218:221], v[22:25]
	v_mfma_f32_16x16x32_f16 v[18:21], v[186:189], v[218:221], v[18:21]
	v_mfma_f32_16x16x32_f16 v[6:9], v[150:153], v[226:229], v[6:9]
	v_mfma_f32_16x16x32_f16 v[2:5], v[186:189], v[226:229], v[2:5]
	s_setprio 0
	s_barrier
; #define PG8_STAGE(bufoff, gbase, voff) do { _Pragma("unroll") for (int _i = 0; _i < 2; ++_i) \
;         __builtin_amdgcn_global_load_lds((const unsigned*)((const char*)(gbase) + (voff)[_i]), (PG8_LAS unsigned*)(lds + (bufoff) + ldsw + _i * 8192), 16, 0, 0); } while (0)
; #define PG8_LDA(dst, b, h) do { _Pragma("unroll") for (int m = 0; m < 4; ++m) _Pragma("unroll") for (int k = 0; k < 2; ++k) dst[m][k] = *(const PG8_LAS bf16x8*)(lds + PG8_SA(b, h) + aoff + m * 2048 + k * 1024); } while (0)
; #define PG8_LDB(dst, b, h) do { _Pragma("unroll") for (int n = 0; n < 2; ++n) _Pragma("unroll") for (int k = 0; k < 2; ++k) dst[n][k] = *(const PG8_LAS bf16x8*)(lds + PG8_SB(b, h) + boff + n * 2048 + k * 1024); } while (0)
; #define PG8_WAIT_V(n) asm volatile("s_waitcnt vmcnt(" #n ")" ::: "memory")
; #define PG8_WAIT_L(n) asm volatile("s_waitcnt lgkmcnt(" #n ")" ::: "memory")
; #define PG8_BAR __builtin_amdgcn_s_barrier()
; #define PG8_SCHED __builtin_amdgcn_sched_barrier(0)
; template <class Epi, class Sched, bool ALIGN_EPI = false, bool SP2 = false, bool F16 = false>
; __device__ __forceinline__ void gemm_phase(PG8_LAS unsigned char* lds, const Gemm g, const Sched& S, const Epi& E) {
;     ...
;         for (int t = 0; t < nt; t += 2) {
;             const bool last = (t == nt - 2);
;             const char* a1 = cA + (size_t)(t + 1) * kstep;
;             const char* a2 = last ? nA : cA + (size_t)(t + 2) * kstep; const char* b2 = last ? nB : cB + (size_t)(t + 2) * kstep;
;     ...
;             PG8_LDB(B0, 1, 0); PG8_LDB(B1, 1, 1); PG8_SCHED; PG8_LDA(At, 1, 0); PG8_STAGE(PG8_SA(0, 1), a2 + hstepA, voffA);
;             PG8_WAIT_V(8); PG8_WAIT_L(0); PG8_BAR; PG8_MMA(0, 0, At, B0); PG8_MMA(0, 1, At, B1); PG8_BAR; PG8_SCHED;
;             PG8_LDA(At, 1, 1); PG8_STAGE(PG8_SB(1, 0), b3, voffB); PG8_STAGE(PG8_SB(1, 1), b3 + hstepB, voffB); PG8_STAGE(PG8_SA(1, 0), a3, voffA);
;             PG8_WAIT_V(8); PG8_WAIT_L(0); PG8_BAR; PG8_MMA(1, 0, At, B0); PG8_MMA(1, 1, At, B1); PG8_BAR; PG8_SCHED;
	s_add_i32 s82, 0, 0x18000
	s_add_i32 s83, 0, 0x1c000
	ds_read_b128 v[130:133], v159
	ds_read_b128 v[134:137], v159 offset:1024
	ds_read_b128 v[138:141], v159 offset:2048
	ds_read_b128 v[142:145], v159 offset:3072
	ds_read_b128 v[146:149], v161
	ds_read_b128 v[150:153], v161 offset:1024
	ds_read_b128 v[182:185], v161 offset:2048
	ds_read_b128 v[186:189], v161 offset:3072
	s_add_u32 s52, s52, s8
	s_addc_u32 s53, s53, 0
	s_mov_b32 m0, s22
	ds_read_b128 v[190:193], v204 offset:32768
	ds_read_b128 v[194:197], v204 offset:33792
	ds_read_b128 v[206:209], v204 offset:34816
	ds_read_b128 v[210:213], v204 offset:35840
	ds_read_b128 v[214:217], v204 offset:36864
	ds_read_b128 v[218:221], v204 offset:37888
	ds_read_b128 v[222:225], v204 offset:38912
	ds_read_b128 v[226:229], v204 offset:39936
	global_load_lds_dwordx4 v154, s[52:53]
	s_mov_b32 m0, s23
	s_nop 0
	global_load_lds_dwordx4 v158, s[52:53]
	s_waitcnt vmcnt(8)
	s_waitcnt lgkmcnt(0)
	s_setprio 1
	s_barrier
	v_mfma_f32_16x16x32_f16 v[122:125], v[130:133], v[190:193], v[122:125]
	v_mfma_f32_16x16x32_f16 v[126:129], v[138:141], v[190:193], v[126:129]
	v_mfma_f32_16x16x32_f16 v[110:113], v[130:133], v[206:209], v[110:113]
	v_mfma_f32_16x16x32_f16 v[106:109], v[138:141], v[206:209], v[106:109]
	v_mfma_f32_16x16x32_f16 v[94:97], v[130:133], v[214:217], v[94:97]
	v_mfma_f32_16x16x32_f16 v[90:93], v[138:141], v[214:217], v[90:93]
	v_mfma_f32_16x16x32_f16 v[78:81], v[130:133], v[222:225], v[78:81]
	v_mfma_f32_16x16x32_f16 v[74:77], v[138:141], v[222:225], v[74:77]
	v_mfma_f32_16x16x32_f16 v[122:125], v[134:137], v[194:197], v[122:125]
	v_mfma_f32_16x16x32_f16 v[126:129], v[142:145], v[194:197], v[126:129]
	v_mfma_f32_16x16x32_f16 v[110:113], v[134:137], v[210:213], v[110:113]
	v_mfma_f32_16x16x32_f16 v[106:109], v[142:145], v[210:213], v[106:109]
	v_mfma_f32_16x16x32_f16 v[94:97], v[134:137], v[218:221], v[94:97]
	v_mfma_f32_16x16x32_f16 v[90:93], v[142:145], v[218:221], v[90:93]
	v_mfma_f32_16x16x32_f16 v[78:81], v[134:137], v[226:229], v[78:81]
	v_mfma_f32_16x16x32_f16 v[74:77], v[142:145], v[226:229], v[74:77]
	v_mfma_f32_16x16x32_f16 v[118:121], v[146:149], v[190:193], v[118:121]
	v_mfma_f32_16x16x32_f16 v[114:117], v[182:185], v[190:193], v[114:117]
	v_mfma_f32_16x16x32_f16 v[102:105], v[146:149], v[206:209], v[102:105]
	v_mfma_f32_16x16x32_f16 v[98:101], v[182:185], v[206:209], v[98:101]
	v_mfma_f32_16x16x32_f16 v[86:89], v[146:149], v[214:217], v[86:89]
	v_mfma_f32_16x16x32_f16 v[82:85], v[182:185], v[214:217], v[82:85]
	v_mfma_f32_16x16x32_f16 v[70:73], v[146:149], v[222:225], v[70:73]
	v_mfma_f32_16x16x32_f16 v[66:69], v[182:185], v[222:225], v[66:69]
	v_mfma_f32_16x16x32_f16 v[118:121], v[150:153], v[194:197], v[118:121]
	v_mfma_f32_16x16x32_f16 v[114:117], v[186:189], v[194:197], v[114:117]
	v_mfma_f32_16x16x32_f16 v[102:105], v[150:153], v[210:213], v[102:105]
	v_mfma_f32_16x16x32_f16 v[98:101], v[186:189], v[210:213], v[98:101]
	v_mfma_f32_16x16x32_f16 v[86:89], v[150:153], v[218:221], v[86:89]
	v_mfma_f32_16x16x32_f16 v[82:85], v[186:189], v[218:221], v[82:85]
	v_mfma_f32_16x16x32_f16 v[70:73], v[150:153], v[226:229], v[70:73]
	v_mfma_f32_16x16x32_f16 v[66:69], v[186:189], v[226:229], v[66:69]
	s_setprio 0
	s_barrier
	s_add_i32 s52, s82, s75
	s_add_i32 vcc_hi, s73, -2
	s_cmp_eq_u32 s74, vcc_hi
	s_cselect_b32 s99, s55, s72
	s_cselect_b32 s98, s54, s24
	s_add_u32 s98, s98, s92
	s_addc_u32 s99, s99, s93
	s_mov_b32 m0, s52
	s_nop 0
	global_load_lds_dwordx4 v156, s[98:99]
	ds_read_b128 v[190:193], v204 offset:49152
	ds_read_b128 v[194:197], v204 offset:50176
	ds_read_b128 v[206:209], v204 offset:51200
	ds_read_b128 v[210:213], v204 offset:52224
	ds_read_b128 v[214:217], v204 offset:53248
	ds_read_b128 v[218:221], v204 offset:54272
	ds_read_b128 v[222:225], v204 offset:55296
	ds_read_b128 v[226:229], v204 offset:56320
	s_add_i32 m0, s52, 0x2000
	s_nop 0
	global_load_lds_dwordx4 v160, s[98:99]
	s_add_i32 s52, s83, s75
	s_add_u32 s98, s98, s48
	s_addc_u32 s99, s99, 0
	s_mov_b32 m0, s52
	s_nop 0
	global_load_lds_dwordx4 v156, s[98:99]
	s_add_i32 m0, s52, 0x2000
	s_nop 0
	global_load_lds_dwordx4 v160, s[98:99]
	s_add_u32 s98, s44, 0x80
	s_addc_u32 s99, s45, 0
	s_cmp_eq_u32 s74, vcc_hi
	s_cselect_b32 s99, s79, s99
	s_cselect_b32 s98, s78, s98
	s_add_u32 s98, s98, s92
	s_addc_u32 s99, s99, s93
	s_mov_b32 m0, s61
	s_nop 0
	global_load_lds_dwordx4 v154, s[98:99]
	s_mov_b32 m0, s18
	s_nop 0
	global_load_lds_dwordx4 v158, s[98:99]
	s_waitcnt vmcnt(8)
	s_waitcnt lgkmcnt(0)
	s_setprio 1
	s_barrier
	v_mfma_f32_16x16x32_f16 v[62:65], v[130:133], v[190:193], v[62:65]
	v_mfma_f32_16x16x32_f16 v[58:61], v[138:141], v[190:193], v[58:61]
	v_mfma_f32_16x16x32_f16 v[46:49], v[130:133], v[206:209], v[46:49]
	v_mfma_f32_16x16x32_f16 v[42:45], v[138:141], v[206:209], v[42:45]
	v_mfma_f32_16x16x32_f16 v[30:33], v[130:133], v[214:217], v[30:33]
	v_mfma_f32_16x16x32_f16 v[26:29], v[138:141], v[214:217], v[26:29]
	v_mfma_f32_16x16x32_f16 v[14:17], v[130:133], v[222:225], v[14:17]
	v_mfma_f32_16x16x32_f16 v[10:13], v[138:141], v[222:225], v[10:13]
	v_mfma_f32_16x16x32_f16 v[62:65], v[134:137], v[194:197], v[62:65]
	v_mfma_f32_16x16x32_f16 v[58:61], v[142:145], v[194:197], v[58:61]
	v_mfma_f32_16x16x32_f16 v[46:49], v[134:137], v[210:213], v[46:49]
	v_mfma_f32_16x16x32_f16 v[42:45], v[142:145], v[210:213], v[42:45]
	v_mfma_f32_16x16x32_f16 v[30:33], v[134:137], v[218:221], v[30:33]
	v_mfma_f32_16x16x32_f16 v[26:29], v[142:145], v[218:221], v[26:29]
	v_mfma_f32_16x16x32_f16 v[14:17], v[134:137], v[226:229], v[14:17]
	v_mfma_f32_16x16x32_f16 v[10:13], v[142:145], v[226:229], v[10:13]
	v_mfma_f32_16x16x32_f16 v[54:57], v[146:149], v[190:193], v[54:57]
	v_mfma_f32_16x16x32_f16 v[50:53], v[182:185], v[190:193], v[50:53]
	v_mfma_f32_16x16x32_f16 v[38:41], v[146:149], v[206:209], v[38:41]
	v_mfma_f32_16x16x32_f16 v[34:37], v[182:185], v[206:209], v[34:37]
	v_mfma_f32_16x16x32_f16 v[22:25], v[146:149], v[214:217], v[22:25]
	v_mfma_f32_16x16x32_f16 v[18:21], v[182:185], v[214:217], v[18:21]
	v_mfma_f32_16x16x32_f16 v[6:9], v[146:149], v[222:225], v[6:9]
	v_mfma_f32_16x16x32_f16 v[2:5], v[182:185], v[222:225], v[2:5]
	v_mfma_f32_16x16x32_f16 v[54:57], v[150:153], v[194:197], v[54:57]
	v_mfma_f32_16x16x32_f16 v[50:53], v[186:189], v[194:197], v[50:53]
	v_mfma_f32_16x16x32_f16 v[38:41], v[150:153], v[210:213], v[38:41]
	v_mfma_f32_16x16x32_f16 v[34:37], v[186:189], v[210:213], v[34:37]
	v_mfma_f32_16x16x32_f16 v[22:25], v[150:153], v[218:221], v[22:25]
	v_mfma_f32_16x16x32_f16 v[18:21], v[186:189], v[218:221], v[18:21]
	v_mfma_f32_16x16x32_f16 v[6:9], v[150:153], v[226:229], v[6:9]
	v_mfma_f32_16x16x32_f16 v[2:5], v[186:189], v[226:229], v[2:5]
	s_setprio 0
	s_barrier
	s_add_u32 s44, s44, 0x100
	s_addc_u32 s45, s45, 0
	s_add_u32 s24, s24, 0x100
	s_addc_u32 s72, s72, 0
	s_cmp_ge_u32 s73, s65
	s_mov_b32 s52, s73
	s_cbranch_scc1 .LBB0_565
; #define PG8_STAGE(bufoff, gbase, voff) do { _Pragma("unroll") for (int _i = 0; _i < 2; ++_i) \
;         __builtin_amdgcn_global_load_lds((const unsigned*)((const char*)(gbase) + (voff)[_i]), (PG8_LAS unsigned*)(lds + (bufoff) + ldsw + _i * 8192), 16, 0, 0); } while (0)
; #define PG8_LDA(dst, b, h) do { _Pragma("unroll") for (int m = 0; m < 4; ++m) _Pragma("unroll") for (int k = 0; k < 2; ++k) dst[m][k] = *(const PG8_LAS bf16x8*)(lds + PG8_SA(b, h) + aoff + m * 2048 + k * 1024); } while (0)
; #define PG8_LDB(dst, b, h) do { _Pragma("unroll") for (int n = 0; n < 2; ++n) _Pragma("unroll") for (int k = 0; k < 2; ++k) dst[n][k] = *(const PG8_LAS bf16x8*)(lds + PG8_SB(b, h) + boff + n * 2048 + k * 1024); } while (0)
; #define PG8_WAIT_V(n) asm volatile("s_waitcnt vmcnt(" #n ")" ::: "memory")
; #define PG8_WAIT_L(n) asm volatile("s_waitcnt lgkmcnt(" #n ")" ::: "memory")
; #define PG8_BAR __builtin_amdgcn_s_barrier()
; #define PG8_SCHED __builtin_amdgcn_sched_barrier(0)
; template <class Epi, class Sched, bool ALIGN_EPI = false, bool SP2 = false, bool F16 = false>
; __device__ __forceinline__ void gemm_phase(PG8_LAS unsigned char* lds, const Gemm g, const Sched& S, const Epi& E) {
;     ...
;             PG8_LDB(B0, 0, 0); PG8_LDB(B1, 0, 1); PG8_SCHED; PG8_LDA(At, 0, 0); PG8_STAGE(PG8_SA(1, 1), a1 + hstepA, voffA);
;             PG8_WAIT_V(8); PG8_WAIT_L(0); PG8_BAR; PG8_MMA(0, 0, At, B0); PG8_MMA(0, 1, At, B1); PG8_BAR; PG8_SCHED;
;             PG8_LDA(At, 0, 1); PG8_STAGE(PG8_SB(0, 0), b2, voffB); PG8_STAGE(PG8_SB(0, 1), b2 + hstepB, voffB); PG8_STAGE(PG8_SA(0, 0), a2, voffA);
;             PG8_WAIT_V(8); PG8_WAIT_L(0); PG8_BAR; PG8_MMA(1, 0, At, B0); PG8_MMA(1, 1, At, B1); PG8_BAR; PG8_SCHED;
.LBB0_564:
	s_add_i32 s73, s52, 2
	s_add_u32 s82, s44, 0x80
	s_addc_u32 s53, s45, 0
	s_add_i32 s94, 0, 0x10000
	s_cmp_eq_u32 s74, s52
	s_cselect_b32 s53, s79, s53
	s_cselect_b32 s52, s78, s82
	s_cselect_b32 s83, s55, s72
	s_cselect_b32 s82, s54, s24
	s_add_i32 s95, 0, 0x14000
	ds_read_b128 v[130:133], v155
	ds_read_b128 v[134:137], v155 offset:1024
	ds_read_b128 v[138:141], v155 offset:2048
	ds_read_b128 v[142:145], v155 offset:3072
	ds_read_b128 v[146:149], v157
	ds_read_b128 v[150:153], v157 offset:1024
	ds_read_b128 v[182:185], v157 offset:2048
	ds_read_b128 v[186:189], v157 offset:3072
	s_add_i32 m0, s35, 0xc000
	ds_read_b128 v[190:193], v204
	ds_read_b128 v[194:197], v204 offset:1024
	ds_read_b128 v[206:209], v204 offset:2048
	ds_read_b128 v[210:213], v204 offset:3072
	ds_read_b128 v[214:217], v204 offset:4096
	ds_read_b128 v[218:221], v204 offset:5120
	ds_read_b128 v[222:225], v204 offset:6144
	ds_read_b128 v[226:229], v204 offset:7168
	global_load_lds_dwordx4 v168, s[44:45]
	s_add_i32 m0, s35, 0xe000
	s_nop 0
	global_load_lds_dwordx4 v170, s[44:45]
	s_waitcnt vmcnt(8)
	s_waitcnt lgkmcnt(0)
	s_setprio 1
	s_barrier
	v_mfma_f32_16x16x32_f16 v[122:125], v[130:133], v[190:193], v[122:125]
	v_mfma_f32_16x16x32_f16 v[126:129], v[138:141], v[190:193], v[126:129]
	v_mfma_f32_16x16x32_f16 v[110:113], v[130:133], v[206:209], v[110:113]
	v_mfma_f32_16x16x32_f16 v[106:109], v[138:141], v[206:209], v[106:109]
	v_mfma_f32_16x16x32_f16 v[94:97], v[130:133], v[214:217], v[94:97]
	v_mfma_f32_16x16x32_f16 v[90:93], v[138:141], v[214:217], v[90:93]
	v_mfma_f32_16x16x32_f16 v[78:81], v[130:133], v[222:225], v[78:81]
	v_mfma_f32_16x16x32_f16 v[74:77], v[138:141], v[222:225], v[74:77]
	v_mfma_f32_16x16x32_f16 v[122:125], v[134:137], v[194:197], v[122:125]
	v_mfma_f32_16x16x32_f16 v[126:129], v[142:145], v[194:197], v[126:129]
	v_mfma_f32_16x16x32_f16 v[110:113], v[134:137], v[210:213], v[110:113]
	v_mfma_f32_16x16x32_f16 v[106:109], v[142:145], v[210:213], v[106:109]
	v_mfma_f32_16x16x32_f16 v[94:97], v[134:137], v[218:221], v[94:97]
	v_mfma_f32_16x16x32_f16 v[90:93], v[142:145], v[218:221], v[90:93]
	v_mfma_f32_16x16x32_f16 v[78:81], v[134:137], v[226:229], v[78:81]
	v_mfma_f32_16x16x32_f16 v[74:77], v[142:145], v[226:229], v[74:77]
	v_mfma_f32_16x16x32_f16 v[118:121], v[146:149], v[190:193], v[118:121]
	v_mfma_f32_16x16x32_f16 v[114:117], v[182:185], v[190:193], v[114:117]
	v_mfma_f32_16x16x32_f16 v[102:105], v[146:149], v[206:209], v[102:105]
	v_mfma_f32_16x16x32_f16 v[98:101], v[182:185], v[206:209], v[98:101]
	v_mfma_f32_16x16x32_f16 v[86:89], v[146:149], v[214:217], v[86:89]
	v_mfma_f32_16x16x32_f16 v[82:85], v[182:185], v[214:217], v[82:85]
	v_mfma_f32_16x16x32_f16 v[70:73], v[146:149], v[222:225], v[70:73]
	v_mfma_f32_16x16x32_f16 v[66:69], v[182:185], v[222:225], v[66:69]
	v_mfma_f32_16x16x32_f16 v[118:121], v[150:153], v[194:197], v[118:121]
	v_mfma_f32_16x16x32_f16 v[114:117], v[186:189], v[194:197], v[114:117]
	v_mfma_f32_16x16x32_f16 v[102:105], v[150:153], v[210:213], v[102:105]
	v_mfma_f32_16x16x32_f16 v[98:101], v[186:189], v[210:213], v[98:101]
	v_mfma_f32_16x16x32_f16 v[86:89], v[150:153], v[218:221], v[86:89]
	v_mfma_f32_16x16x32_f16 v[82:85], v[186:189], v[218:221], v[82:85]
	v_mfma_f32_16x16x32_f16 v[70:73], v[150:153], v[226:229], v[70:73]
	v_mfma_f32_16x16x32_f16 v[66:69], v[186:189], v[226:229], v[66:69]
	s_setprio 0
	s_barrier
	s_add_i32 s94, s94, s75
	s_mov_b32 m0, s94
	s_nop 0
	global_load_lds_dwordx4 v156, s[82:83]
	ds_read_b128 v[190:193], v204 offset:16384
	ds_read_b128 v[194:197], v204 offset:17408
	ds_read_b128 v[206:209], v204 offset:18432
	ds_read_b128 v[210:213], v204 offset:19456
	ds_read_b128 v[214:217], v204 offset:20480
	ds_read_b128 v[218:221], v204 offset:21504
	ds_read_b128 v[222:225], v204 offset:22528
	ds_read_b128 v[226:229], v204 offset:23552
	s_add_i32 m0, s94, 0x2000
	s_nop 0
	global_load_lds_dwordx4 v160, s[82:83]
	s_add_i32 s94, s95, s75
	s_add_u32 s82, s82, s48
	s_addc_u32 s83, s83, 0
	s_mov_b32 m0, s94
	s_nop 0
	global_load_lds_dwordx4 v156, s[82:83]
	s_add_i32 m0, s94, 0x2000
	s_nop 0
	global_load_lds_dwordx4 v160, s[82:83]
	s_mov_b32 m0, s35
	s_nop 0
	global_load_lds_dwordx4 v154, s[52:53]
	s_mov_b32 m0, s2
	s_nop 0
	global_load_lds_dwordx4 v158, s[52:53]
	s_waitcnt vmcnt(8)
	s_waitcnt lgkmcnt(0)
	s_setprio 1
	s_barrier
	v_mfma_f32_16x16x32_f16 v[62:65], v[130:133], v[190:193], v[62:65]
	v_mfma_f32_16x16x32_f16 v[58:61], v[138:141], v[190:193], v[58:61]
	v_mfma_f32_16x16x32_f16 v[46:49], v[130:133], v[206:209], v[46:49]
	v_mfma_f32_16x16x32_f16 v[42:45], v[138:141], v[206:209], v[42:45]
	v_mfma_f32_16x16x32_f16 v[30:33], v[130:133], v[214:217], v[30:33]
	v_mfma_f32_16x16x32_f16 v[26:29], v[138:141], v[214:217], v[26:29]
	v_mfma_f32_16x16x32_f16 v[14:17], v[130:133], v[222:225], v[14:17]
	v_mfma_f32_16x16x32_f16 v[10:13], v[138:141], v[222:225], v[10:13]
	v_mfma_f32_16x16x32_f16 v[62:65], v[134:137], v[194:197], v[62:65]
	v_mfma_f32_16x16x32_f16 v[58:61], v[142:145], v[194:197], v[58:61]
	v_mfma_f32_16x16x32_f16 v[46:49], v[134:137], v[210:213], v[46:49]
	v_mfma_f32_16x16x32_f16 v[42:45], v[142:145], v[210:213], v[42:45]
	v_mfma_f32_16x16x32_f16 v[30:33], v[134:137], v[218:221], v[30:33]
	v_mfma_f32_16x16x32_f16 v[26:29], v[142:145], v[218:221], v[26:29]
	v_mfma_f32_16x16x32_f16 v[14:17], v[134:137], v[226:229], v[14:17]
	v_mfma_f32_16x16x32_f16 v[10:13], v[142:145], v[226:229], v[10:13]
	v_mfma_f32_16x16x32_f16 v[54:57], v[146:149], v[190:193], v[54:57]
	v_mfma_f32_16x16x32_f16 v[50:53], v[182:185], v[190:193], v[50:53]
	v_mfma_f32_16x16x32_f16 v[38:41], v[146:149], v[206:209], v[38:41]
	v_mfma_f32_16x16x32_f16 v[34:37], v[182:185], v[206:209], v[34:37]
	v_mfma_f32_16x16x32_f16 v[22:25], v[146:149], v[214:217], v[22:25]
	v_mfma_f32_16x16x32_f16 v[18:21], v[182:185], v[214:217], v[18:21]
	v_mfma_f32_16x16x32_f16 v[6:9], v[146:149], v[222:225], v[6:9]
	v_mfma_f32_16x16x32_f16 v[2:5], v[182:185], v[222:225], v[2:5]
	v_mfma_f32_16x16x32_f16 v[54:57], v[150:153], v[194:197], v[54:57]
	v_mfma_f32_16x16x32_f16 v[50:53], v[186:189], v[194:197], v[50:53]
	v_mfma_f32_16x16x32_f16 v[38:41], v[150:153], v[210:213], v[38:41]
	v_mfma_f32_16x16x32_f16 v[34:37], v[186:189], v[210:213], v[34:37]
	v_mfma_f32_16x16x32_f16 v[22:25], v[150:153], v[218:221], v[22:25]
	v_mfma_f32_16x16x32_f16 v[18:21], v[186:189], v[218:221], v[18:21]
	v_mfma_f32_16x16x32_f16 v[6:9], v[150:153], v[226:229], v[6:9]
	v_mfma_f32_16x16x32_f16 v[2:5], v[186:189], v[226:229], v[2:5]
	s_setprio 0
	s_barrier
; #define PG8_STAGE(bufoff, gbase, voff) do { _Pragma("unroll") for (int _i = 0; _i < 2; ++_i) \
;         __builtin_amdgcn_global_load_lds((const unsigned*)((const char*)(gbase) + (voff)[_i]), (PG8_LAS unsigned*)(lds + (bufoff) + ldsw + _i * 8192), 16, 0, 0); } while (0)
; #define PG8_LDA(dst, b, h) do { _Pragma("unroll") for (int m = 0; m < 4; ++m) _Pragma("unroll") for (int k = 0; k < 2; ++k) dst[m][k] = *(const PG8_LAS bf16x8*)(lds + PG8_SA(b, h) + aoff + m * 2048 + k * 1024); } while (0)
; #define PG8_LDB(dst, b, h) do { _Pragma("unroll") for (int n = 0; n < 2; ++n) _Pragma("unroll") for (int k = 0; k < 2; ++k) dst[n][k] = *(const PG8_LAS bf16x8*)(lds + PG8_SB(b, h) + boff + n * 2048 + k * 1024); } while (0)
; #define PG8_WAIT_V(n) asm volatile("s_waitcnt vmcnt(" #n ")" ::: "memory")
; #define PG8_WAIT_L(n) asm volatile("s_waitcnt lgkmcnt(" #n ")" ::: "memory")
; #define PG8_BAR __builtin_amdgcn_s_barrier()
; #define PG8_SCHED __builtin_amdgcn_sched_barrier(0)
; template <class Epi, class Sched, bool ALIGN_EPI = false, bool SP2 = false, bool F16 = false>
; __device__ __forceinline__ void gemm_phase(PG8_LAS unsigned char* lds, const Gemm g, const Sched& S, const Epi& E) {
;     ...
;         for (int t = 0; t < nt; t += 2) {
;             const bool last = (t == nt - 2);
;             const char* a1 = cA + (size_t)(t + 1) * kstep;
;             const char* a2 = last ? nA : cA + (size_t)(t + 2) * kstep; const char* b2 = last ? nB : cB + (size_t)(t + 2) * kstep;
;     ...
;             PG8_LDB(B0, 1, 0); PG8_LDB(B1, 1, 1); PG8_SCHED; PG8_LDA(At, 1, 0); PG8_STAGE(PG8_SA(0, 1), a2 + hstepA, voffA);
;             PG8_WAIT_V(8); PG8_WAIT_L(0); PG8_BAR; PG8_MMA(0, 0, At, B0); PG8_MMA(0, 1, At, B1); PG8_BAR; PG8_SCHED;
;             PG8_LDA(At, 1, 1); PG8_STAGE(PG8_SB(1, 0), b3, voffB); PG8_STAGE(PG8_SB(1, 1), b3 + hstepB, voffB); PG8_STAGE(PG8_SA(1, 0), a3, voffA);
;             PG8_WAIT_V(8); PG8_WAIT_L(0); PG8_BAR; PG8_MMA(1, 0, At, B0); PG8_MMA(1, 1, At, B1); PG8_BAR; PG8_SCHED;
	s_add_i32 s82, 0, 0x18000
	s_add_i32 s83, 0, 0x1c000
	ds_read_b128 v[130:133], v159
	ds_read_b128 v[134:137], v159 offset:1024
	ds_read_b128 v[138:141], v159 offset:2048
	ds_read_b128 v[142:145], v159 offset:3072
	ds_read_b128 v[146:149], v161
	ds_read_b128 v[150:153], v161 offset:1024
	ds_read_b128 v[182:185], v161 offset:2048
	ds_read_b128 v[186:189], v161 offset:3072
	s_add_u32 s52, s52, s8
	s_addc_u32 s53, s53, 0
	s_mov_b32 m0, s22
	ds_read_b128 v[190:193], v204 offset:32768
	ds_read_b128 v[194:197], v204 offset:33792
	ds_read_b128 v[206:209], v204 offset:34816
	ds_read_b128 v[210:213], v204 offset:35840
	ds_read_b128 v[214:217], v204 offset:36864
	ds_read_b128 v[218:221], v204 offset:37888
	ds_read_b128 v[222:225], v204 offset:38912
	ds_read_b128 v[226:229], v204 offset:39936
	global_load_lds_dwordx4 v154, s[52:53]
	s_mov_b32 m0, s23
	s_nop 0
	global_load_lds_dwordx4 v158, s[52:53]
	s_waitcnt vmcnt(8)
	s_waitcnt lgkmcnt(0)
	s_setprio 1
	s_barrier
	v_mfma_f32_16x16x32_f16 v[122:125], v[130:133], v[190:193], v[122:125]
	v_mfma_f32_16x16x32_f16 v[126:129], v[138:141], v[190:193], v[126:129]
	v_mfma_f32_16x16x32_f16 v[110:113], v[130:133], v[206:209], v[110:113]
	v_mfma_f32_16x16x32_f16 v[106:109], v[138:141], v[206:209], v[106:109]
	v_mfma_f32_16x16x32_f16 v[94:97], v[130:133], v[214:217], v[94:97]
	v_mfma_f32_16x16x32_f16 v[90:93], v[138:141], v[214:217], v[90:93]
	v_mfma_f32_16x16x32_f16 v[78:81], v[130:133], v[222:225], v[78:81]
	v_mfma_f32_16x16x32_f16 v[74:77], v[138:141], v[222:225], v[74:77]
	v_mfma_f32_16x16x32_f16 v[122:125], v[134:137], v[194:197], v[122:125]
	v_mfma_f32_16x16x32_f16 v[126:129], v[142:145], v[194:197], v[126:129]
	v_mfma_f32_16x16x32_f16 v[110:113], v[134:137], v[210:213], v[110:113]
	v_mfma_f32_16x16x32_f16 v[106:109], v[142:145], v[210:213], v[106:109]
	v_mfma_f32_16x16x32_f16 v[94:97], v[134:137], v[218:221], v[94:97]
	v_mfma_f32_16x16x32_f16 v[90:93], v[142:145], v[218:221], v[90:93]
	v_mfma_f32_16x16x32_f16 v[78:81], v[134:137], v[226:229], v[78:81]
	v_mfma_f32_16x16x32_f16 v[74:77], v[142:145], v[226:229], v[74:77]
	v_mfma_f32_16x16x32_f16 v[118:121], v[146:149], v[190:193], v[118:121]
	v_mfma_f32_16x16x32_f16 v[114:117], v[182:185], v[190:193], v[114:117]
	v_mfma_f32_16x16x32_f16 v[102:105], v[146:149], v[206:209], v[102:105]
	v_mfma_f32_16x16x32_f16 v[98:101], v[182:185], v[206:209], v[98:101]
	v_mfma_f32_16x16x32_f16 v[86:89], v[146:149], v[214:217], v[86:89]
	v_mfma_f32_16x16x32_f16 v[82:85], v[182:185], v[214:217], v[82:85]
	v_mfma_f32_16x16x32_f16 v[70:73], v[146:149], v[222:225], v[70:73]
	v_mfma_f32_16x16x32_f16 v[66:69], v[182:185], v[222:225], v[66:69]
	v_mfma_f32_16x16x32_f16 v[118:121], v[150:153], v[194:197], v[118:121]
	v_mfma_f32_16x16x32_f16 v[114:117], v[186:189], v[194:197], v[114:117]
	v_mfma_f32_16x16x32_f16 v[102:105], v[150:153], v[210:213], v[102:105]
	v_mfma_f32_16x16x32_f16 v[98:101], v[186:189], v[210:213], v[98:101]
	v_mfma_f32_16x16x32_f16 v[86:89], v[150:153], v[218:221], v[86:89]
	v_mfma_f32_16x16x32_f16 v[82:85], v[186:189], v[218:221], v[82:85]
	v_mfma_f32_16x16x32_f16 v[70:73], v[150:153], v[226:229], v[70:73]
	v_mfma_f32_16x16x32_f16 v[66:69], v[186:189], v[226:229], v[66:69]
	s_setprio 0
	s_barrier
	s_add_i32 s52, s82, s75
	s_add_i32 vcc_hi, s73, -2
	s_cmp_eq_u32 s74, vcc_hi
	s_cselect_b32 s99, s55, s72
	s_cselect_b32 s98, s54, s24
	s_add_u32 s98, s98, s92
	s_addc_u32 s99, s99, s93
	s_mov_b32 m0, s52
	s_nop 0
	global_load_lds_dwordx4 v156, s[98:99]
	ds_read_b128 v[190:193], v204 offset:49152
	ds_read_b128 v[194:197], v204 offset:50176
	ds_read_b128 v[206:209], v204 offset:51200
	ds_read_b128 v[210:213], v204 offset:52224
	ds_read_b128 v[214:217], v204 offset:53248
	ds_read_b128 v[218:221], v204 offset:54272
	ds_read_b128 v[222:225], v204 offset:55296
	ds_read_b128 v[226:229], v204 offset:56320
	s_add_i32 m0, s52, 0x2000
	s_nop 0
	global_load_lds_dwordx4 v160, s[98:99]
	s_add_i32 s52, s83, s75
	s_add_u32 s98, s98, s48
	s_addc_u32 s99, s99, 0
	s_mov_b32 m0, s52
	s_nop 0
	global_load_lds_dwordx4 v156, s[98:99]
	s_add_i32 m0, s52, 0x2000
	s_nop 0
	global_load_lds_dwordx4 v160, s[98:99]
	s_add_u32 s98, s44, 0x80
	s_addc_u32 s99, s45, 0
	s_cmp_eq_u32 s74, vcc_hi
	s_cselect_b32 s99, s79, s99
	s_cselect_b32 s98, s78, s98
	s_add_u32 s98, s98, s92
	s_addc_u32 s99, s99, s93
	s_mov_b32 m0, s61
	s_nop 0
	global_load_lds_dwordx4 v154, s[98:99]
	s_mov_b32 m0, s18
	s_nop 0
	global_load_lds_dwordx4 v158, s[98:99]
	s_waitcnt vmcnt(8)
	s_waitcnt lgkmcnt(0)
	s_setprio 1
	s_barrier
	v_mfma_f32_16x16x32_f16 v[62:65], v[130:133], v[190:193], v[62:65]
	v_mfma_f32_16x16x32_f16 v[58:61], v[138:141], v[190:193], v[58:61]
	v_mfma_f32_16x16x32_f16 v[46:49], v[130:133], v[206:209], v[46:49]
	v_mfma_f32_16x16x32_f16 v[42:45], v[138:141], v[206:209], v[42:45]
	v_mfma_f32_16x16x32_f16 v[30:33], v[130:133], v[214:217], v[30:33]
	v_mfma_f32_16x16x32_f16 v[26:29], v[138:141], v[214:217], v[26:29]
	v_mfma_f32_16x16x32_f16 v[14:17], v[130:133], v[222:225], v[14:17]
	v_mfma_f32_16x16x32_f16 v[10:13], v[138:141], v[222:225], v[10:13]
	v_mfma_f32_16x16x32_f16 v[62:65], v[134:137], v[194:197], v[62:65]
	v_mfma_f32_16x16x32_f16 v[58:61], v[142:145], v[194:197], v[58:61]
	v_mfma_f32_16x16x32_f16 v[46:49], v[134:137], v[210:213], v[46:49]
	v_mfma_f32_16x16x32_f16 v[42:45], v[142:145], v[210:213], v[42:45]
	v_mfma_f32_16x16x32_f16 v[30:33], v[134:137], v[218:221], v[30:33]
	v_mfma_f32_16x16x32_f16 v[26:29], v[142:145], v[218:221], v[26:29]
	v_mfma_f32_16x16x32_f16 v[14:17], v[134:137], v[226:229], v[14:17]
	v_mfma_f32_16x16x32_f16 v[10:13], v[142:145], v[226:229], v[10:13]
	v_mfma_f32_16x16x32_f16 v[54:57], v[146:149], v[190:193], v[54:57]
	v_mfma_f32_16x16x32_f16 v[50:53], v[182:185], v[190:193], v[50:53]
	v_mfma_f32_16x16x32_f16 v[38:41], v[146:149], v[206:209], v[38:41]
	v_mfma_f32_16x16x32_f16 v[34:37], v[182:185], v[206:209], v[34:37]
	v_mfma_f32_16x16x32_f16 v[22:25], v[146:149], v[214:217], v[22:25]
	v_mfma_f32_16x16x32_f16 v[18:21], v[182:185], v[214:217], v[18:21]
	v_mfma_f32_16x16x32_f16 v[6:9], v[146:149], v[222:225], v[6:9]
	v_mfma_f32_16x16x32_f16 v[2:5], v[182:185], v[222:225], v[2:5]
	v_mfma_f32_16x16x32_f16 v[54:57], v[150:153], v[194:197], v[54:57]
	v_mfma_f32_16x16x32_f16 v[50:53], v[186:189], v[194:197], v[50:53]
	v_mfma_f32_16x16x32_f16 v[38:41], v[150:153], v[210:213], v[38:41]
	v_mfma_f32_16x16x32_f16 v[34:37], v[186:189], v[210:213], v[34:37]
	v_mfma_f32_16x16x32_f16 v[22:25], v[150:153], v[218:221], v[22:25]
	v_mfma_f32_16x16x32_f16 v[18:21], v[186:189], v[218:221], v[18:21]
	v_mfma_f32_16x16x32_f16 v[6:9], v[150:153], v[226:229], v[6:9]
	v_mfma_f32_16x16x32_f16 v[2:5], v[186:189], v[226:229], v[2:5]
	s_setprio 0
	s_barrier
	s_add_u32 s44, s44, 0x100
	s_addc_u32 s45, s45, 0
	s_add_u32 s24, s24, 0x100
	s_addc_u32 s72, s72, 0
	s_cmp_ge_u32 s73, s65
	s_mov_b32 s52, s73
	s_cbranch_scc0 .LBB0_564
